# K-loops: LDS wait moved off the hand-off barrier path - counted lgkmcnt waits at the first consuming MFMA of each block (all seven loops)
# baseline (speedup 1.0000x reference)
.LBB0_110:
	s_add_u32 vcc_lo, s78, 0x160080
	s_addc_u32 vcc_hi, s79, 0
	s_add_u32 s84, s76, 0x100
	s_addc_u32 s85, s77, 0
	s_mov_b32 s93, -2
	s_add_u32 s72, vcc_lo, 0xffea0080
	s_addc_u32 s73, vcc_hi, -1
	s_add_i32 s95, 0, 0x10000
	s_cmp_eq_u32 s93, 12
	s_cselect_b32 s79, s1, s73
	s_cselect_b32 s78, s0, s72
	v_add_u32_e32 v26, s95, v186
	s_cselect_b32 s77, s89, s85
	s_cselect_b32 s76, s88, s84
	s_add_i32 s12, 0, 0x14000
	ds_read_b128 v[36:39], v26
	ds_read_b128 v[56:59], v26 offset:1024
	ds_read_b128 v[84:87], v26 offset:2048
	ds_read_b128 v[104:107], v26 offset:3072
	v_add_u32_e32 v26, s12, v186
	ds_read_b128 v[124:127], v26
	ds_read_b128 v[144:147], v26 offset:1024
	ds_read_b128 v[156:159], v26 offset:2048
	ds_read_b128 v[180:183], v26 offset:3072
	v_lshl_add_u64 v[226:227], vcc, 0, v[176:177]
	s_add_i32 m0, s17, 0xc000
	ds_read_b128 v[190:193], v188
	ds_read_b128 v[194:197], v188 offset:1024
	ds_read_b128 v[198:201], v188 offset:2048
	ds_read_b128 v[202:205], v188 offset:3072
	ds_read_b128 v[206:209], v188 offset:4096
	ds_read_b128 v[210:213], v188 offset:5120
	ds_read_b128 v[214:217], v188 offset:6144
	ds_read_b128 v[218:221], v188 offset:7168
	global_load_lds_dwordx4 v[226:227], off
	v_lshl_add_u64 v[226:227], vcc, 0, v[178:179]
	s_add_i32 m0, s17, 0xe000
	s_nop 0
	global_load_lds_dwordx4 v[226:227], off
	s_waitcnt vmcnt(8)
	s_setprio 1
	s_barrier
	s_waitcnt lgkmcnt(7)
	v_mfma_f32_16x16x32_bf16 v[148:151], v[36:39], v[190:193], 0
	v_mfma_f32_16x16x32_bf16 v[152:155], v[84:87], v[190:193], 0
	s_waitcnt lgkmcnt(5)
	v_mfma_f32_16x16x32_bf16 v[128:131], v[36:39], v[198:201], 0
	v_mfma_f32_16x16x32_bf16 v[132:135], v[84:87], v[198:201], 0
	s_waitcnt lgkmcnt(3)
	v_mfma_f32_16x16x32_bf16 v[108:111], v[36:39], v[206:209], 0
	v_mfma_f32_16x16x32_bf16 v[112:115], v[84:87], v[206:209], 0
	s_waitcnt lgkmcnt(1)
	v_mfma_f32_16x16x32_bf16 v[88:91], v[36:39], v[214:217], 0
	v_mfma_f32_16x16x32_bf16 v[92:95], v[84:87], v[214:217], 0
	v_mfma_f32_16x16x32_bf16 v[148:151], v[56:59], v[194:197], v[148:151]
	v_mfma_f32_16x16x32_bf16 v[152:155], v[104:107], v[194:197], v[152:155]
	v_mfma_f32_16x16x32_bf16 v[128:131], v[56:59], v[202:205], v[128:131]
	v_mfma_f32_16x16x32_bf16 v[132:135], v[104:107], v[202:205], v[132:135]
	v_mfma_f32_16x16x32_bf16 v[108:111], v[56:59], v[210:213], v[108:111]
	v_mfma_f32_16x16x32_bf16 v[112:115], v[104:107], v[210:213], v[112:115]
	s_waitcnt lgkmcnt(0)
	v_mfma_f32_16x16x32_bf16 v[88:91], v[56:59], v[218:221], v[88:91]
	v_mfma_f32_16x16x32_bf16 v[92:95], v[104:107], v[218:221], v[92:95]
	s_setprio 0
	s_setprio 1
	v_mfma_f32_16x16x32_bf16 v[140:143], v[124:127], v[190:193], 0
	v_mfma_f32_16x16x32_bf16 v[136:139], v[156:159], v[190:193], 0
	v_mfma_f32_16x16x32_bf16 v[120:123], v[124:127], v[198:201], 0
	v_mfma_f32_16x16x32_bf16 v[116:119], v[156:159], v[198:201], 0
	v_mfma_f32_16x16x32_bf16 v[100:103], v[124:127], v[206:209], 0
	v_mfma_f32_16x16x32_bf16 v[96:99], v[156:159], v[206:209], 0
	v_mfma_f32_16x16x32_bf16 v[80:83], v[124:127], v[214:217], 0
	v_mfma_f32_16x16x32_bf16 v[76:79], v[156:159], v[214:217], 0
	v_mfma_f32_16x16x32_bf16 v[140:143], v[144:147], v[194:197], v[140:143]
	v_mfma_f32_16x16x32_bf16 v[136:139], v[180:183], v[194:197], v[136:139]
	v_mfma_f32_16x16x32_bf16 v[120:123], v[144:147], v[202:205], v[120:123]
	v_mfma_f32_16x16x32_bf16 v[116:119], v[180:183], v[202:205], v[116:119]
	v_mfma_f32_16x16x32_bf16 v[100:103], v[144:147], v[210:213], v[100:103]
	v_mfma_f32_16x16x32_bf16 v[96:99], v[180:183], v[210:213], v[96:99]
	v_mfma_f32_16x16x32_bf16 v[80:83], v[144:147], v[218:221], v[80:83]
	v_mfma_f32_16x16x32_bf16 v[76:79], v[180:183], v[218:221], v[76:79]
	s_barrier
	s_setprio 0
	s_add_i32 s72, s95, s16
	v_lshl_add_u64 v[226:227], s[76:77], 0, v[164:165]
	s_mov_b32 m0, s72
	ds_read_b128 v[190:193], v188 offset:16384
	ds_read_b128 v[194:197], v188 offset:17408
	ds_read_b128 v[198:201], v188 offset:18432
	ds_read_b128 v[202:205], v188 offset:19456
	ds_read_b128 v[206:209], v188 offset:20480
	ds_read_b128 v[210:213], v188 offset:21504
	ds_read_b128 v[214:217], v188 offset:22528
	ds_read_b128 v[218:221], v188 offset:23552
	global_load_lds_dwordx4 v[226:227], off
	s_add_i32 m0, s72, 0x2000
	s_add_u32 s72, s76, 0x40000
	v_lshl_add_u64 v[228:229], s[76:77], 0, v[160:161]
	s_addc_u32 s73, s77, 0
	s_add_i32 s12, s12, s16
	global_load_lds_dwordx4 v[228:229], off
	v_lshl_add_u64 v[230:231], s[72:73], 0, v[164:165]
	s_mov_b32 m0, s12
	v_lshl_add_u64 v[232:233], s[78:79], 0, v[162:163]
	global_load_lds_dwordx4 v[230:231], off
	v_lshl_add_u64 v[230:231], s[72:73], 0, v[160:161]
	s_add_i32 m0, s12, 0x2000
	s_nop 0
	global_load_lds_dwordx4 v[230:231], off
	v_lshl_add_u64 v[230:231], s[78:79], 0, v[166:167]
	s_mov_b32 m0, s17
	s_nop 0
	global_load_lds_dwordx4 v[230:231], off
	s_mov_b32 m0, s46
	s_nop 0
	global_load_lds_dwordx4 v[232:233], off
	s_waitcnt vmcnt(8)
	s_setprio 1
	s_barrier
	s_waitcnt lgkmcnt(7)
	v_mfma_f32_16x16x32_bf16 v[68:71], v[36:39], v[190:193], 0
	v_mfma_f32_16x16x32_bf16 v[72:75], v[84:87], v[190:193], 0
	s_waitcnt lgkmcnt(5)
	v_mfma_f32_16x16x32_bf16 v[48:51], v[36:39], v[198:201], 0
	v_mfma_f32_16x16x32_bf16 v[52:55], v[84:87], v[198:201], 0
	s_waitcnt lgkmcnt(3)
	v_mfma_f32_16x16x32_bf16 v[28:31], v[36:39], v[206:209], 0
	v_mfma_f32_16x16x32_bf16 v[32:35], v[84:87], v[206:209], 0
	s_waitcnt lgkmcnt(1)
	v_mfma_f32_16x16x32_bf16 v[10:13], v[36:39], v[214:217], 0
	v_mfma_f32_16x16x32_bf16 v[14:17], v[84:87], v[214:217], 0
	v_mfma_f32_16x16x32_bf16 v[68:71], v[56:59], v[194:197], v[68:71]
	v_mfma_f32_16x16x32_bf16 v[72:75], v[104:107], v[194:197], v[72:75]
	v_mfma_f32_16x16x32_bf16 v[48:51], v[56:59], v[202:205], v[48:51]
	v_mfma_f32_16x16x32_bf16 v[52:55], v[104:107], v[202:205], v[52:55]
	v_mfma_f32_16x16x32_bf16 v[28:31], v[56:59], v[210:213], v[28:31]
	v_mfma_f32_16x16x32_bf16 v[32:35], v[104:107], v[210:213], v[32:35]
	s_waitcnt lgkmcnt(0)
	v_mfma_f32_16x16x32_bf16 v[10:13], v[56:59], v[218:221], v[10:13]
	v_mfma_f32_16x16x32_bf16 v[14:17], v[104:107], v[218:221], v[14:17]
	s_setprio 0
	s_setprio 1
	v_mfma_f32_16x16x32_bf16 v[44:47], v[124:127], v[198:201], 0
	v_mfma_f32_16x16x32_bf16 v[40:43], v[156:159], v[198:201], 0
	v_mfma_f32_16x16x32_bf16 v[22:25], v[124:127], v[206:209], 0
	v_mfma_f32_16x16x32_bf16 v[18:21], v[156:159], v[206:209], 0
	v_mfma_f32_16x16x32_bf16 v[2:5], v[124:127], v[214:217], 0
	v_mfma_f32_16x16x32_bf16 v[6:9], v[156:159], v[214:217], 0
	v_mfma_f32_16x16x32_bf16 v[36:39], v[124:127], v[190:193], 0
	v_mfma_f32_16x16x32_bf16 v[56:59], v[156:159], v[190:193], 0
	v_mfma_f32_16x16x32_bf16 v[44:47], v[144:147], v[202:205], v[44:47]
	v_mfma_f32_16x16x32_bf16 v[40:43], v[180:183], v[202:205], v[40:43]
	v_mfma_f32_16x16x32_bf16 v[22:25], v[144:147], v[210:213], v[22:25]
	v_mfma_f32_16x16x32_bf16 v[18:21], v[180:183], v[210:213], v[18:21]
	v_mfma_f32_16x16x32_bf16 v[2:5], v[144:147], v[218:221], v[2:5]
	v_mfma_f32_16x16x32_bf16 v[6:9], v[180:183], v[218:221], v[6:9]
	v_mfma_f32_16x16x32_bf16 v[36:39], v[144:147], v[194:197], v[36:39]
	v_mfma_f32_16x16x32_bf16 v[56:59], v[180:183], v[194:197], v[56:59]
	s_barrier
	s_setprio 0
	s_add_i32 s12, 0, 0x18000
	v_add_u32_e32 v26, s12, v186
	s_add_i32 s95, 0, 0x1c000
	ds_read_b128 v[60:63], v26
	ds_read_b128 v[64:67], v26 offset:1024
	ds_read_b128 v[84:87], v26 offset:2048
	ds_read_b128 v[104:107], v26 offset:3072
	v_add_u32_e32 v26, s95, v186
	ds_read_b128 v[124:127], v26
	ds_read_b128 v[144:147], v26 offset:1024
	ds_read_b128 v[156:159], v26 offset:2048
	ds_read_b128 v[180:183], v26 offset:3072
	s_add_u32 s72, s78, 0x160000
	s_addc_u32 s73, s79, 0
	s_mov_b32 m0, s47
	v_lshl_add_u64 v[234:235], s[72:73], 0, v[166:167]
	ds_read_b128 v[190:193], v188 offset:32768
	ds_read_b128 v[194:197], v188 offset:33792
	ds_read_b128 v[198:201], v188 offset:34816
	ds_read_b128 v[202:205], v188 offset:35840
	ds_read_b128 v[206:209], v188 offset:36864
	ds_read_b128 v[210:213], v188 offset:37888
	ds_read_b128 v[214:217], v188 offset:38912
	ds_read_b128 v[218:221], v188 offset:39936
	global_load_lds_dwordx4 v[234:235], off
	v_lshl_add_u64 v[234:235], s[72:73], 0, v[162:163]
	s_mov_b32 m0, s8
	s_nop 0
	global_load_lds_dwordx4 v[234:235], off
	s_waitcnt vmcnt(8)
	s_setprio 1
	s_barrier
	s_waitcnt lgkmcnt(7)
	v_mfma_f32_16x16x32_bf16 v[148:151], v[60:63], v[190:193], v[148:151]
	v_mfma_f32_16x16x32_bf16 v[152:155], v[84:87], v[190:193], v[152:155]
	s_waitcnt lgkmcnt(5)
	v_mfma_f32_16x16x32_bf16 v[128:131], v[60:63], v[198:201], v[128:131]
	v_mfma_f32_16x16x32_bf16 v[132:135], v[84:87], v[198:201], v[132:135]
	s_waitcnt lgkmcnt(3)
	v_mfma_f32_16x16x32_bf16 v[108:111], v[60:63], v[206:209], v[108:111]
	v_mfma_f32_16x16x32_bf16 v[112:115], v[84:87], v[206:209], v[112:115]
	s_waitcnt lgkmcnt(1)
	v_mfma_f32_16x16x32_bf16 v[88:91], v[60:63], v[214:217], v[88:91]
	v_mfma_f32_16x16x32_bf16 v[92:95], v[84:87], v[214:217], v[92:95]
	v_mfma_f32_16x16x32_bf16 v[148:151], v[64:67], v[194:197], v[148:151]
	v_mfma_f32_16x16x32_bf16 v[152:155], v[104:107], v[194:197], v[152:155]
	v_mfma_f32_16x16x32_bf16 v[128:131], v[64:67], v[202:205], v[128:131]
	v_mfma_f32_16x16x32_bf16 v[132:135], v[104:107], v[202:205], v[132:135]
	v_mfma_f32_16x16x32_bf16 v[108:111], v[64:67], v[210:213], v[108:111]
	v_mfma_f32_16x16x32_bf16 v[112:115], v[104:107], v[210:213], v[112:115]
	s_waitcnt lgkmcnt(0)
	v_mfma_f32_16x16x32_bf16 v[88:91], v[64:67], v[218:221], v[88:91]
	v_mfma_f32_16x16x32_bf16 v[92:95], v[104:107], v[218:221], v[92:95]
	s_setprio 0
	s_setprio 1
	v_mfma_f32_16x16x32_bf16 v[140:143], v[124:127], v[190:193], v[140:143]
	v_mfma_f32_16x16x32_bf16 v[136:139], v[156:159], v[190:193], v[136:139]
	v_mfma_f32_16x16x32_bf16 v[120:123], v[124:127], v[198:201], v[120:123]
	v_mfma_f32_16x16x32_bf16 v[116:119], v[156:159], v[198:201], v[116:119]
	v_mfma_f32_16x16x32_bf16 v[100:103], v[124:127], v[206:209], v[100:103]
	v_mfma_f32_16x16x32_bf16 v[96:99], v[156:159], v[206:209], v[96:99]
	v_mfma_f32_16x16x32_bf16 v[80:83], v[124:127], v[214:217], v[80:83]
	v_mfma_f32_16x16x32_bf16 v[76:79], v[156:159], v[214:217], v[76:79]
	v_mfma_f32_16x16x32_bf16 v[140:143], v[144:147], v[194:197], v[140:143]
	v_mfma_f32_16x16x32_bf16 v[136:139], v[180:183], v[194:197], v[136:139]
	v_mfma_f32_16x16x32_bf16 v[120:123], v[144:147], v[202:205], v[120:123]
	v_mfma_f32_16x16x32_bf16 v[116:119], v[180:183], v[202:205], v[116:119]
	v_mfma_f32_16x16x32_bf16 v[100:103], v[144:147], v[210:213], v[100:103]
	v_mfma_f32_16x16x32_bf16 v[96:99], v[180:183], v[210:213], v[96:99]
	v_mfma_f32_16x16x32_bf16 v[80:83], v[144:147], v[218:221], v[80:83]
	v_mfma_f32_16x16x32_bf16 v[76:79], v[180:183], v[218:221], v[76:79]
	s_barrier
	s_setprio 0
	s_add_i32 s12, s12, s16
	v_lshl_add_u64 v[226:227], v[226:227], 0, s[82:83]
	s_mov_b32 m0, s12
	ds_read_b128 v[190:193], v188 offset:49152
	ds_read_b128 v[194:197], v188 offset:50176
	ds_read_b128 v[198:201], v188 offset:51200
	ds_read_b128 v[202:205], v188 offset:52224
	ds_read_b128 v[206:209], v188 offset:53248
	ds_read_b128 v[210:213], v188 offset:54272
	ds_read_b128 v[214:217], v188 offset:55296
	ds_read_b128 v[218:221], v188 offset:56320
	global_load_lds_dwordx4 v[226:227], off
	s_add_i32 m0, s12, 0x2000
	s_add_u32 s72, s76, 0x40080
	v_lshl_add_u64 v[226:227], v[228:229], 0, s[82:83]
	s_addc_u32 s73, s77, 0
	s_add_i32 s12, s95, s16
	global_load_lds_dwordx4 v[226:227], off
	v_lshl_add_u64 v[226:227], s[72:73], 0, v[164:165]
	s_mov_b32 m0, s12
	s_nop 0
	global_load_lds_dwordx4 v[226:227], off
	v_lshl_add_u64 v[226:227], s[72:73], 0, v[160:161]
	s_add_i32 m0, s12, 0x2000
	s_nop 0
	global_load_lds_dwordx4 v[226:227], off
	v_lshl_add_u64 v[226:227], v[230:231], 0, s[82:83]
	s_mov_b32 m0, s22
	s_nop 0
	global_load_lds_dwordx4 v[226:227], off
	v_lshl_add_u64 v[226:227], v[232:233], 0, s[82:83]
	s_mov_b32 m0, s80
	s_nop 0
	global_load_lds_dwordx4 v[226:227], off
	s_waitcnt vmcnt(8)
	s_setprio 1
	s_barrier
	s_waitcnt lgkmcnt(7)
	v_mfma_f32_16x16x32_bf16 v[68:71], v[60:63], v[190:193], v[68:71]
	v_mfma_f32_16x16x32_bf16 v[72:75], v[84:87], v[190:193], v[72:75]
	s_waitcnt lgkmcnt(5)
	v_mfma_f32_16x16x32_bf16 v[48:51], v[60:63], v[198:201], v[48:51]
	v_mfma_f32_16x16x32_bf16 v[52:55], v[84:87], v[198:201], v[52:55]
	s_waitcnt lgkmcnt(3)
	v_mfma_f32_16x16x32_bf16 v[28:31], v[60:63], v[206:209], v[28:31]
	v_mfma_f32_16x16x32_bf16 v[32:35], v[84:87], v[206:209], v[32:35]
	s_waitcnt lgkmcnt(1)
	v_mfma_f32_16x16x32_bf16 v[10:13], v[60:63], v[214:217], v[10:13]
	v_mfma_f32_16x16x32_bf16 v[14:17], v[84:87], v[214:217], v[14:17]
	v_mfma_f32_16x16x32_bf16 v[68:71], v[64:67], v[194:197], v[68:71]
	v_mfma_f32_16x16x32_bf16 v[72:75], v[104:107], v[194:197], v[72:75]
	v_mfma_f32_16x16x32_bf16 v[48:51], v[64:67], v[202:205], v[48:51]
	v_mfma_f32_16x16x32_bf16 v[52:55], v[104:107], v[202:205], v[52:55]
	v_mfma_f32_16x16x32_bf16 v[28:31], v[64:67], v[210:213], v[28:31]
	v_mfma_f32_16x16x32_bf16 v[32:35], v[104:107], v[210:213], v[32:35]
	s_waitcnt lgkmcnt(0)
	v_mfma_f32_16x16x32_bf16 v[10:13], v[64:67], v[218:221], v[10:13]
	v_mfma_f32_16x16x32_bf16 v[14:17], v[104:107], v[218:221], v[14:17]
	s_setprio 0
	s_setprio 1
	v_mfma_f32_16x16x32_bf16 v[36:39], v[124:127], v[190:193], v[36:39]
	v_mfma_f32_16x16x32_bf16 v[64:67], v[144:147], v[194:197], v[36:39]
	v_mfma_f32_16x16x32_bf16 v[36:39], v[156:159], v[190:193], v[56:59]
	v_mfma_f32_16x16x32_bf16 v[60:63], v[180:183], v[194:197], v[36:39]
	v_mfma_f32_16x16x32_bf16 v[36:39], v[124:127], v[198:201], v[44:47]
	v_mfma_f32_16x16x32_bf16 v[44:47], v[144:147], v[202:205], v[36:39]
	v_mfma_f32_16x16x32_bf16 v[36:39], v[156:159], v[198:201], v[40:43]
	v_mfma_f32_16x16x32_bf16 v[22:25], v[124:127], v[206:209], v[22:25]
	v_mfma_f32_16x16x32_bf16 v[18:21], v[156:159], v[206:209], v[18:21]
	v_mfma_f32_16x16x32_bf16 v[2:5], v[124:127], v[214:217], v[2:5]
	v_mfma_f32_16x16x32_bf16 v[6:9], v[156:159], v[214:217], v[6:9]
	v_mfma_f32_16x16x32_bf16 v[40:43], v[180:183], v[202:205], v[36:39]
	v_mfma_f32_16x16x32_bf16 v[22:25], v[144:147], v[210:213], v[22:25]
	v_mfma_f32_16x16x32_bf16 v[18:21], v[180:183], v[210:213], v[18:21]
	v_mfma_f32_16x16x32_bf16 v[2:5], v[144:147], v[218:221], v[2:5]
	v_mfma_f32_16x16x32_bf16 v[6:9], v[180:183], v[218:221], v[6:9]
	s_barrier
	s_setprio 0
	s_add_i32 s93, s93, 2
	s_add_u32 vcc_lo, vcc_lo, 0x100
	s_addc_u32 vcc_hi, vcc_hi, 0
	s_add_u32 s84, s84, 0x100
	s_addc_u32 s85, s85, 0
.LBB0_111:
	s_add_u32 s72, vcc_lo, 0xffea0080
	s_addc_u32 s73, vcc_hi, -1
	s_add_i32 s95, 0, 0x10000
	s_cmp_eq_u32 s93, 12
	s_cselect_b32 s79, s1, s73
	s_cselect_b32 s78, s0, s72
	v_add_u32_e32 v26, s95, v186
	s_cselect_b32 s77, s89, s85
	s_cselect_b32 s76, s88, s84
	s_add_i32 s12, 0, 0x14000
	ds_read_b128 v[36:39], v26
	ds_read_b128 v[56:59], v26 offset:1024
	ds_read_b128 v[84:87], v26 offset:2048
	ds_read_b128 v[104:107], v26 offset:3072
	v_add_u32_e32 v26, s12, v186
	ds_read_b128 v[124:127], v26
	ds_read_b128 v[144:147], v26 offset:1024
	ds_read_b128 v[156:159], v26 offset:2048
	ds_read_b128 v[180:183], v26 offset:3072
	v_lshl_add_u64 v[226:227], vcc, 0, v[176:177]
	s_add_i32 m0, s17, 0xc000
	ds_read_b128 v[190:193], v188
	ds_read_b128 v[194:197], v188 offset:1024
	ds_read_b128 v[198:201], v188 offset:2048
	ds_read_b128 v[202:205], v188 offset:3072
	ds_read_b128 v[206:209], v188 offset:4096
	ds_read_b128 v[210:213], v188 offset:5120
	ds_read_b128 v[214:217], v188 offset:6144
	ds_read_b128 v[218:221], v188 offset:7168
	global_load_lds_dwordx4 v[226:227], off
	v_lshl_add_u64 v[226:227], vcc, 0, v[178:179]
	s_add_i32 m0, s17, 0xe000
	s_nop 0
	global_load_lds_dwordx4 v[226:227], off
	s_waitcnt vmcnt(8)
	s_setprio 1
	s_barrier
	s_waitcnt lgkmcnt(7)
	v_mfma_f32_16x16x32_bf16 v[148:151], v[36:39], v[190:193], v[148:151]
	v_mfma_f32_16x16x32_bf16 v[152:155], v[84:87], v[190:193], v[152:155]
	s_waitcnt lgkmcnt(5)
	v_mfma_f32_16x16x32_bf16 v[128:131], v[36:39], v[198:201], v[128:131]
	v_mfma_f32_16x16x32_bf16 v[132:135], v[84:87], v[198:201], v[132:135]
	s_waitcnt lgkmcnt(3)
	v_mfma_f32_16x16x32_bf16 v[108:111], v[36:39], v[206:209], v[108:111]
	v_mfma_f32_16x16x32_bf16 v[112:115], v[84:87], v[206:209], v[112:115]
	s_waitcnt lgkmcnt(1)
	v_mfma_f32_16x16x32_bf16 v[88:91], v[36:39], v[214:217], v[88:91]
	v_mfma_f32_16x16x32_bf16 v[92:95], v[84:87], v[214:217], v[92:95]
	v_mfma_f32_16x16x32_bf16 v[148:151], v[56:59], v[194:197], v[148:151]
	v_mfma_f32_16x16x32_bf16 v[152:155], v[104:107], v[194:197], v[152:155]
	v_mfma_f32_16x16x32_bf16 v[128:131], v[56:59], v[202:205], v[128:131]
	v_mfma_f32_16x16x32_bf16 v[132:135], v[104:107], v[202:205], v[132:135]
	v_mfma_f32_16x16x32_bf16 v[108:111], v[56:59], v[210:213], v[108:111]
	v_mfma_f32_16x16x32_bf16 v[112:115], v[104:107], v[210:213], v[112:115]
	s_waitcnt lgkmcnt(0)
	v_mfma_f32_16x16x32_bf16 v[88:91], v[56:59], v[218:221], v[88:91]
	v_mfma_f32_16x16x32_bf16 v[92:95], v[104:107], v[218:221], v[92:95]
	s_setprio 0
	s_setprio 1
	v_mfma_f32_16x16x32_bf16 v[140:143], v[124:127], v[190:193], v[140:143]
	v_mfma_f32_16x16x32_bf16 v[136:139], v[156:159], v[190:193], v[136:139]
	v_mfma_f32_16x16x32_bf16 v[120:123], v[124:127], v[198:201], v[120:123]
	v_mfma_f32_16x16x32_bf16 v[116:119], v[156:159], v[198:201], v[116:119]
	v_mfma_f32_16x16x32_bf16 v[100:103], v[124:127], v[206:209], v[100:103]
	v_mfma_f32_16x16x32_bf16 v[96:99], v[156:159], v[206:209], v[96:99]
	v_mfma_f32_16x16x32_bf16 v[80:83], v[124:127], v[214:217], v[80:83]
	v_mfma_f32_16x16x32_bf16 v[76:79], v[156:159], v[214:217], v[76:79]
	v_mfma_f32_16x16x32_bf16 v[140:143], v[144:147], v[194:197], v[140:143]
	v_mfma_f32_16x16x32_bf16 v[136:139], v[180:183], v[194:197], v[136:139]
	v_mfma_f32_16x16x32_bf16 v[120:123], v[144:147], v[202:205], v[120:123]
	v_mfma_f32_16x16x32_bf16 v[116:119], v[180:183], v[202:205], v[116:119]
	v_mfma_f32_16x16x32_bf16 v[100:103], v[144:147], v[210:213], v[100:103]
	v_mfma_f32_16x16x32_bf16 v[96:99], v[180:183], v[210:213], v[96:99]
	v_mfma_f32_16x16x32_bf16 v[80:83], v[144:147], v[218:221], v[80:83]
	v_mfma_f32_16x16x32_bf16 v[76:79], v[180:183], v[218:221], v[76:79]
	s_barrier
	s_setprio 0
	s_add_i32 s72, s95, s16
	v_lshl_add_u64 v[226:227], s[76:77], 0, v[164:165]
	s_mov_b32 m0, s72
	ds_read_b128 v[190:193], v188 offset:16384
	ds_read_b128 v[194:197], v188 offset:17408
	ds_read_b128 v[198:201], v188 offset:18432
	ds_read_b128 v[202:205], v188 offset:19456
	ds_read_b128 v[206:209], v188 offset:20480
	ds_read_b128 v[210:213], v188 offset:21504
	ds_read_b128 v[214:217], v188 offset:22528
	ds_read_b128 v[218:221], v188 offset:23552
	global_load_lds_dwordx4 v[226:227], off
	s_add_i32 m0, s72, 0x2000
	s_add_u32 s72, s76, 0x40000
	v_lshl_add_u64 v[228:229], s[76:77], 0, v[160:161]
	s_addc_u32 s73, s77, 0
	s_add_i32 s12, s12, s16
	global_load_lds_dwordx4 v[228:229], off
	v_lshl_add_u64 v[230:231], s[72:73], 0, v[164:165]
	s_mov_b32 m0, s12
	v_lshl_add_u64 v[232:233], s[78:79], 0, v[162:163]
	global_load_lds_dwordx4 v[230:231], off
	v_lshl_add_u64 v[230:231], s[72:73], 0, v[160:161]
	s_add_i32 m0, s12, 0x2000
	s_nop 0
	global_load_lds_dwordx4 v[230:231], off
	v_lshl_add_u64 v[230:231], s[78:79], 0, v[166:167]
	s_mov_b32 m0, s17
	s_nop 0
	global_load_lds_dwordx4 v[230:231], off
	s_mov_b32 m0, s46
	s_nop 0
	global_load_lds_dwordx4 v[232:233], off
	s_waitcnt vmcnt(8)
	s_setprio 1
	s_barrier
	s_waitcnt lgkmcnt(7)
	v_mfma_f32_16x16x32_bf16 v[68:71], v[36:39], v[190:193], v[68:71]
	v_mfma_f32_16x16x32_bf16 v[72:75], v[84:87], v[190:193], v[72:75]
	s_waitcnt lgkmcnt(5)
	v_mfma_f32_16x16x32_bf16 v[48:51], v[36:39], v[198:201], v[48:51]
	v_mfma_f32_16x16x32_bf16 v[52:55], v[84:87], v[198:201], v[52:55]
	s_waitcnt lgkmcnt(3)
	v_mfma_f32_16x16x32_bf16 v[28:31], v[36:39], v[206:209], v[28:31]
	v_mfma_f32_16x16x32_bf16 v[32:35], v[84:87], v[206:209], v[32:35]
	s_waitcnt lgkmcnt(1)
	v_mfma_f32_16x16x32_bf16 v[10:13], v[36:39], v[214:217], v[10:13]
	v_mfma_f32_16x16x32_bf16 v[14:17], v[84:87], v[214:217], v[14:17]
	v_mfma_f32_16x16x32_bf16 v[68:71], v[56:59], v[194:197], v[68:71]
	v_mfma_f32_16x16x32_bf16 v[72:75], v[104:107], v[194:197], v[72:75]
	v_mfma_f32_16x16x32_bf16 v[48:51], v[56:59], v[202:205], v[48:51]
	v_mfma_f32_16x16x32_bf16 v[52:55], v[104:107], v[202:205], v[52:55]
	v_mfma_f32_16x16x32_bf16 v[28:31], v[56:59], v[210:213], v[28:31]
	v_mfma_f32_16x16x32_bf16 v[32:35], v[104:107], v[210:213], v[32:35]
	s_waitcnt lgkmcnt(0)
	v_mfma_f32_16x16x32_bf16 v[10:13], v[56:59], v[218:221], v[10:13]
	v_mfma_f32_16x16x32_bf16 v[14:17], v[104:107], v[218:221], v[14:17]
	s_setprio 0
	s_setprio 1
	v_mfma_f32_16x16x32_bf16 v[44:47], v[124:127], v[198:201], v[44:47]
	v_mfma_f32_16x16x32_bf16 v[40:43], v[156:159], v[198:201], v[40:43]
	v_mfma_f32_16x16x32_bf16 v[22:25], v[124:127], v[206:209], v[22:25]
	v_mfma_f32_16x16x32_bf16 v[18:21], v[156:159], v[206:209], v[18:21]
	v_mfma_f32_16x16x32_bf16 v[2:5], v[124:127], v[214:217], v[2:5]
	v_mfma_f32_16x16x32_bf16 v[6:9], v[156:159], v[214:217], v[6:9]
	v_mfma_f32_16x16x32_bf16 v[36:39], v[124:127], v[190:193], v[64:67]
	v_mfma_f32_16x16x32_bf16 v[56:59], v[156:159], v[190:193], v[60:63]
	v_mfma_f32_16x16x32_bf16 v[44:47], v[144:147], v[202:205], v[44:47]
	v_mfma_f32_16x16x32_bf16 v[40:43], v[180:183], v[202:205], v[40:43]
	v_mfma_f32_16x16x32_bf16 v[22:25], v[144:147], v[210:213], v[22:25]
	v_mfma_f32_16x16x32_bf16 v[18:21], v[180:183], v[210:213], v[18:21]
	v_mfma_f32_16x16x32_bf16 v[2:5], v[144:147], v[218:221], v[2:5]
	v_mfma_f32_16x16x32_bf16 v[6:9], v[180:183], v[218:221], v[6:9]
	v_mfma_f32_16x16x32_bf16 v[36:39], v[144:147], v[194:197], v[36:39]
	v_mfma_f32_16x16x32_bf16 v[56:59], v[180:183], v[194:197], v[56:59]
	s_barrier
	s_setprio 0
	s_add_i32 s12, 0, 0x18000
	v_add_u32_e32 v26, s12, v186
	s_add_i32 s95, 0, 0x1c000
	ds_read_b128 v[60:63], v26
	ds_read_b128 v[64:67], v26 offset:1024
	ds_read_b128 v[84:87], v26 offset:2048
	ds_read_b128 v[104:107], v26 offset:3072
	v_add_u32_e32 v26, s95, v186
	ds_read_b128 v[124:127], v26
	ds_read_b128 v[144:147], v26 offset:1024
	ds_read_b128 v[156:159], v26 offset:2048
	ds_read_b128 v[180:183], v26 offset:3072
	s_add_u32 s72, s78, 0x160000
	s_addc_u32 s73, s79, 0
	s_mov_b32 m0, s47
	v_lshl_add_u64 v[234:235], s[72:73], 0, v[166:167]
	ds_read_b128 v[190:193], v188 offset:32768
	ds_read_b128 v[194:197], v188 offset:33792
	ds_read_b128 v[198:201], v188 offset:34816
	ds_read_b128 v[202:205], v188 offset:35840
	ds_read_b128 v[206:209], v188 offset:36864
	ds_read_b128 v[210:213], v188 offset:37888
	ds_read_b128 v[214:217], v188 offset:38912
	ds_read_b128 v[218:221], v188 offset:39936
	global_load_lds_dwordx4 v[234:235], off
	v_lshl_add_u64 v[234:235], s[72:73], 0, v[162:163]
	s_mov_b32 m0, s8
	s_nop 0
	global_load_lds_dwordx4 v[234:235], off
	s_waitcnt vmcnt(8)
	s_setprio 1
	s_barrier
	s_waitcnt lgkmcnt(7)
	v_mfma_f32_16x16x32_bf16 v[148:151], v[60:63], v[190:193], v[148:151]
	v_mfma_f32_16x16x32_bf16 v[152:155], v[84:87], v[190:193], v[152:155]
	s_waitcnt lgkmcnt(5)
	v_mfma_f32_16x16x32_bf16 v[128:131], v[60:63], v[198:201], v[128:131]
	v_mfma_f32_16x16x32_bf16 v[132:135], v[84:87], v[198:201], v[132:135]
	s_waitcnt lgkmcnt(3)
	v_mfma_f32_16x16x32_bf16 v[108:111], v[60:63], v[206:209], v[108:111]
	v_mfma_f32_16x16x32_bf16 v[112:115], v[84:87], v[206:209], v[112:115]
	s_waitcnt lgkmcnt(1)
	v_mfma_f32_16x16x32_bf16 v[88:91], v[60:63], v[214:217], v[88:91]
	v_mfma_f32_16x16x32_bf16 v[92:95], v[84:87], v[214:217], v[92:95]
	v_mfma_f32_16x16x32_bf16 v[148:151], v[64:67], v[194:197], v[148:151]
	v_mfma_f32_16x16x32_bf16 v[152:155], v[104:107], v[194:197], v[152:155]
	v_mfma_f32_16x16x32_bf16 v[128:131], v[64:67], v[202:205], v[128:131]
	v_mfma_f32_16x16x32_bf16 v[132:135], v[104:107], v[202:205], v[132:135]
	v_mfma_f32_16x16x32_bf16 v[108:111], v[64:67], v[210:213], v[108:111]
	v_mfma_f32_16x16x32_bf16 v[112:115], v[104:107], v[210:213], v[112:115]
	s_waitcnt lgkmcnt(0)
	v_mfma_f32_16x16x32_bf16 v[88:91], v[64:67], v[218:221], v[88:91]
	v_mfma_f32_16x16x32_bf16 v[92:95], v[104:107], v[218:221], v[92:95]
	s_setprio 0
	s_setprio 1
	v_mfma_f32_16x16x32_bf16 v[140:143], v[124:127], v[190:193], v[140:143]
	v_mfma_f32_16x16x32_bf16 v[136:139], v[156:159], v[190:193], v[136:139]
	v_mfma_f32_16x16x32_bf16 v[120:123], v[124:127], v[198:201], v[120:123]
	v_mfma_f32_16x16x32_bf16 v[116:119], v[156:159], v[198:201], v[116:119]
	v_mfma_f32_16x16x32_bf16 v[100:103], v[124:127], v[206:209], v[100:103]
	v_mfma_f32_16x16x32_bf16 v[96:99], v[156:159], v[206:209], v[96:99]
	v_mfma_f32_16x16x32_bf16 v[80:83], v[124:127], v[214:217], v[80:83]
	v_mfma_f32_16x16x32_bf16 v[76:79], v[156:159], v[214:217], v[76:79]
	v_mfma_f32_16x16x32_bf16 v[140:143], v[144:147], v[194:197], v[140:143]
	v_mfma_f32_16x16x32_bf16 v[136:139], v[180:183], v[194:197], v[136:139]
	v_mfma_f32_16x16x32_bf16 v[120:123], v[144:147], v[202:205], v[120:123]
	v_mfma_f32_16x16x32_bf16 v[116:119], v[180:183], v[202:205], v[116:119]
	v_mfma_f32_16x16x32_bf16 v[100:103], v[144:147], v[210:213], v[100:103]
	v_mfma_f32_16x16x32_bf16 v[96:99], v[180:183], v[210:213], v[96:99]
	v_mfma_f32_16x16x32_bf16 v[80:83], v[144:147], v[218:221], v[80:83]
	v_mfma_f32_16x16x32_bf16 v[76:79], v[180:183], v[218:221], v[76:79]
	s_barrier
	s_setprio 0
	s_add_i32 s12, s12, s16
	v_lshl_add_u64 v[226:227], v[226:227], 0, s[82:83]
	s_mov_b32 m0, s12
	ds_read_b128 v[190:193], v188 offset:49152
	ds_read_b128 v[194:197], v188 offset:50176
	ds_read_b128 v[198:201], v188 offset:51200
	ds_read_b128 v[202:205], v188 offset:52224
	ds_read_b128 v[206:209], v188 offset:53248
	ds_read_b128 v[210:213], v188 offset:54272
	ds_read_b128 v[214:217], v188 offset:55296
	ds_read_b128 v[218:221], v188 offset:56320
	global_load_lds_dwordx4 v[226:227], off
	s_add_i32 m0, s12, 0x2000
	s_add_u32 s72, s76, 0x40080
	v_lshl_add_u64 v[226:227], v[228:229], 0, s[82:83]
	s_addc_u32 s73, s77, 0
	s_add_i32 s12, s95, s16
	global_load_lds_dwordx4 v[226:227], off
	v_lshl_add_u64 v[226:227], s[72:73], 0, v[164:165]
	s_mov_b32 m0, s12
	s_nop 0
	global_load_lds_dwordx4 v[226:227], off
	v_lshl_add_u64 v[226:227], s[72:73], 0, v[160:161]
	s_add_i32 m0, s12, 0x2000
	s_nop 0
	global_load_lds_dwordx4 v[226:227], off
	v_lshl_add_u64 v[226:227], v[230:231], 0, s[82:83]
	s_mov_b32 m0, s22
	s_nop 0
	global_load_lds_dwordx4 v[226:227], off
	v_lshl_add_u64 v[226:227], v[232:233], 0, s[82:83]
	s_mov_b32 m0, s80
	s_nop 0
	global_load_lds_dwordx4 v[226:227], off
	s_waitcnt vmcnt(8)
	s_setprio 1
	s_barrier
	s_waitcnt lgkmcnt(7)
	v_mfma_f32_16x16x32_bf16 v[68:71], v[60:63], v[190:193], v[68:71]
	v_mfma_f32_16x16x32_bf16 v[72:75], v[84:87], v[190:193], v[72:75]
	s_waitcnt lgkmcnt(5)
	v_mfma_f32_16x16x32_bf16 v[48:51], v[60:63], v[198:201], v[48:51]
	v_mfma_f32_16x16x32_bf16 v[52:55], v[84:87], v[198:201], v[52:55]
	s_waitcnt lgkmcnt(3)
	v_mfma_f32_16x16x32_bf16 v[28:31], v[60:63], v[206:209], v[28:31]
	v_mfma_f32_16x16x32_bf16 v[32:35], v[84:87], v[206:209], v[32:35]
	s_waitcnt lgkmcnt(1)
	v_mfma_f32_16x16x32_bf16 v[10:13], v[60:63], v[214:217], v[10:13]
	v_mfma_f32_16x16x32_bf16 v[14:17], v[84:87], v[214:217], v[14:17]
	v_mfma_f32_16x16x32_bf16 v[68:71], v[64:67], v[194:197], v[68:71]
	v_mfma_f32_16x16x32_bf16 v[72:75], v[104:107], v[194:197], v[72:75]
	v_mfma_f32_16x16x32_bf16 v[48:51], v[64:67], v[202:205], v[48:51]
	v_mfma_f32_16x16x32_bf16 v[52:55], v[104:107], v[202:205], v[52:55]
	v_mfma_f32_16x16x32_bf16 v[28:31], v[64:67], v[210:213], v[28:31]
	v_mfma_f32_16x16x32_bf16 v[32:35], v[104:107], v[210:213], v[32:35]
	s_waitcnt lgkmcnt(0)
	v_mfma_f32_16x16x32_bf16 v[10:13], v[64:67], v[218:221], v[10:13]
	v_mfma_f32_16x16x32_bf16 v[14:17], v[104:107], v[218:221], v[14:17]
	s_setprio 0
	s_setprio 1
	v_mfma_f32_16x16x32_bf16 v[36:39], v[124:127], v[190:193], v[36:39]
	v_mfma_f32_16x16x32_bf16 v[64:67], v[144:147], v[194:197], v[36:39]
	v_mfma_f32_16x16x32_bf16 v[36:39], v[156:159], v[190:193], v[56:59]
	v_mfma_f32_16x16x32_bf16 v[60:63], v[180:183], v[194:197], v[36:39]
	v_mfma_f32_16x16x32_bf16 v[36:39], v[124:127], v[198:201], v[44:47]
	v_mfma_f32_16x16x32_bf16 v[44:47], v[144:147], v[202:205], v[36:39]
	v_mfma_f32_16x16x32_bf16 v[36:39], v[156:159], v[198:201], v[40:43]
	v_mfma_f32_16x16x32_bf16 v[22:25], v[124:127], v[206:209], v[22:25]
	v_mfma_f32_16x16x32_bf16 v[18:21], v[156:159], v[206:209], v[18:21]
	v_mfma_f32_16x16x32_bf16 v[2:5], v[124:127], v[214:217], v[2:5]
	v_mfma_f32_16x16x32_bf16 v[6:9], v[156:159], v[214:217], v[6:9]
	v_mfma_f32_16x16x32_bf16 v[40:43], v[180:183], v[202:205], v[36:39]
	v_mfma_f32_16x16x32_bf16 v[22:25], v[144:147], v[210:213], v[22:25]
	v_mfma_f32_16x16x32_bf16 v[18:21], v[180:183], v[210:213], v[18:21]
	v_mfma_f32_16x16x32_bf16 v[2:5], v[144:147], v[218:221], v[2:5]
	v_mfma_f32_16x16x32_bf16 v[6:9], v[180:183], v[218:221], v[6:9]
	s_barrier
	s_setprio 0
	s_add_i32 s93, s93, 2
	s_add_u32 vcc_lo, vcc_lo, 0x100
	s_addc_u32 vcc_hi, vcc_hi, 0
	s_add_u32 s84, s84, 0x100
	s_addc_u32 s85, s85, 0
	s_cmp_gt_u32 s93, 13
	s_cbranch_scc0 .LBB0_111
	s_and_b64 vcc, exec, s[60:61]
	s_cbranch_vccz .LBB0_114
	s_barrier

.LBB0_207:
	s_xor_b64 s[38:39], s[38:39], -1
	s_add_u32 s90, s78, 0x20080
	s_addc_u32 s91, s79, 0
	s_add_u32 s76, s76, 0x100
	s_addc_u32 s77, s77, 0
	s_mov_b32 s78, -2
	s_add_u32 s72, s90, 0xfffe0080
	s_addc_u32 s73, s91, -1
	s_add_i32 s79, 0, 0x10000
	s_cmp_eq_u32 s78, 4
	s_cselect_b32 s95, s89, s73
	s_cselect_b32 s94, s88, s72
	s_cselect_b32 s93, s61, s77
	s_cselect_b32 s92, s60, s76
	s_add_i32 s72, 0, 0x14000
	v_add_u32_e32 v14, s79, v189
	v_add_u32_e32 v26, s72, v189
	ds_read_b128 v[2:5], v14
	ds_read_b128 v[6:9], v14 offset:1024
	ds_read_b128 v[10:13], v14 offset:2048
	ds_read_b128 v[14:17], v14 offset:3072
	ds_read_b128 v[18:21], v26
	ds_read_b128 v[22:25], v26 offset:1024
	ds_read_b128 v[192:195], v26 offset:2048
	ds_read_b128 v[196:199], v26 offset:3072
	v_lshl_add_u64 v[216:217], s[90:91], 0, v[166:167]
	s_add_i32 m0, s11, 0xc000
	ds_read_b128 v[178:181], v190
	ds_read_b128 v[182:185], v190 offset:1024
	ds_read_b128 v[200:203], v190 offset:2048
	ds_read_b128 v[204:207], v190 offset:3072
	ds_read_b128 v[208:211], v190 offset:4096
	ds_read_b128 v[212:215], v190 offset:5120
	ds_read_b128 v[226:229], v190 offset:6144
	ds_read_b128 v[230:233], v190 offset:7168
	global_load_lds_dwordx4 v[216:217], off
	v_lshl_add_u64 v[216:217], s[90:91], 0, v[176:177]
	s_add_i32 m0, s11, 0xe000
	s_nop 0
	global_load_lds_dwordx4 v[216:217], off
	s_waitcnt vmcnt(8)
	s_setprio 1
	s_barrier
	s_waitcnt lgkmcnt(6)
	v_mfma_scale_f32_16x16x128_f8f6f4 v[148:151], v[2:9], v[178:185], 0, v186, v186 op_sel_hi:[0,0,0]
	v_mfma_scale_f32_16x16x128_f8f6f4 v[152:155], v[10:17], v[178:185], 0, v186, v186 op_sel_hi:[0,0,0]
	s_waitcnt lgkmcnt(4)
	v_mfma_scale_f32_16x16x128_f8f6f4 v[124:127], v[2:9], v[200:207], 0, v186, v186 op_sel_hi:[0,0,0]
	v_mfma_scale_f32_16x16x128_f8f6f4 v[128:131], v[10:17], v[200:207], 0, v186, v186 op_sel_hi:[0,0,0]
	s_waitcnt lgkmcnt(2)
	v_mfma_scale_f32_16x16x128_f8f6f4 v[108:111], v[2:9], v[208:215], 0, v186, v186 op_sel_hi:[0,0,0]
	v_mfma_scale_f32_16x16x128_f8f6f4 v[112:115], v[10:17], v[208:215], 0, v186, v186 op_sel_hi:[0,0,0]
	s_waitcnt lgkmcnt(0)
	v_mfma_scale_f32_16x16x128_f8f6f4 v[92:95], v[2:9], v[226:233], 0, v186, v186 op_sel_hi:[0,0,0]
	v_mfma_scale_f32_16x16x128_f8f6f4 v[96:99], v[10:17], v[226:233], 0, v186, v186 op_sel_hi:[0,0,0]
	s_setprio 0
	s_setprio 1
	v_mfma_scale_f32_16x16x128_f8f6f4 v[140:143], v[18:25], v[178:185], 0, v186, v186 op_sel_hi:[0,0,0]
	v_mfma_scale_f32_16x16x128_f8f6f4 v[144:147], v[192:199], v[178:185], 0, v186, v186 op_sel_hi:[0,0,0]
	v_mfma_scale_f32_16x16x128_f8f6f4 v[132:135], v[18:25], v[200:207], 0, v186, v186 op_sel_hi:[0,0,0]
	v_mfma_scale_f32_16x16x128_f8f6f4 v[136:139], v[192:199], v[200:207], 0, v186, v186 op_sel_hi:[0,0,0]
	v_mfma_scale_f32_16x16x128_f8f6f4 v[116:119], v[18:25], v[208:215], 0, v186, v186 op_sel_hi:[0,0,0]
	v_mfma_scale_f32_16x16x128_f8f6f4 v[120:123], v[192:199], v[208:215], 0, v186, v186 op_sel_hi:[0,0,0]
	v_mfma_scale_f32_16x16x128_f8f6f4 v[100:103], v[18:25], v[226:233], 0, v186, v186 op_sel_hi:[0,0,0]
	v_mfma_scale_f32_16x16x128_f8f6f4 v[104:107], v[192:199], v[226:233], 0, v186, v186 op_sel_hi:[0,0,0]
	s_barrier
	s_setprio 0
	s_add_i32 s73, s79, s8
	v_lshl_add_u64 v[178:179], s[92:93], 0, v[158:159]
	s_mov_b32 m0, s73
	ds_read_b128 v[200:203], v190 offset:16384
	ds_read_b128 v[204:207], v190 offset:17408
	ds_read_b128 v[208:211], v190 offset:18432
	ds_read_b128 v[212:215], v190 offset:19456
	ds_read_b128 v[226:229], v190 offset:20480
	ds_read_b128 v[230:233], v190 offset:21504
	ds_read_b128 v[234:237], v190 offset:22528
	ds_read_b128 v[238:241], v190 offset:23552
	global_load_lds_dwordx4 v[178:179], off
	s_add_i32 m0, s73, 0x2000
	s_add_u32 s80, s92, 0x20000
	v_lshl_add_u64 v[180:181], s[92:93], 0, v[162:163]
	s_addc_u32 s81, s93, 0
	s_add_i32 s72, s72, s8
	global_load_lds_dwordx4 v[180:181], off
	v_lshl_add_u64 v[182:183], s[80:81], 0, v[158:159]
	s_mov_b32 m0, s72
	v_lshl_add_u64 v[184:185], s[94:95], 0, v[160:161]
	global_load_lds_dwordx4 v[182:183], off
	v_lshl_add_u64 v[182:183], s[80:81], 0, v[162:163]
	s_add_i32 m0, s72, 0x2000
	s_nop 0
	global_load_lds_dwordx4 v[182:183], off
	v_lshl_add_u64 v[182:183], s[94:95], 0, v[156:157]
	s_mov_b32 m0, s11
	s_nop 0
	global_load_lds_dwordx4 v[182:183], off
	s_mov_b32 m0, s16
	s_nop 0
	global_load_lds_dwordx4 v[184:185], off
	s_waitcnt vmcnt(8)
	s_setprio 1
	s_barrier
	s_waitcnt lgkmcnt(6)
	v_mfma_scale_f32_16x16x128_f8f6f4 v[76:79], v[2:9], v[200:207], 0, v186, v186 op_sel_hi:[0,0,0]
	v_mfma_scale_f32_16x16x128_f8f6f4 v[80:83], v[10:17], v[200:207], 0, v186, v186 op_sel_hi:[0,0,0]
	s_waitcnt lgkmcnt(4)
	v_mfma_scale_f32_16x16x128_f8f6f4 v[60:63], v[2:9], v[208:215], 0, v186, v186 op_sel_hi:[0,0,0]
	v_mfma_scale_f32_16x16x128_f8f6f4 v[64:67], v[10:17], v[208:215], 0, v186, v186 op_sel_hi:[0,0,0]
	s_waitcnt lgkmcnt(2)
	v_mfma_scale_f32_16x16x128_f8f6f4 v[44:47], v[2:9], v[226:233], 0, v186, v186 op_sel_hi:[0,0,0]
	v_mfma_scale_f32_16x16x128_f8f6f4 v[48:51], v[10:17], v[226:233], 0, v186, v186 op_sel_hi:[0,0,0]
	s_waitcnt lgkmcnt(0)
	v_mfma_scale_f32_16x16x128_f8f6f4 v[28:31], v[2:9], v[234:241], 0, v186, v186 op_sel_hi:[0,0,0]
	v_mfma_scale_f32_16x16x128_f8f6f4 v[32:35], v[10:17], v[234:241], 0, v186, v186 op_sel_hi:[0,0,0]
	s_setprio 0
	s_setprio 1
	v_mfma_scale_f32_16x16x128_f8f6f4 v[84:87], v[18:25], v[200:207], 0, v186, v186 op_sel_hi:[0,0,0]
	v_mfma_scale_f32_16x16x128_f8f6f4 v[88:91], v[192:199], v[200:207], 0, v186, v186 op_sel_hi:[0,0,0]
	v_mfma_scale_f32_16x16x128_f8f6f4 v[68:71], v[18:25], v[208:215], 0, v186, v186 op_sel_hi:[0,0,0]
	v_mfma_scale_f32_16x16x128_f8f6f4 v[72:75], v[192:199], v[208:215], 0, v186, v186 op_sel_hi:[0,0,0]
	v_mfma_scale_f32_16x16x128_f8f6f4 v[52:55], v[18:25], v[226:233], 0, v186, v186 op_sel_hi:[0,0,0]
	v_mfma_scale_f32_16x16x128_f8f6f4 v[56:59], v[192:199], v[226:233], 0, v186, v186 op_sel_hi:[0,0,0]
	v_mfma_scale_f32_16x16x128_f8f6f4 v[36:39], v[18:25], v[234:241], 0, v186, v186 op_sel_hi:[0,0,0]
	v_mfma_scale_f32_16x16x128_f8f6f4 v[40:43], v[192:199], v[234:241], 0, v186, v186 op_sel_hi:[0,0,0]
	s_barrier
	s_setprio 0
	s_add_i32 s79, 0, 0x18000
	s_add_i32 s72, 0, 0x1c000
	v_add_u32_e32 v2, s79, v189
	v_add_u32_e32 v22, s72, v189
	ds_read_b128 v[10:13], v2
	ds_read_b128 v[14:17], v2 offset:1024
	ds_read_b128 v[192:195], v2 offset:2048
	ds_read_b128 v[196:199], v2 offset:3072
	ds_read_b128 v[2:5], v22
	ds_read_b128 v[6:9], v22 offset:1024
	ds_read_b128 v[18:21], v22 offset:2048
	ds_read_b128 v[22:25], v22 offset:3072
	s_add_u32 s80, s94, 0x20000
	s_addc_u32 s81, s95, 0
	s_mov_b32 m0, s17
	v_lshl_add_u64 v[216:217], s[80:81], 0, v[156:157]
	ds_read_b128 v[200:203], v190 offset:32768
	ds_read_b128 v[204:207], v190 offset:33792
	ds_read_b128 v[208:211], v190 offset:34816
	ds_read_b128 v[212:215], v190 offset:35840
	ds_read_b128 v[226:229], v190 offset:36864
	ds_read_b128 v[230:233], v190 offset:37888
	ds_read_b128 v[234:237], v190 offset:38912
	ds_read_b128 v[238:241], v190 offset:39936
	global_load_lds_dwordx4 v[216:217], off
	v_lshl_add_u64 v[216:217], s[80:81], 0, v[160:161]
	s_mov_b32 m0, s22
	s_nop 0
	global_load_lds_dwordx4 v[216:217], off
	s_waitcnt vmcnt(8)
	s_setprio 1
	s_barrier
	s_waitcnt lgkmcnt(6)
	v_mfma_scale_f32_16x16x128_f8f6f4 v[148:151], v[10:17], v[200:207], v[148:151], v186, v186 op_sel_hi:[0,0,0]
	v_mfma_scale_f32_16x16x128_f8f6f4 v[152:155], v[192:199], v[200:207], v[152:155], v186, v186 op_sel_hi:[0,0,0]
	s_waitcnt lgkmcnt(4)
	v_mfma_scale_f32_16x16x128_f8f6f4 v[124:127], v[10:17], v[208:215], v[124:127], v186, v186 op_sel_hi:[0,0,0]
	v_mfma_scale_f32_16x16x128_f8f6f4 v[128:131], v[192:199], v[208:215], v[128:131], v186, v186 op_sel_hi:[0,0,0]
	s_waitcnt lgkmcnt(2)
	v_mfma_scale_f32_16x16x128_f8f6f4 v[108:111], v[10:17], v[226:233], v[108:111], v186, v186 op_sel_hi:[0,0,0]
	v_mfma_scale_f32_16x16x128_f8f6f4 v[112:115], v[192:199], v[226:233], v[112:115], v186, v186 op_sel_hi:[0,0,0]
	s_waitcnt lgkmcnt(0)
	v_mfma_scale_f32_16x16x128_f8f6f4 v[92:95], v[10:17], v[234:241], v[92:95], v186, v186 op_sel_hi:[0,0,0]
	v_mfma_scale_f32_16x16x128_f8f6f4 v[96:99], v[192:199], v[234:241], v[96:99], v186, v186 op_sel_hi:[0,0,0]
	s_setprio 0
	s_setprio 1
	v_mfma_scale_f32_16x16x128_f8f6f4 v[140:143], v[2:9], v[200:207], v[140:143], v186, v186 op_sel_hi:[0,0,0]
	v_mfma_scale_f32_16x16x128_f8f6f4 v[144:147], v[18:25], v[200:207], v[144:147], v186, v186 op_sel_hi:[0,0,0]
	v_mfma_scale_f32_16x16x128_f8f6f4 v[132:135], v[2:9], v[208:215], v[132:135], v186, v186 op_sel_hi:[0,0,0]
	v_mfma_scale_f32_16x16x128_f8f6f4 v[136:139], v[18:25], v[208:215], v[136:139], v186, v186 op_sel_hi:[0,0,0]
	v_mfma_scale_f32_16x16x128_f8f6f4 v[116:119], v[2:9], v[226:233], v[116:119], v186, v186 op_sel_hi:[0,0,0]
	v_mfma_scale_f32_16x16x128_f8f6f4 v[120:123], v[18:25], v[226:233], v[120:123], v186, v186 op_sel_hi:[0,0,0]
	v_mfma_scale_f32_16x16x128_f8f6f4 v[100:103], v[2:9], v[234:241], v[100:103], v186, v186 op_sel_hi:[0,0,0]
	v_mfma_scale_f32_16x16x128_f8f6f4 v[104:107], v[18:25], v[234:241], v[104:107], v186, v186 op_sel_hi:[0,0,0]
	s_barrier
	s_setprio 0
	s_add_i32 s73, s79, s8
	v_lshl_add_u64 v[178:179], v[178:179], 0, s[82:83]
	s_mov_b32 m0, s73
	ds_read_b128 v[200:203], v190 offset:49152
	ds_read_b128 v[204:207], v190 offset:50176
	ds_read_b128 v[208:211], v190 offset:51200
	ds_read_b128 v[212:215], v190 offset:52224
	ds_read_b128 v[226:229], v190 offset:53248
	ds_read_b128 v[230:233], v190 offset:54272
	ds_read_b128 v[234:237], v190 offset:55296
	ds_read_b128 v[238:241], v190 offset:56320
	global_load_lds_dwordx4 v[178:179], off
	s_add_i32 m0, s73, 0x2000
	s_add_u32 s80, s92, 0x20080
	v_lshl_add_u64 v[178:179], v[180:181], 0, s[82:83]
	s_addc_u32 s81, s93, 0
	s_add_i32 s72, s72, s8
	global_load_lds_dwordx4 v[178:179], off
	v_lshl_add_u64 v[178:179], s[80:81], 0, v[158:159]
	s_mov_b32 m0, s72
	s_nop 0
	global_load_lds_dwordx4 v[178:179], off
	v_lshl_add_u64 v[178:179], s[80:81], 0, v[162:163]
	s_add_i32 m0, s72, 0x2000
	s_nop 0
	global_load_lds_dwordx4 v[178:179], off
	v_lshl_add_u64 v[178:179], v[182:183], 0, s[82:83]
	s_mov_b32 m0, s26
	s_nop 0
	global_load_lds_dwordx4 v[178:179], off
	v_lshl_add_u64 v[178:179], v[184:185], 0, s[82:83]
	s_mov_b32 m0, s27
	s_nop 0
	global_load_lds_dwordx4 v[178:179], off
	s_waitcnt vmcnt(8)
	s_setprio 1
	s_barrier
	s_waitcnt lgkmcnt(6)
	v_mfma_scale_f32_16x16x128_f8f6f4 v[76:79], v[10:17], v[200:207], v[76:79], v186, v186 op_sel_hi:[0,0,0]
	v_mfma_scale_f32_16x16x128_f8f6f4 v[80:83], v[192:199], v[200:207], v[80:83], v186, v186 op_sel_hi:[0,0,0]
	s_waitcnt lgkmcnt(4)
	v_mfma_scale_f32_16x16x128_f8f6f4 v[60:63], v[10:17], v[208:215], v[60:63], v186, v186 op_sel_hi:[0,0,0]
	v_mfma_scale_f32_16x16x128_f8f6f4 v[64:67], v[192:199], v[208:215], v[64:67], v186, v186 op_sel_hi:[0,0,0]
	s_waitcnt lgkmcnt(2)
	v_mfma_scale_f32_16x16x128_f8f6f4 v[44:47], v[10:17], v[226:233], v[44:47], v186, v186 op_sel_hi:[0,0,0]
	v_mfma_scale_f32_16x16x128_f8f6f4 v[48:51], v[192:199], v[226:233], v[48:51], v186, v186 op_sel_hi:[0,0,0]
	s_waitcnt lgkmcnt(0)
	v_mfma_scale_f32_16x16x128_f8f6f4 v[28:31], v[10:17], v[234:241], v[28:31], v186, v186 op_sel_hi:[0,0,0]
	v_mfma_scale_f32_16x16x128_f8f6f4 v[32:35], v[192:199], v[234:241], v[32:35], v186, v186 op_sel_hi:[0,0,0]
	s_setprio 0
	s_setprio 1
	v_mfma_scale_f32_16x16x128_f8f6f4 v[84:87], v[2:9], v[200:207], v[84:87], v186, v186 op_sel_hi:[0,0,0]
	v_mfma_scale_f32_16x16x128_f8f6f4 v[88:91], v[18:25], v[200:207], v[88:91], v186, v186 op_sel_hi:[0,0,0]
	v_mfma_scale_f32_16x16x128_f8f6f4 v[68:71], v[2:9], v[208:215], v[68:71], v186, v186 op_sel_hi:[0,0,0]
	v_mfma_scale_f32_16x16x128_f8f6f4 v[72:75], v[18:25], v[208:215], v[72:75], v186, v186 op_sel_hi:[0,0,0]
	v_mfma_scale_f32_16x16x128_f8f6f4 v[52:55], v[2:9], v[226:233], v[52:55], v186, v186 op_sel_hi:[0,0,0]
	v_mfma_scale_f32_16x16x128_f8f6f4 v[56:59], v[18:25], v[226:233], v[56:59], v186, v186 op_sel_hi:[0,0,0]
	v_mfma_scale_f32_16x16x128_f8f6f4 v[36:39], v[2:9], v[234:241], v[36:39], v186, v186 op_sel_hi:[0,0,0]
	v_mfma_scale_f32_16x16x128_f8f6f4 v[40:43], v[18:25], v[234:241], v[40:43], v186, v186 op_sel_hi:[0,0,0]
	s_barrier
	s_setprio 0
	s_add_i32 s78, s78, 2
	s_add_u32 s90, s90, 0x100
	s_addc_u32 s91, s91, 0
	s_add_u32 s76, s76, 0x100
	s_addc_u32 s77, s77, 0
.LBB0_208:
	s_add_u32 s72, s90, 0xfffe0080
	s_addc_u32 s73, s91, -1
	s_add_i32 s79, 0, 0x10000
	s_cmp_eq_u32 s78, 4
	s_cselect_b32 s95, s89, s73
	s_cselect_b32 s94, s88, s72
	s_cselect_b32 s93, s61, s77
	s_cselect_b32 s92, s60, s76
	s_add_i32 s72, 0, 0x14000
	v_add_u32_e32 v14, s79, v189
	v_add_u32_e32 v26, s72, v189
	ds_read_b128 v[2:5], v14
	ds_read_b128 v[6:9], v14 offset:1024
	ds_read_b128 v[10:13], v14 offset:2048
	ds_read_b128 v[14:17], v14 offset:3072
	ds_read_b128 v[18:21], v26
	ds_read_b128 v[22:25], v26 offset:1024
	ds_read_b128 v[192:195], v26 offset:2048
	ds_read_b128 v[196:199], v26 offset:3072
	v_lshl_add_u64 v[216:217], s[90:91], 0, v[166:167]
	s_add_i32 m0, s11, 0xc000
	ds_read_b128 v[178:181], v190
	ds_read_b128 v[182:185], v190 offset:1024
	ds_read_b128 v[200:203], v190 offset:2048
	ds_read_b128 v[204:207], v190 offset:3072
	ds_read_b128 v[208:211], v190 offset:4096
	ds_read_b128 v[212:215], v190 offset:5120
	ds_read_b128 v[226:229], v190 offset:6144
	ds_read_b128 v[230:233], v190 offset:7168
	global_load_lds_dwordx4 v[216:217], off
	v_lshl_add_u64 v[216:217], s[90:91], 0, v[176:177]
	s_add_i32 m0, s11, 0xe000
	s_nop 0
	global_load_lds_dwordx4 v[216:217], off
	s_waitcnt vmcnt(8)
	s_setprio 1
	s_barrier
	s_waitcnt lgkmcnt(6)
	v_mfma_scale_f32_16x16x128_f8f6f4 v[148:151], v[2:9], v[178:185], v[148:151], v186, v186 op_sel_hi:[0,0,0]
	v_mfma_scale_f32_16x16x128_f8f6f4 v[152:155], v[10:17], v[178:185], v[152:155], v186, v186 op_sel_hi:[0,0,0]
	s_waitcnt lgkmcnt(4)
	v_mfma_scale_f32_16x16x128_f8f6f4 v[124:127], v[2:9], v[200:207], v[124:127], v186, v186 op_sel_hi:[0,0,0]
	v_mfma_scale_f32_16x16x128_f8f6f4 v[128:131], v[10:17], v[200:207], v[128:131], v186, v186 op_sel_hi:[0,0,0]
	s_waitcnt lgkmcnt(2)
	v_mfma_scale_f32_16x16x128_f8f6f4 v[108:111], v[2:9], v[208:215], v[108:111], v186, v186 op_sel_hi:[0,0,0]
	v_mfma_scale_f32_16x16x128_f8f6f4 v[112:115], v[10:17], v[208:215], v[112:115], v186, v186 op_sel_hi:[0,0,0]
	s_waitcnt lgkmcnt(0)
	v_mfma_scale_f32_16x16x128_f8f6f4 v[92:95], v[2:9], v[226:233], v[92:95], v186, v186 op_sel_hi:[0,0,0]
	v_mfma_scale_f32_16x16x128_f8f6f4 v[96:99], v[10:17], v[226:233], v[96:99], v186, v186 op_sel_hi:[0,0,0]
	s_setprio 0
	s_setprio 1
	v_mfma_scale_f32_16x16x128_f8f6f4 v[140:143], v[18:25], v[178:185], v[140:143], v186, v186 op_sel_hi:[0,0,0]
	v_mfma_scale_f32_16x16x128_f8f6f4 v[144:147], v[192:199], v[178:185], v[144:147], v186, v186 op_sel_hi:[0,0,0]
	v_mfma_scale_f32_16x16x128_f8f6f4 v[132:135], v[18:25], v[200:207], v[132:135], v186, v186 op_sel_hi:[0,0,0]
	v_mfma_scale_f32_16x16x128_f8f6f4 v[136:139], v[192:199], v[200:207], v[136:139], v186, v186 op_sel_hi:[0,0,0]
	v_mfma_scale_f32_16x16x128_f8f6f4 v[116:119], v[18:25], v[208:215], v[116:119], v186, v186 op_sel_hi:[0,0,0]
	v_mfma_scale_f32_16x16x128_f8f6f4 v[120:123], v[192:199], v[208:215], v[120:123], v186, v186 op_sel_hi:[0,0,0]
	v_mfma_scale_f32_16x16x128_f8f6f4 v[100:103], v[18:25], v[226:233], v[100:103], v186, v186 op_sel_hi:[0,0,0]
	v_mfma_scale_f32_16x16x128_f8f6f4 v[104:107], v[192:199], v[226:233], v[104:107], v186, v186 op_sel_hi:[0,0,0]
	s_barrier
	s_setprio 0
	s_add_i32 s73, s79, s8
	v_lshl_add_u64 v[178:179], s[92:93], 0, v[158:159]
	s_mov_b32 m0, s73
	ds_read_b128 v[200:203], v190 offset:16384
	ds_read_b128 v[204:207], v190 offset:17408
	ds_read_b128 v[208:211], v190 offset:18432
	ds_read_b128 v[212:215], v190 offset:19456
	ds_read_b128 v[226:229], v190 offset:20480
	ds_read_b128 v[230:233], v190 offset:21504
	ds_read_b128 v[234:237], v190 offset:22528
	ds_read_b128 v[238:241], v190 offset:23552
	global_load_lds_dwordx4 v[178:179], off
	s_add_i32 m0, s73, 0x2000
	s_add_u32 s80, s92, 0x20000
	v_lshl_add_u64 v[180:181], s[92:93], 0, v[162:163]
	s_addc_u32 s81, s93, 0
	s_add_i32 s72, s72, s8
	global_load_lds_dwordx4 v[180:181], off
	v_lshl_add_u64 v[182:183], s[80:81], 0, v[158:159]
	s_mov_b32 m0, s72
	v_lshl_add_u64 v[184:185], s[94:95], 0, v[160:161]
	global_load_lds_dwordx4 v[182:183], off
	v_lshl_add_u64 v[182:183], s[80:81], 0, v[162:163]
	s_add_i32 m0, s72, 0x2000
	s_nop 0
	global_load_lds_dwordx4 v[182:183], off
	v_lshl_add_u64 v[182:183], s[94:95], 0, v[156:157]
	s_mov_b32 m0, s11
	s_nop 0
	global_load_lds_dwordx4 v[182:183], off
	s_mov_b32 m0, s16
	s_nop 0
	global_load_lds_dwordx4 v[184:185], off
	s_waitcnt vmcnt(8)
	s_setprio 1
	s_barrier
	s_waitcnt lgkmcnt(6)
	v_mfma_scale_f32_16x16x128_f8f6f4 v[76:79], v[2:9], v[200:207], v[76:79], v186, v186 op_sel_hi:[0,0,0]
	v_mfma_scale_f32_16x16x128_f8f6f4 v[80:83], v[10:17], v[200:207], v[80:83], v186, v186 op_sel_hi:[0,0,0]
	s_waitcnt lgkmcnt(4)
	v_mfma_scale_f32_16x16x128_f8f6f4 v[60:63], v[2:9], v[208:215], v[60:63], v186, v186 op_sel_hi:[0,0,0]
	v_mfma_scale_f32_16x16x128_f8f6f4 v[64:67], v[10:17], v[208:215], v[64:67], v186, v186 op_sel_hi:[0,0,0]
	s_waitcnt lgkmcnt(2)
	v_mfma_scale_f32_16x16x128_f8f6f4 v[44:47], v[2:9], v[226:233], v[44:47], v186, v186 op_sel_hi:[0,0,0]
	v_mfma_scale_f32_16x16x128_f8f6f4 v[48:51], v[10:17], v[226:233], v[48:51], v186, v186 op_sel_hi:[0,0,0]
	s_waitcnt lgkmcnt(0)
	v_mfma_scale_f32_16x16x128_f8f6f4 v[28:31], v[2:9], v[234:241], v[28:31], v186, v186 op_sel_hi:[0,0,0]
	v_mfma_scale_f32_16x16x128_f8f6f4 v[32:35], v[10:17], v[234:241], v[32:35], v186, v186 op_sel_hi:[0,0,0]
	s_setprio 0
	s_setprio 1
	v_mfma_scale_f32_16x16x128_f8f6f4 v[84:87], v[18:25], v[200:207], v[84:87], v186, v186 op_sel_hi:[0,0,0]
	v_mfma_scale_f32_16x16x128_f8f6f4 v[88:91], v[192:199], v[200:207], v[88:91], v186, v186 op_sel_hi:[0,0,0]
	v_mfma_scale_f32_16x16x128_f8f6f4 v[68:71], v[18:25], v[208:215], v[68:71], v186, v186 op_sel_hi:[0,0,0]
	v_mfma_scale_f32_16x16x128_f8f6f4 v[72:75], v[192:199], v[208:215], v[72:75], v186, v186 op_sel_hi:[0,0,0]
	v_mfma_scale_f32_16x16x128_f8f6f4 v[52:55], v[18:25], v[226:233], v[52:55], v186, v186 op_sel_hi:[0,0,0]
	v_mfma_scale_f32_16x16x128_f8f6f4 v[56:59], v[192:199], v[226:233], v[56:59], v186, v186 op_sel_hi:[0,0,0]
	v_mfma_scale_f32_16x16x128_f8f6f4 v[36:39], v[18:25], v[234:241], v[36:39], v186, v186 op_sel_hi:[0,0,0]
	v_mfma_scale_f32_16x16x128_f8f6f4 v[40:43], v[192:199], v[234:241], v[40:43], v186, v186 op_sel_hi:[0,0,0]
	s_barrier
	s_setprio 0
	s_add_i32 s79, 0, 0x18000
	s_add_i32 s72, 0, 0x1c000
	v_add_u32_e32 v2, s79, v189
	v_add_u32_e32 v22, s72, v189
	ds_read_b128 v[10:13], v2
	ds_read_b128 v[14:17], v2 offset:1024
	ds_read_b128 v[192:195], v2 offset:2048
	ds_read_b128 v[196:199], v2 offset:3072
	ds_read_b128 v[2:5], v22
	ds_read_b128 v[6:9], v22 offset:1024
	ds_read_b128 v[18:21], v22 offset:2048
	ds_read_b128 v[22:25], v22 offset:3072
	s_add_u32 s80, s94, 0x20000
	s_addc_u32 s81, s95, 0
	s_mov_b32 m0, s17
	v_lshl_add_u64 v[216:217], s[80:81], 0, v[156:157]
	ds_read_b128 v[200:203], v190 offset:32768
	ds_read_b128 v[204:207], v190 offset:33792
	ds_read_b128 v[208:211], v190 offset:34816
	ds_read_b128 v[212:215], v190 offset:35840
	ds_read_b128 v[226:229], v190 offset:36864
	ds_read_b128 v[230:233], v190 offset:37888
	ds_read_b128 v[234:237], v190 offset:38912
	ds_read_b128 v[238:241], v190 offset:39936
	global_load_lds_dwordx4 v[216:217], off
	v_lshl_add_u64 v[216:217], s[80:81], 0, v[160:161]
	s_mov_b32 m0, s22
	s_nop 0
	global_load_lds_dwordx4 v[216:217], off
	s_waitcnt vmcnt(8)
	s_setprio 1
	s_barrier
	s_waitcnt lgkmcnt(6)
	v_mfma_scale_f32_16x16x128_f8f6f4 v[148:151], v[10:17], v[200:207], v[148:151], v186, v186 op_sel_hi:[0,0,0]
	v_mfma_scale_f32_16x16x128_f8f6f4 v[152:155], v[192:199], v[200:207], v[152:155], v186, v186 op_sel_hi:[0,0,0]
	s_waitcnt lgkmcnt(4)
	v_mfma_scale_f32_16x16x128_f8f6f4 v[124:127], v[10:17], v[208:215], v[124:127], v186, v186 op_sel_hi:[0,0,0]
	v_mfma_scale_f32_16x16x128_f8f6f4 v[128:131], v[192:199], v[208:215], v[128:131], v186, v186 op_sel_hi:[0,0,0]
	s_waitcnt lgkmcnt(2)
	v_mfma_scale_f32_16x16x128_f8f6f4 v[108:111], v[10:17], v[226:233], v[108:111], v186, v186 op_sel_hi:[0,0,0]
	v_mfma_scale_f32_16x16x128_f8f6f4 v[112:115], v[192:199], v[226:233], v[112:115], v186, v186 op_sel_hi:[0,0,0]
	s_waitcnt lgkmcnt(0)
	v_mfma_scale_f32_16x16x128_f8f6f4 v[92:95], v[10:17], v[234:241], v[92:95], v186, v186 op_sel_hi:[0,0,0]
	v_mfma_scale_f32_16x16x128_f8f6f4 v[96:99], v[192:199], v[234:241], v[96:99], v186, v186 op_sel_hi:[0,0,0]
	s_setprio 0
	s_setprio 1
	v_mfma_scale_f32_16x16x128_f8f6f4 v[140:143], v[2:9], v[200:207], v[140:143], v186, v186 op_sel_hi:[0,0,0]
	v_mfma_scale_f32_16x16x128_f8f6f4 v[144:147], v[18:25], v[200:207], v[144:147], v186, v186 op_sel_hi:[0,0,0]
	v_mfma_scale_f32_16x16x128_f8f6f4 v[132:135], v[2:9], v[208:215], v[132:135], v186, v186 op_sel_hi:[0,0,0]
	v_mfma_scale_f32_16x16x128_f8f6f4 v[136:139], v[18:25], v[208:215], v[136:139], v186, v186 op_sel_hi:[0,0,0]
	v_mfma_scale_f32_16x16x128_f8f6f4 v[116:119], v[2:9], v[226:233], v[116:119], v186, v186 op_sel_hi:[0,0,0]
	v_mfma_scale_f32_16x16x128_f8f6f4 v[120:123], v[18:25], v[226:233], v[120:123], v186, v186 op_sel_hi:[0,0,0]
	v_mfma_scale_f32_16x16x128_f8f6f4 v[100:103], v[2:9], v[234:241], v[100:103], v186, v186 op_sel_hi:[0,0,0]
	v_mfma_scale_f32_16x16x128_f8f6f4 v[104:107], v[18:25], v[234:241], v[104:107], v186, v186 op_sel_hi:[0,0,0]
	s_barrier
	s_setprio 0
	s_add_i32 s73, s79, s8
	v_lshl_add_u64 v[178:179], v[178:179], 0, s[82:83]
	s_mov_b32 m0, s73
	ds_read_b128 v[200:203], v190 offset:49152
	ds_read_b128 v[204:207], v190 offset:50176
	ds_read_b128 v[208:211], v190 offset:51200
	ds_read_b128 v[212:215], v190 offset:52224
	ds_read_b128 v[226:229], v190 offset:53248
	ds_read_b128 v[230:233], v190 offset:54272
	ds_read_b128 v[234:237], v190 offset:55296
	ds_read_b128 v[238:241], v190 offset:56320
	global_load_lds_dwordx4 v[178:179], off
	s_add_i32 m0, s73, 0x2000
	s_add_u32 s80, s92, 0x20080
	v_lshl_add_u64 v[178:179], v[180:181], 0, s[82:83]
	s_addc_u32 s81, s93, 0
	s_add_i32 s72, s72, s8
	global_load_lds_dwordx4 v[178:179], off
	v_lshl_add_u64 v[178:179], s[80:81], 0, v[158:159]
	s_mov_b32 m0, s72
	s_nop 0
	global_load_lds_dwordx4 v[178:179], off
	v_lshl_add_u64 v[178:179], s[80:81], 0, v[162:163]
	s_add_i32 m0, s72, 0x2000
	s_nop 0
	global_load_lds_dwordx4 v[178:179], off
	v_lshl_add_u64 v[178:179], v[182:183], 0, s[82:83]
	s_mov_b32 m0, s26
	s_nop 0
	global_load_lds_dwordx4 v[178:179], off
	v_lshl_add_u64 v[178:179], v[184:185], 0, s[82:83]
	s_mov_b32 m0, s27
	s_nop 0
	global_load_lds_dwordx4 v[178:179], off
	s_waitcnt vmcnt(8)
	s_setprio 1
	s_barrier
	s_waitcnt lgkmcnt(6)
	v_mfma_scale_f32_16x16x128_f8f6f4 v[76:79], v[10:17], v[200:207], v[76:79], v186, v186 op_sel_hi:[0,0,0]
	v_mfma_scale_f32_16x16x128_f8f6f4 v[80:83], v[192:199], v[200:207], v[80:83], v186, v186 op_sel_hi:[0,0,0]
	s_waitcnt lgkmcnt(4)
	v_mfma_scale_f32_16x16x128_f8f6f4 v[60:63], v[10:17], v[208:215], v[60:63], v186, v186 op_sel_hi:[0,0,0]
	v_mfma_scale_f32_16x16x128_f8f6f4 v[64:67], v[192:199], v[208:215], v[64:67], v186, v186 op_sel_hi:[0,0,0]
	s_waitcnt lgkmcnt(2)
	v_mfma_scale_f32_16x16x128_f8f6f4 v[44:47], v[10:17], v[226:233], v[44:47], v186, v186 op_sel_hi:[0,0,0]
	v_mfma_scale_f32_16x16x128_f8f6f4 v[48:51], v[192:199], v[226:233], v[48:51], v186, v186 op_sel_hi:[0,0,0]
	s_waitcnt lgkmcnt(0)
	v_mfma_scale_f32_16x16x128_f8f6f4 v[28:31], v[10:17], v[234:241], v[28:31], v186, v186 op_sel_hi:[0,0,0]
	v_mfma_scale_f32_16x16x128_f8f6f4 v[32:35], v[192:199], v[234:241], v[32:35], v186, v186 op_sel_hi:[0,0,0]
	s_setprio 0
	s_setprio 1
	v_mfma_scale_f32_16x16x128_f8f6f4 v[84:87], v[2:9], v[200:207], v[84:87], v186, v186 op_sel_hi:[0,0,0]
	v_mfma_scale_f32_16x16x128_f8f6f4 v[88:91], v[18:25], v[200:207], v[88:91], v186, v186 op_sel_hi:[0,0,0]
	v_mfma_scale_f32_16x16x128_f8f6f4 v[68:71], v[2:9], v[208:215], v[68:71], v186, v186 op_sel_hi:[0,0,0]
	v_mfma_scale_f32_16x16x128_f8f6f4 v[72:75], v[18:25], v[208:215], v[72:75], v186, v186 op_sel_hi:[0,0,0]
	v_mfma_scale_f32_16x16x128_f8f6f4 v[52:55], v[2:9], v[226:233], v[52:55], v186, v186 op_sel_hi:[0,0,0]
	v_mfma_scale_f32_16x16x128_f8f6f4 v[56:59], v[18:25], v[226:233], v[56:59], v186, v186 op_sel_hi:[0,0,0]
	v_mfma_scale_f32_16x16x128_f8f6f4 v[36:39], v[2:9], v[234:241], v[36:39], v186, v186 op_sel_hi:[0,0,0]
	v_mfma_scale_f32_16x16x128_f8f6f4 v[40:43], v[18:25], v[234:241], v[40:43], v186, v186 op_sel_hi:[0,0,0]
	s_barrier
	s_setprio 0
	s_add_i32 s78, s78, 2
	s_add_u32 s90, s90, 0x100
	s_addc_u32 s91, s91, 0
	s_add_u32 s76, s76, 0x100
	s_addc_u32 s77, s77, 0
	s_cmp_gt_u32 s78, 5
	s_cbranch_scc0 .LBB0_208
	s_and_b64 vcc, exec, s[30:31]
	s_cbranch_vccz .LBB0_211
	s_barrier

.LBB0_382:
	s_add_u32 s52, s52, 0x20080
	s_addc_u32 s53, s53, 0
	s_add_u32 s35, s20, 0x100
	s_addc_u32 s47, s21, 0
	s_mov_b32 s68, -2
	s_add_u32 s12, s52, 0xfffe0080
	s_addc_u32 s54, s53, -1
	s_add_i32 s72, 0, 0x10000
	s_cmp_eq_u32 s68, 4
	s_cselect_b32 s59, s37, s54
	s_cselect_b32 s58, s36, s12
	s_cselect_b32 s55, s21, s47
	s_cselect_b32 s54, s20, s35
	s_add_i32 s12, 0, 0x14000
	v_add_u32_e32 v14, s72, v190
	v_add_u32_e32 v26, s12, v190
	ds_read_b128 v[2:5], v14
	ds_read_b128 v[6:9], v14 offset:1024
	ds_read_b128 v[10:13], v14 offset:2048
	ds_read_b128 v[14:17], v14 offset:3072
	ds_read_b128 v[18:21], v26
	ds_read_b128 v[22:25], v26 offset:1024
	ds_read_b128 v[192:195], v26 offset:2048
	ds_read_b128 v[196:199], v26 offset:3072
	v_lshl_add_u64 v[216:217], s[52:53], 0, v[166:167]
	s_add_i32 m0, s11, 0xc000
	ds_read_b128 v[178:181], v191
	ds_read_b128 v[182:185], v191 offset:1024
	ds_read_b128 v[200:203], v191 offset:2048
	ds_read_b128 v[204:207], v191 offset:3072
	ds_read_b128 v[208:211], v191 offset:4096
	ds_read_b128 v[212:215], v191 offset:5120
	ds_read_b128 v[226:229], v191 offset:6144
	ds_read_b128 v[230:233], v191 offset:7168
	global_load_lds_dwordx4 v[216:217], off
	v_lshl_add_u64 v[216:217], s[52:53], 0, v[176:177]
	s_add_i32 m0, s11, 0xe000
	s_nop 0
	global_load_lds_dwordx4 v[216:217], off
	s_waitcnt vmcnt(8)
	s_setprio 1
	s_barrier
	s_waitcnt lgkmcnt(6)
	v_mfma_scale_f32_16x16x128_f8f6f4 v[140:143], v[2:9], v[178:185], 0, v187, v187 op_sel_hi:[0,0,0]
	v_mfma_scale_f32_16x16x128_f8f6f4 v[144:147], v[10:17], v[178:185], 0, v187, v187 op_sel_hi:[0,0,0]
	s_waitcnt lgkmcnt(4)
	v_mfma_scale_f32_16x16x128_f8f6f4 v[124:127], v[2:9], v[200:207], 0, v187, v187 op_sel_hi:[0,0,0]
	v_mfma_scale_f32_16x16x128_f8f6f4 v[128:131], v[10:17], v[200:207], 0, v187, v187 op_sel_hi:[0,0,0]
	s_waitcnt lgkmcnt(2)
	v_mfma_scale_f32_16x16x128_f8f6f4 v[108:111], v[2:9], v[208:215], 0, v187, v187 op_sel_hi:[0,0,0]
	v_mfma_scale_f32_16x16x128_f8f6f4 v[112:115], v[10:17], v[208:215], 0, v187, v187 op_sel_hi:[0,0,0]
	s_waitcnt lgkmcnt(0)
	v_mfma_scale_f32_16x16x128_f8f6f4 v[76:79], v[2:9], v[226:233], 0, v187, v187 op_sel_hi:[0,0,0]
	v_mfma_scale_f32_16x16x128_f8f6f4 v[84:87], v[10:17], v[226:233], 0, v187, v187 op_sel_hi:[0,0,0]
	s_setprio 0
	s_setprio 1
	v_mfma_scale_f32_16x16x128_f8f6f4 v[148:151], v[18:25], v[178:185], 0, v187, v187 op_sel_hi:[0,0,0]
	v_mfma_scale_f32_16x16x128_f8f6f4 v[152:155], v[192:199], v[178:185], 0, v187, v187 op_sel_hi:[0,0,0]
	v_mfma_scale_f32_16x16x128_f8f6f4 v[132:135], v[18:25], v[200:207], 0, v187, v187 op_sel_hi:[0,0,0]
	v_mfma_scale_f32_16x16x128_f8f6f4 v[136:139], v[192:199], v[200:207], 0, v187, v187 op_sel_hi:[0,0,0]
	v_mfma_scale_f32_16x16x128_f8f6f4 v[116:119], v[18:25], v[208:215], 0, v187, v187 op_sel_hi:[0,0,0]
	v_mfma_scale_f32_16x16x128_f8f6f4 v[120:123], v[192:199], v[208:215], 0, v187, v187 op_sel_hi:[0,0,0]
	v_mfma_scale_f32_16x16x128_f8f6f4 v[96:99], v[18:25], v[226:233], 0, v187, v187 op_sel_hi:[0,0,0]
	v_mfma_scale_f32_16x16x128_f8f6f4 v[104:107], v[192:199], v[226:233], 0, v187, v187 op_sel_hi:[0,0,0]
	s_barrier
	s_setprio 0
	s_add_i32 s72, s72, s8
	v_lshl_add_u64 v[178:179], s[54:55], 0, v[158:159]
	s_mov_b32 m0, s72
	ds_read_b128 v[200:203], v191 offset:16384
	ds_read_b128 v[204:207], v191 offset:17408
	ds_read_b128 v[208:211], v191 offset:18432
	ds_read_b128 v[212:215], v191 offset:19456
	ds_read_b128 v[226:229], v191 offset:20480
	ds_read_b128 v[230:233], v191 offset:21504
	ds_read_b128 v[234:237], v191 offset:22528
	ds_read_b128 v[238:241], v191 offset:23552
	global_load_lds_dwordx4 v[178:179], off
	s_add_i32 m0, s72, 0x2000
	s_add_u32 s72, s54, 0x20000
	v_lshl_add_u64 v[180:181], s[54:55], 0, v[162:163]
	s_addc_u32 s73, s55, 0
	s_add_i32 s12, s12, s8
	global_load_lds_dwordx4 v[180:181], off
	v_lshl_add_u64 v[182:183], s[72:73], 0, v[158:159]
	s_mov_b32 m0, s12
	v_lshl_add_u64 v[184:185], s[58:59], 0, v[160:161]
	global_load_lds_dwordx4 v[182:183], off
	v_lshl_add_u64 v[182:183], s[72:73], 0, v[162:163]
	s_add_i32 m0, s12, 0x2000
	s_nop 0
	global_load_lds_dwordx4 v[182:183], off
	v_lshl_add_u64 v[182:183], s[58:59], 0, v[156:157]
	s_mov_b32 m0, s11
	s_nop 0
	global_load_lds_dwordx4 v[182:183], off
	s_mov_b32 m0, s16
	s_nop 0
	global_load_lds_dwordx4 v[184:185], off
	s_waitcnt vmcnt(8)
	s_setprio 1
	s_barrier
	s_waitcnt lgkmcnt(6)
	v_mfma_scale_f32_16x16x128_f8f6f4 v[80:83], v[2:9], v[200:207], 0, v187, v187 op_sel_hi:[0,0,0]
	v_mfma_scale_f32_16x16x128_f8f6f4 v[88:91], v[10:17], v[200:207], 0, v187, v187 op_sel_hi:[0,0,0]
	s_waitcnt lgkmcnt(4)
	v_mfma_scale_f32_16x16x128_f8f6f4 v[60:63], v[2:9], v[208:215], 0, v187, v187 op_sel_hi:[0,0,0]
	v_mfma_scale_f32_16x16x128_f8f6f4 v[64:67], v[10:17], v[208:215], 0, v187, v187 op_sel_hi:[0,0,0]
	s_waitcnt lgkmcnt(2)
	v_mfma_scale_f32_16x16x128_f8f6f4 v[44:47], v[2:9], v[226:233], 0, v187, v187 op_sel_hi:[0,0,0]
	v_mfma_scale_f32_16x16x128_f8f6f4 v[48:51], v[10:17], v[226:233], 0, v187, v187 op_sel_hi:[0,0,0]
	s_waitcnt lgkmcnt(0)
	v_mfma_scale_f32_16x16x128_f8f6f4 v[28:31], v[2:9], v[234:241], 0, v187, v187 op_sel_hi:[0,0,0]
	v_mfma_scale_f32_16x16x128_f8f6f4 v[32:35], v[10:17], v[234:241], 0, v187, v187 op_sel_hi:[0,0,0]
	s_setprio 0
	s_setprio 1
	v_mfma_scale_f32_16x16x128_f8f6f4 v[92:95], v[18:25], v[200:207], 0, v187, v187 op_sel_hi:[0,0,0]
	v_mfma_scale_f32_16x16x128_f8f6f4 v[100:103], v[192:199], v[200:207], 0, v187, v187 op_sel_hi:[0,0,0]
	v_mfma_scale_f32_16x16x128_f8f6f4 v[68:71], v[18:25], v[208:215], 0, v187, v187 op_sel_hi:[0,0,0]
	v_mfma_scale_f32_16x16x128_f8f6f4 v[72:75], v[192:199], v[208:215], 0, v187, v187 op_sel_hi:[0,0,0]
	v_mfma_scale_f32_16x16x128_f8f6f4 v[52:55], v[18:25], v[226:233], 0, v187, v187 op_sel_hi:[0,0,0]
	v_mfma_scale_f32_16x16x128_f8f6f4 v[56:59], v[192:199], v[226:233], 0, v187, v187 op_sel_hi:[0,0,0]
	v_mfma_scale_f32_16x16x128_f8f6f4 v[36:39], v[18:25], v[234:241], 0, v187, v187 op_sel_hi:[0,0,0]
	v_mfma_scale_f32_16x16x128_f8f6f4 v[40:43], v[192:199], v[234:241], 0, v187, v187 op_sel_hi:[0,0,0]
	s_barrier
	s_setprio 0
	s_add_i32 s74, 0, 0x18000
	s_add_i32 s12, 0, 0x1c000
	v_add_u32_e32 v2, s74, v190
	v_add_u32_e32 v22, s12, v190
	ds_read_b128 v[10:13], v2
	ds_read_b128 v[14:17], v2 offset:1024
	ds_read_b128 v[192:195], v2 offset:2048
	ds_read_b128 v[196:199], v2 offset:3072
	ds_read_b128 v[2:5], v22
	ds_read_b128 v[6:9], v22 offset:1024
	ds_read_b128 v[18:21], v22 offset:2048
	ds_read_b128 v[22:25], v22 offset:3072
	s_add_u32 s58, s58, 0x20000
	s_addc_u32 s59, s59, 0
	s_mov_b32 m0, s17
	v_lshl_add_u64 v[216:217], s[58:59], 0, v[156:157]
	ds_read_b128 v[200:203], v191 offset:32768
	ds_read_b128 v[204:207], v191 offset:33792
	ds_read_b128 v[208:211], v191 offset:34816
	ds_read_b128 v[212:215], v191 offset:35840
	ds_read_b128 v[226:229], v191 offset:36864
	ds_read_b128 v[230:233], v191 offset:37888
	ds_read_b128 v[234:237], v191 offset:38912
	ds_read_b128 v[238:241], v191 offset:39936
	global_load_lds_dwordx4 v[216:217], off
	v_lshl_add_u64 v[216:217], s[58:59], 0, v[160:161]
	s_mov_b32 m0, s22
	s_nop 0
	global_load_lds_dwordx4 v[216:217], off
	s_waitcnt vmcnt(8)
	s_setprio 1
	s_barrier
	s_waitcnt lgkmcnt(6)
	v_mfma_scale_f32_16x16x128_f8f6f4 v[140:143], v[10:17], v[200:207], v[140:143], v187, v187 op_sel_hi:[0,0,0]
	v_mfma_scale_f32_16x16x128_f8f6f4 v[144:147], v[192:199], v[200:207], v[144:147], v187, v187 op_sel_hi:[0,0,0]
	s_waitcnt lgkmcnt(4)
	v_mfma_scale_f32_16x16x128_f8f6f4 v[124:127], v[10:17], v[208:215], v[124:127], v187, v187 op_sel_hi:[0,0,0]
	v_mfma_scale_f32_16x16x128_f8f6f4 v[128:131], v[192:199], v[208:215], v[128:131], v187, v187 op_sel_hi:[0,0,0]
	s_waitcnt lgkmcnt(2)
	v_mfma_scale_f32_16x16x128_f8f6f4 v[108:111], v[10:17], v[226:233], v[108:111], v187, v187 op_sel_hi:[0,0,0]
	v_mfma_scale_f32_16x16x128_f8f6f4 v[112:115], v[192:199], v[226:233], v[112:115], v187, v187 op_sel_hi:[0,0,0]
	s_waitcnt lgkmcnt(0)
	v_mfma_scale_f32_16x16x128_f8f6f4 v[76:79], v[10:17], v[234:241], v[76:79], v187, v187 op_sel_hi:[0,0,0]
	v_mfma_scale_f32_16x16x128_f8f6f4 v[84:87], v[192:199], v[234:241], v[84:87], v187, v187 op_sel_hi:[0,0,0]
	s_setprio 0
	s_setprio 1
	v_mfma_scale_f32_16x16x128_f8f6f4 v[148:151], v[2:9], v[200:207], v[148:151], v187, v187 op_sel_hi:[0,0,0]
	v_mfma_scale_f32_16x16x128_f8f6f4 v[152:155], v[18:25], v[200:207], v[152:155], v187, v187 op_sel_hi:[0,0,0]
	v_mfma_scale_f32_16x16x128_f8f6f4 v[132:135], v[2:9], v[208:215], v[132:135], v187, v187 op_sel_hi:[0,0,0]
	v_mfma_scale_f32_16x16x128_f8f6f4 v[136:139], v[18:25], v[208:215], v[136:139], v187, v187 op_sel_hi:[0,0,0]
	v_mfma_scale_f32_16x16x128_f8f6f4 v[116:119], v[2:9], v[226:233], v[116:119], v187, v187 op_sel_hi:[0,0,0]
	v_mfma_scale_f32_16x16x128_f8f6f4 v[120:123], v[18:25], v[226:233], v[120:123], v187, v187 op_sel_hi:[0,0,0]
	v_mfma_scale_f32_16x16x128_f8f6f4 v[96:99], v[2:9], v[234:241], v[96:99], v187, v187 op_sel_hi:[0,0,0]
	v_mfma_scale_f32_16x16x128_f8f6f4 v[104:107], v[18:25], v[234:241], v[104:107], v187, v187 op_sel_hi:[0,0,0]
	s_barrier
	s_setprio 0
	s_add_i32 s58, s74, s8
	v_lshl_add_u64 v[178:179], v[178:179], 0, s[82:83]
	s_mov_b32 m0, s58
	ds_read_b128 v[200:203], v191 offset:49152
	ds_read_b128 v[204:207], v191 offset:50176
	ds_read_b128 v[208:211], v191 offset:51200
	ds_read_b128 v[212:215], v191 offset:52224
	ds_read_b128 v[226:229], v191 offset:53248
	ds_read_b128 v[230:233], v191 offset:54272
	ds_read_b128 v[234:237], v191 offset:55296
	ds_read_b128 v[238:241], v191 offset:56320
	global_load_lds_dwordx4 v[178:179], off
	s_add_i32 m0, s58, 0x2000
	s_add_u32 s54, s54, 0x20080
	v_lshl_add_u64 v[178:179], v[180:181], 0, s[82:83]
	s_addc_u32 s55, s55, 0
	s_add_i32 s12, s12, s8
	global_load_lds_dwordx4 v[178:179], off
	v_lshl_add_u64 v[178:179], s[54:55], 0, v[158:159]
	s_mov_b32 m0, s12
	s_nop 0
	global_load_lds_dwordx4 v[178:179], off
	v_lshl_add_u64 v[178:179], s[54:55], 0, v[162:163]
	s_add_i32 m0, s12, 0x2000
	s_nop 0
	global_load_lds_dwordx4 v[178:179], off
	v_lshl_add_u64 v[178:179], v[182:183], 0, s[82:83]
	s_mov_b32 m0, s23
	s_nop 0
	global_load_lds_dwordx4 v[178:179], off
	v_lshl_add_u64 v[178:179], v[184:185], 0, s[82:83]
	s_mov_b32 m0, s26
	s_nop 0
	global_load_lds_dwordx4 v[178:179], off
	s_waitcnt vmcnt(8)
	s_setprio 1
	s_barrier
	s_waitcnt lgkmcnt(6)
	v_mfma_scale_f32_16x16x128_f8f6f4 v[80:83], v[10:17], v[200:207], v[80:83], v187, v187 op_sel_hi:[0,0,0]
	v_mfma_scale_f32_16x16x128_f8f6f4 v[88:91], v[192:199], v[200:207], v[88:91], v187, v187 op_sel_hi:[0,0,0]
	s_waitcnt lgkmcnt(4)
	v_mfma_scale_f32_16x16x128_f8f6f4 v[60:63], v[10:17], v[208:215], v[60:63], v187, v187 op_sel_hi:[0,0,0]
	v_mfma_scale_f32_16x16x128_f8f6f4 v[64:67], v[192:199], v[208:215], v[64:67], v187, v187 op_sel_hi:[0,0,0]
	s_waitcnt lgkmcnt(2)
	v_mfma_scale_f32_16x16x128_f8f6f4 v[44:47], v[10:17], v[226:233], v[44:47], v187, v187 op_sel_hi:[0,0,0]
	v_mfma_scale_f32_16x16x128_f8f6f4 v[48:51], v[192:199], v[226:233], v[48:51], v187, v187 op_sel_hi:[0,0,0]
	s_waitcnt lgkmcnt(0)
	v_mfma_scale_f32_16x16x128_f8f6f4 v[28:31], v[10:17], v[234:241], v[28:31], v187, v187 op_sel_hi:[0,0,0]
	v_mfma_scale_f32_16x16x128_f8f6f4 v[32:35], v[192:199], v[234:241], v[32:35], v187, v187 op_sel_hi:[0,0,0]
	s_setprio 0
	s_setprio 1
	v_mfma_scale_f32_16x16x128_f8f6f4 v[92:95], v[2:9], v[200:207], v[92:95], v187, v187 op_sel_hi:[0,0,0]
	v_mfma_scale_f32_16x16x128_f8f6f4 v[100:103], v[18:25], v[200:207], v[100:103], v187, v187 op_sel_hi:[0,0,0]
	v_mfma_scale_f32_16x16x128_f8f6f4 v[68:71], v[2:9], v[208:215], v[68:71], v187, v187 op_sel_hi:[0,0,0]
	v_mfma_scale_f32_16x16x128_f8f6f4 v[72:75], v[18:25], v[208:215], v[72:75], v187, v187 op_sel_hi:[0,0,0]
	v_mfma_scale_f32_16x16x128_f8f6f4 v[52:55], v[2:9], v[226:233], v[52:55], v187, v187 op_sel_hi:[0,0,0]
	v_mfma_scale_f32_16x16x128_f8f6f4 v[56:59], v[18:25], v[226:233], v[56:59], v187, v187 op_sel_hi:[0,0,0]
	v_mfma_scale_f32_16x16x128_f8f6f4 v[36:39], v[2:9], v[234:241], v[36:39], v187, v187 op_sel_hi:[0,0,0]
	v_mfma_scale_f32_16x16x128_f8f6f4 v[40:43], v[18:25], v[234:241], v[40:43], v187, v187 op_sel_hi:[0,0,0]
	s_barrier
	s_setprio 0
	s_add_i32 s68, s68, 2
	s_add_u32 s52, s52, 0x100
	s_addc_u32 s53, s53, 0
	s_add_u32 s35, s35, 0x100
	s_addc_u32 s47, s47, 0
.LBB0_383:
	s_add_u32 s12, s52, 0xfffe0080
	s_addc_u32 s54, s53, -1
	s_add_i32 s72, 0, 0x10000
	s_cmp_eq_u32 s68, 4
	s_cselect_b32 s59, s37, s54
	s_cselect_b32 s58, s36, s12
	s_cselect_b32 s55, s21, s47
	s_cselect_b32 s54, s20, s35
	s_add_i32 s12, 0, 0x14000
	v_add_u32_e32 v14, s72, v190
	v_add_u32_e32 v26, s12, v190
	ds_read_b128 v[2:5], v14
	ds_read_b128 v[6:9], v14 offset:1024
	ds_read_b128 v[10:13], v14 offset:2048
	ds_read_b128 v[14:17], v14 offset:3072
	ds_read_b128 v[18:21], v26
	ds_read_b128 v[22:25], v26 offset:1024
	ds_read_b128 v[192:195], v26 offset:2048
	ds_read_b128 v[196:199], v26 offset:3072
	v_lshl_add_u64 v[216:217], s[52:53], 0, v[166:167]
	s_add_i32 m0, s11, 0xc000
	ds_read_b128 v[178:181], v191
	ds_read_b128 v[182:185], v191 offset:1024
	ds_read_b128 v[200:203], v191 offset:2048
	ds_read_b128 v[204:207], v191 offset:3072
	ds_read_b128 v[208:211], v191 offset:4096
	ds_read_b128 v[212:215], v191 offset:5120
	ds_read_b128 v[226:229], v191 offset:6144
	ds_read_b128 v[230:233], v191 offset:7168
	global_load_lds_dwordx4 v[216:217], off
	v_lshl_add_u64 v[216:217], s[52:53], 0, v[176:177]
	s_add_i32 m0, s11, 0xe000
	s_nop 0
	global_load_lds_dwordx4 v[216:217], off
	s_waitcnt vmcnt(8)
	s_setprio 1
	s_barrier
	s_waitcnt lgkmcnt(6)
	v_mfma_scale_f32_16x16x128_f8f6f4 v[140:143], v[2:9], v[178:185], v[140:143], v187, v187 op_sel_hi:[0,0,0]
	v_mfma_scale_f32_16x16x128_f8f6f4 v[144:147], v[10:17], v[178:185], v[144:147], v187, v187 op_sel_hi:[0,0,0]
	s_waitcnt lgkmcnt(4)
	v_mfma_scale_f32_16x16x128_f8f6f4 v[124:127], v[2:9], v[200:207], v[124:127], v187, v187 op_sel_hi:[0,0,0]
	v_mfma_scale_f32_16x16x128_f8f6f4 v[128:131], v[10:17], v[200:207], v[128:131], v187, v187 op_sel_hi:[0,0,0]
	s_waitcnt lgkmcnt(2)
	v_mfma_scale_f32_16x16x128_f8f6f4 v[108:111], v[2:9], v[208:215], v[108:111], v187, v187 op_sel_hi:[0,0,0]
	v_mfma_scale_f32_16x16x128_f8f6f4 v[112:115], v[10:17], v[208:215], v[112:115], v187, v187 op_sel_hi:[0,0,0]
	s_waitcnt lgkmcnt(0)
	v_mfma_scale_f32_16x16x128_f8f6f4 v[76:79], v[2:9], v[226:233], v[76:79], v187, v187 op_sel_hi:[0,0,0]
	v_mfma_scale_f32_16x16x128_f8f6f4 v[84:87], v[10:17], v[226:233], v[84:87], v187, v187 op_sel_hi:[0,0,0]
	s_setprio 0
	s_setprio 1
	v_mfma_scale_f32_16x16x128_f8f6f4 v[148:151], v[18:25], v[178:185], v[148:151], v187, v187 op_sel_hi:[0,0,0]
	v_mfma_scale_f32_16x16x128_f8f6f4 v[152:155], v[192:199], v[178:185], v[152:155], v187, v187 op_sel_hi:[0,0,0]
	v_mfma_scale_f32_16x16x128_f8f6f4 v[132:135], v[18:25], v[200:207], v[132:135], v187, v187 op_sel_hi:[0,0,0]
	v_mfma_scale_f32_16x16x128_f8f6f4 v[136:139], v[192:199], v[200:207], v[136:139], v187, v187 op_sel_hi:[0,0,0]
	v_mfma_scale_f32_16x16x128_f8f6f4 v[116:119], v[18:25], v[208:215], v[116:119], v187, v187 op_sel_hi:[0,0,0]
	v_mfma_scale_f32_16x16x128_f8f6f4 v[120:123], v[192:199], v[208:215], v[120:123], v187, v187 op_sel_hi:[0,0,0]
	v_mfma_scale_f32_16x16x128_f8f6f4 v[96:99], v[18:25], v[226:233], v[96:99], v187, v187 op_sel_hi:[0,0,0]
	v_mfma_scale_f32_16x16x128_f8f6f4 v[104:107], v[192:199], v[226:233], v[104:107], v187, v187 op_sel_hi:[0,0,0]
	s_barrier
	s_setprio 0
	s_add_i32 s72, s72, s8
	v_lshl_add_u64 v[178:179], s[54:55], 0, v[158:159]
	s_mov_b32 m0, s72
	ds_read_b128 v[200:203], v191 offset:16384
	ds_read_b128 v[204:207], v191 offset:17408
	ds_read_b128 v[208:211], v191 offset:18432
	ds_read_b128 v[212:215], v191 offset:19456
	ds_read_b128 v[226:229], v191 offset:20480
	ds_read_b128 v[230:233], v191 offset:21504
	ds_read_b128 v[234:237], v191 offset:22528
	ds_read_b128 v[238:241], v191 offset:23552
	global_load_lds_dwordx4 v[178:179], off
	s_add_i32 m0, s72, 0x2000
	s_add_u32 s72, s54, 0x20000
	v_lshl_add_u64 v[180:181], s[54:55], 0, v[162:163]
	s_addc_u32 s73, s55, 0
	s_add_i32 s12, s12, s8
	global_load_lds_dwordx4 v[180:181], off
	v_lshl_add_u64 v[182:183], s[72:73], 0, v[158:159]
	s_mov_b32 m0, s12
	v_lshl_add_u64 v[184:185], s[58:59], 0, v[160:161]
	global_load_lds_dwordx4 v[182:183], off
	v_lshl_add_u64 v[182:183], s[72:73], 0, v[162:163]
	s_add_i32 m0, s12, 0x2000
	s_nop 0
	global_load_lds_dwordx4 v[182:183], off
	v_lshl_add_u64 v[182:183], s[58:59], 0, v[156:157]
	s_mov_b32 m0, s11
	s_nop 0
	global_load_lds_dwordx4 v[182:183], off
	s_mov_b32 m0, s16
	s_nop 0
	global_load_lds_dwordx4 v[184:185], off
	s_waitcnt vmcnt(8)
	s_setprio 1
	s_barrier
	s_waitcnt lgkmcnt(6)
	v_mfma_scale_f32_16x16x128_f8f6f4 v[80:83], v[2:9], v[200:207], v[80:83], v187, v187 op_sel_hi:[0,0,0]
	v_mfma_scale_f32_16x16x128_f8f6f4 v[88:91], v[10:17], v[200:207], v[88:91], v187, v187 op_sel_hi:[0,0,0]
	s_waitcnt lgkmcnt(4)
	v_mfma_scale_f32_16x16x128_f8f6f4 v[60:63], v[2:9], v[208:215], v[60:63], v187, v187 op_sel_hi:[0,0,0]
	v_mfma_scale_f32_16x16x128_f8f6f4 v[64:67], v[10:17], v[208:215], v[64:67], v187, v187 op_sel_hi:[0,0,0]
	s_waitcnt lgkmcnt(2)
	v_mfma_scale_f32_16x16x128_f8f6f4 v[44:47], v[2:9], v[226:233], v[44:47], v187, v187 op_sel_hi:[0,0,0]
	v_mfma_scale_f32_16x16x128_f8f6f4 v[48:51], v[10:17], v[226:233], v[48:51], v187, v187 op_sel_hi:[0,0,0]
	s_waitcnt lgkmcnt(0)
	v_mfma_scale_f32_16x16x128_f8f6f4 v[28:31], v[2:9], v[234:241], v[28:31], v187, v187 op_sel_hi:[0,0,0]
	v_mfma_scale_f32_16x16x128_f8f6f4 v[32:35], v[10:17], v[234:241], v[32:35], v187, v187 op_sel_hi:[0,0,0]
	s_setprio 0
	s_setprio 1
	v_mfma_scale_f32_16x16x128_f8f6f4 v[92:95], v[18:25], v[200:207], v[92:95], v187, v187 op_sel_hi:[0,0,0]
	v_mfma_scale_f32_16x16x128_f8f6f4 v[100:103], v[192:199], v[200:207], v[100:103], v187, v187 op_sel_hi:[0,0,0]
	v_mfma_scale_f32_16x16x128_f8f6f4 v[68:71], v[18:25], v[208:215], v[68:71], v187, v187 op_sel_hi:[0,0,0]
	v_mfma_scale_f32_16x16x128_f8f6f4 v[72:75], v[192:199], v[208:215], v[72:75], v187, v187 op_sel_hi:[0,0,0]
	v_mfma_scale_f32_16x16x128_f8f6f4 v[52:55], v[18:25], v[226:233], v[52:55], v187, v187 op_sel_hi:[0,0,0]
	v_mfma_scale_f32_16x16x128_f8f6f4 v[56:59], v[192:199], v[226:233], v[56:59], v187, v187 op_sel_hi:[0,0,0]
	v_mfma_scale_f32_16x16x128_f8f6f4 v[36:39], v[18:25], v[234:241], v[36:39], v187, v187 op_sel_hi:[0,0,0]
	v_mfma_scale_f32_16x16x128_f8f6f4 v[40:43], v[192:199], v[234:241], v[40:43], v187, v187 op_sel_hi:[0,0,0]
	s_barrier
	s_setprio 0
	s_add_i32 s74, 0, 0x18000
	s_add_i32 s12, 0, 0x1c000
	v_add_u32_e32 v2, s74, v190
	v_add_u32_e32 v22, s12, v190
	ds_read_b128 v[10:13], v2
	ds_read_b128 v[14:17], v2 offset:1024
	ds_read_b128 v[192:195], v2 offset:2048
	ds_read_b128 v[196:199], v2 offset:3072
	ds_read_b128 v[2:5], v22
	ds_read_b128 v[6:9], v22 offset:1024
	ds_read_b128 v[18:21], v22 offset:2048
	ds_read_b128 v[22:25], v22 offset:3072
	s_add_u32 s58, s58, 0x20000
	s_addc_u32 s59, s59, 0
	s_mov_b32 m0, s17
	v_lshl_add_u64 v[216:217], s[58:59], 0, v[156:157]
	ds_read_b128 v[200:203], v191 offset:32768
	ds_read_b128 v[204:207], v191 offset:33792
	ds_read_b128 v[208:211], v191 offset:34816
	ds_read_b128 v[212:215], v191 offset:35840
	ds_read_b128 v[226:229], v191 offset:36864
	ds_read_b128 v[230:233], v191 offset:37888
	ds_read_b128 v[234:237], v191 offset:38912
	ds_read_b128 v[238:241], v191 offset:39936
	global_load_lds_dwordx4 v[216:217], off
	v_lshl_add_u64 v[216:217], s[58:59], 0, v[160:161]
	s_mov_b32 m0, s22
	s_nop 0
	global_load_lds_dwordx4 v[216:217], off
	s_waitcnt vmcnt(8)
	s_setprio 1
	s_barrier
	s_waitcnt lgkmcnt(6)
	v_mfma_scale_f32_16x16x128_f8f6f4 v[140:143], v[10:17], v[200:207], v[140:143], v187, v187 op_sel_hi:[0,0,0]
	v_mfma_scale_f32_16x16x128_f8f6f4 v[144:147], v[192:199], v[200:207], v[144:147], v187, v187 op_sel_hi:[0,0,0]
	s_waitcnt lgkmcnt(4)
	v_mfma_scale_f32_16x16x128_f8f6f4 v[124:127], v[10:17], v[208:215], v[124:127], v187, v187 op_sel_hi:[0,0,0]
	v_mfma_scale_f32_16x16x128_f8f6f4 v[128:131], v[192:199], v[208:215], v[128:131], v187, v187 op_sel_hi:[0,0,0]
	s_waitcnt lgkmcnt(2)
	v_mfma_scale_f32_16x16x128_f8f6f4 v[108:111], v[10:17], v[226:233], v[108:111], v187, v187 op_sel_hi:[0,0,0]
	v_mfma_scale_f32_16x16x128_f8f6f4 v[112:115], v[192:199], v[226:233], v[112:115], v187, v187 op_sel_hi:[0,0,0]
	s_waitcnt lgkmcnt(0)
	v_mfma_scale_f32_16x16x128_f8f6f4 v[76:79], v[10:17], v[234:241], v[76:79], v187, v187 op_sel_hi:[0,0,0]
	v_mfma_scale_f32_16x16x128_f8f6f4 v[84:87], v[192:199], v[234:241], v[84:87], v187, v187 op_sel_hi:[0,0,0]
	s_setprio 0
	s_setprio 1
	v_mfma_scale_f32_16x16x128_f8f6f4 v[148:151], v[2:9], v[200:207], v[148:151], v187, v187 op_sel_hi:[0,0,0]
	v_mfma_scale_f32_16x16x128_f8f6f4 v[152:155], v[18:25], v[200:207], v[152:155], v187, v187 op_sel_hi:[0,0,0]
	v_mfma_scale_f32_16x16x128_f8f6f4 v[132:135], v[2:9], v[208:215], v[132:135], v187, v187 op_sel_hi:[0,0,0]
	v_mfma_scale_f32_16x16x128_f8f6f4 v[136:139], v[18:25], v[208:215], v[136:139], v187, v187 op_sel_hi:[0,0,0]
	v_mfma_scale_f32_16x16x128_f8f6f4 v[116:119], v[2:9], v[226:233], v[116:119], v187, v187 op_sel_hi:[0,0,0]
	v_mfma_scale_f32_16x16x128_f8f6f4 v[120:123], v[18:25], v[226:233], v[120:123], v187, v187 op_sel_hi:[0,0,0]
	v_mfma_scale_f32_16x16x128_f8f6f4 v[96:99], v[2:9], v[234:241], v[96:99], v187, v187 op_sel_hi:[0,0,0]
	v_mfma_scale_f32_16x16x128_f8f6f4 v[104:107], v[18:25], v[234:241], v[104:107], v187, v187 op_sel_hi:[0,0,0]
	s_barrier
	s_setprio 0
	s_add_i32 s58, s74, s8
	v_lshl_add_u64 v[178:179], v[178:179], 0, s[82:83]
	s_mov_b32 m0, s58
	ds_read_b128 v[200:203], v191 offset:49152
	ds_read_b128 v[204:207], v191 offset:50176
	ds_read_b128 v[208:211], v191 offset:51200
	ds_read_b128 v[212:215], v191 offset:52224
	ds_read_b128 v[226:229], v191 offset:53248
	ds_read_b128 v[230:233], v191 offset:54272
	ds_read_b128 v[234:237], v191 offset:55296
	ds_read_b128 v[238:241], v191 offset:56320
	global_load_lds_dwordx4 v[178:179], off
	s_add_i32 m0, s58, 0x2000
	s_add_u32 s54, s54, 0x20080
	v_lshl_add_u64 v[178:179], v[180:181], 0, s[82:83]
	s_addc_u32 s55, s55, 0
	s_add_i32 s12, s12, s8
	global_load_lds_dwordx4 v[178:179], off
	v_lshl_add_u64 v[178:179], s[54:55], 0, v[158:159]
	s_mov_b32 m0, s12
	s_nop 0
	global_load_lds_dwordx4 v[178:179], off
	v_lshl_add_u64 v[178:179], s[54:55], 0, v[162:163]
	s_add_i32 m0, s12, 0x2000
	s_nop 0
	global_load_lds_dwordx4 v[178:179], off
	v_lshl_add_u64 v[178:179], v[182:183], 0, s[82:83]
	s_mov_b32 m0, s23
	s_nop 0
	global_load_lds_dwordx4 v[178:179], off
	v_lshl_add_u64 v[178:179], v[184:185], 0, s[82:83]
	s_mov_b32 m0, s26
	s_nop 0
	global_load_lds_dwordx4 v[178:179], off
	s_waitcnt vmcnt(8)
	s_setprio 1
	s_barrier
	s_waitcnt lgkmcnt(6)
	v_mfma_scale_f32_16x16x128_f8f6f4 v[80:83], v[10:17], v[200:207], v[80:83], v187, v187 op_sel_hi:[0,0,0]
	v_mfma_scale_f32_16x16x128_f8f6f4 v[88:91], v[192:199], v[200:207], v[88:91], v187, v187 op_sel_hi:[0,0,0]
	s_waitcnt lgkmcnt(4)
	v_mfma_scale_f32_16x16x128_f8f6f4 v[60:63], v[10:17], v[208:215], v[60:63], v187, v187 op_sel_hi:[0,0,0]
	v_mfma_scale_f32_16x16x128_f8f6f4 v[64:67], v[192:199], v[208:215], v[64:67], v187, v187 op_sel_hi:[0,0,0]
	s_waitcnt lgkmcnt(2)
	v_mfma_scale_f32_16x16x128_f8f6f4 v[44:47], v[10:17], v[226:233], v[44:47], v187, v187 op_sel_hi:[0,0,0]
	v_mfma_scale_f32_16x16x128_f8f6f4 v[48:51], v[192:199], v[226:233], v[48:51], v187, v187 op_sel_hi:[0,0,0]
	s_waitcnt lgkmcnt(0)
	v_mfma_scale_f32_16x16x128_f8f6f4 v[28:31], v[10:17], v[234:241], v[28:31], v187, v187 op_sel_hi:[0,0,0]
	v_mfma_scale_f32_16x16x128_f8f6f4 v[32:35], v[192:199], v[234:241], v[32:35], v187, v187 op_sel_hi:[0,0,0]
	s_setprio 0
	s_setprio 1
	v_mfma_scale_f32_16x16x128_f8f6f4 v[92:95], v[2:9], v[200:207], v[92:95], v187, v187 op_sel_hi:[0,0,0]
	v_mfma_scale_f32_16x16x128_f8f6f4 v[100:103], v[18:25], v[200:207], v[100:103], v187, v187 op_sel_hi:[0,0,0]
	v_mfma_scale_f32_16x16x128_f8f6f4 v[68:71], v[2:9], v[208:215], v[68:71], v187, v187 op_sel_hi:[0,0,0]
	v_mfma_scale_f32_16x16x128_f8f6f4 v[72:75], v[18:25], v[208:215], v[72:75], v187, v187 op_sel_hi:[0,0,0]
	v_mfma_scale_f32_16x16x128_f8f6f4 v[52:55], v[2:9], v[226:233], v[52:55], v187, v187 op_sel_hi:[0,0,0]
	v_mfma_scale_f32_16x16x128_f8f6f4 v[56:59], v[18:25], v[226:233], v[56:59], v187, v187 op_sel_hi:[0,0,0]
	v_mfma_scale_f32_16x16x128_f8f6f4 v[36:39], v[2:9], v[234:241], v[36:39], v187, v187 op_sel_hi:[0,0,0]
	v_mfma_scale_f32_16x16x128_f8f6f4 v[40:43], v[18:25], v[234:241], v[40:43], v187, v187 op_sel_hi:[0,0,0]
	s_barrier
	s_setprio 0
	s_add_i32 s68, s68, 2
	s_add_u32 s52, s52, 0x100
	s_addc_u32 s53, s53, 0
	s_add_u32 s35, s35, 0x100
	s_addc_u32 s47, s47, 0
	s_cmp_gt_u32 s68, 5
	s_cbranch_scc0 .LBB0_383
	s_and_b64 vcc, exec, s[30:31]
	s_cbranch_vccz .LBB0_386
	s_barrier

.LBB0_492:
	s_add_i32 s12, s20, 0xf2de0080
	s_cmp_lg_u32 s36, 4
	s_cselect_b32 s12, s12, 0
	s_add_u32 s30, s84, s12
	s_addc_u32 s31, s85, 0
	s_add_i32 s37, 0, 0x10000
	s_add_u32 s28, s0, s12
	s_addc_u32 s29, s1, 0
	s_add_i32 s12, 0, 0x14000
	v_add_u32_e32 v14, s37, v186
	v_add_u32_e32 v166, s12, v186
	ds_read_b128 v[2:5], v14
	ds_read_b128 v[6:9], v14 offset:1024
	ds_read_b128 v[10:13], v14 offset:2048
	ds_read_b128 v[14:17], v14 offset:3072
	ds_read_b128 v[18:21], v166
	ds_read_b128 v[22:25], v166 offset:1024
	ds_read_b128 v[188:191], v166 offset:2048
	ds_read_b128 v[192:195], v166 offset:3072
	v_lshl_add_u64 v[166:167], v[162:163], 0, s[20:21]
	s_add_i32 m0, s17, 0xc000
	ds_read_b128 v[196:199], v187
	ds_read_b128 v[200:203], v187 offset:1024
	ds_read_b128 v[204:207], v187 offset:2048
	ds_read_b128 v[208:211], v187 offset:3072
	ds_read_b128 v[212:215], v187 offset:4096
	ds_read_b128 v[216:219], v187 offset:5120
	ds_read_b128 v[226:229], v187 offset:6144
	ds_read_b128 v[230:233], v187 offset:7168
	global_load_lds_dwordx4 v[166:167], off
	v_lshl_add_u64 v[166:167], v[164:165], 0, s[20:21]
	s_add_i32 m0, s17, 0xe000
	s_nop 0
	global_load_lds_dwordx4 v[166:167], off
	s_waitcnt vmcnt(8)
	s_setprio 1
	s_barrier
	s_waitcnt lgkmcnt(6)
	v_mfma_scale_f32_16x16x128_f8f6f4 v[144:147], v[2:9], v[196:203], v[144:147], v183, v183 op_sel_hi:[0,0,0]
	v_mfma_scale_f32_16x16x128_f8f6f4 v[148:151], v[10:17], v[196:203], v[148:151], v183, v183 op_sel_hi:[0,0,0]
	s_waitcnt lgkmcnt(4)
	v_mfma_scale_f32_16x16x128_f8f6f4 v[124:127], v[2:9], v[204:211], v[124:127], v183, v183 op_sel_hi:[0,0,0]
	v_mfma_scale_f32_16x16x128_f8f6f4 v[128:131], v[10:17], v[204:211], v[128:131], v183, v183 op_sel_hi:[0,0,0]
	s_waitcnt lgkmcnt(2)
	v_mfma_scale_f32_16x16x128_f8f6f4 v[108:111], v[2:9], v[212:219], v[108:111], v183, v183 op_sel_hi:[0,0,0]
	v_mfma_scale_f32_16x16x128_f8f6f4 v[112:115], v[10:17], v[212:219], v[112:115], v183, v183 op_sel_hi:[0,0,0]
	s_waitcnt lgkmcnt(0)
	v_mfma_scale_f32_16x16x128_f8f6f4 v[92:95], v[2:9], v[226:233], v[92:95], v183, v183 op_sel_hi:[0,0,0]
	v_mfma_scale_f32_16x16x128_f8f6f4 v[96:99], v[10:17], v[226:233], v[96:99], v183, v183 op_sel_hi:[0,0,0]
	s_setprio 0
	s_setprio 1
	v_mfma_scale_f32_16x16x128_f8f6f4 v[152:155], v[18:25], v[196:203], v[152:155], v183, v183 op_sel_hi:[0,0,0]
	v_mfma_scale_f32_16x16x128_f8f6f4 v[140:143], v[188:195], v[196:203], v[140:143], v183, v183 op_sel_hi:[0,0,0]
	v_mfma_scale_f32_16x16x128_f8f6f4 v[132:135], v[18:25], v[204:211], v[132:135], v183, v183 op_sel_hi:[0,0,0]
	v_mfma_scale_f32_16x16x128_f8f6f4 v[136:139], v[188:195], v[204:211], v[136:139], v183, v183 op_sel_hi:[0,0,0]
	v_mfma_scale_f32_16x16x128_f8f6f4 v[116:119], v[18:25], v[212:219], v[116:119], v183, v183 op_sel_hi:[0,0,0]
	v_mfma_scale_f32_16x16x128_f8f6f4 v[120:123], v[188:195], v[212:219], v[120:123], v183, v183 op_sel_hi:[0,0,0]
	v_mfma_scale_f32_16x16x128_f8f6f4 v[100:103], v[18:25], v[226:233], v[100:103], v183, v183 op_sel_hi:[0,0,0]
	v_mfma_scale_f32_16x16x128_f8f6f4 v[104:107], v[188:195], v[226:233], v[104:107], v183, v183 op_sel_hi:[0,0,0]
	s_barrier
	s_setprio 0
	s_add_i32 s37, s37, s16
	v_lshl_add_u64 v[166:167], s[28:29], 0, v[26:27]
	s_mov_b32 m0, s37
	ds_read_b128 v[196:199], v187 offset:16384
	ds_read_b128 v[200:203], v187 offset:17408
	ds_read_b128 v[204:207], v187 offset:18432
	ds_read_b128 v[208:211], v187 offset:19456
	ds_read_b128 v[212:215], v187 offset:20480
	ds_read_b128 v[216:219], v187 offset:21504
	ds_read_b128 v[226:229], v187 offset:22528
	ds_read_b128 v[230:233], v187 offset:23552
	global_load_lds_dwordx4 v[166:167], off
	s_add_i32 m0, s37, 0x2000
	s_add_u32 s38, s28, 0x20000
	v_lshl_add_u64 v[176:177], s[28:29], 0, v[160:161]
	s_addc_u32 s39, s29, 0
	s_add_i32 s12, s12, s16
	global_load_lds_dwordx4 v[176:177], off
	v_lshl_add_u64 v[178:179], s[38:39], 0, v[26:27]
	s_mov_b32 m0, s12
	v_lshl_add_u64 v[180:181], s[30:31], 0, v[158:159]
	global_load_lds_dwordx4 v[178:179], off
	v_lshl_add_u64 v[178:179], s[38:39], 0, v[160:161]
	s_add_i32 m0, s12, 0x2000
	s_nop 0
	global_load_lds_dwordx4 v[178:179], off
	v_lshl_add_u64 v[178:179], s[30:31], 0, v[156:157]
	s_mov_b32 m0, s17
	s_nop 0
	global_load_lds_dwordx4 v[178:179], off
	s_mov_b32 m0, s22
	s_nop 0
	global_load_lds_dwordx4 v[180:181], off
	s_waitcnt vmcnt(8)
	s_setprio 1
	s_barrier
	s_waitcnt lgkmcnt(6)
	v_mfma_scale_f32_16x16x128_f8f6f4 v[76:79], v[2:9], v[196:203], v[76:79], v183, v183 op_sel_hi:[0,0,0]
	v_mfma_scale_f32_16x16x128_f8f6f4 v[80:83], v[10:17], v[196:203], v[80:83], v183, v183 op_sel_hi:[0,0,0]
	s_waitcnt lgkmcnt(4)
	v_mfma_scale_f32_16x16x128_f8f6f4 v[60:63], v[2:9], v[204:211], v[60:63], v183, v183 op_sel_hi:[0,0,0]
	v_mfma_scale_f32_16x16x128_f8f6f4 v[64:67], v[10:17], v[204:211], v[64:67], v183, v183 op_sel_hi:[0,0,0]
	s_waitcnt lgkmcnt(2)
	v_mfma_scale_f32_16x16x128_f8f6f4 v[44:47], v[2:9], v[212:219], v[44:47], v183, v183 op_sel_hi:[0,0,0]
	v_mfma_scale_f32_16x16x128_f8f6f4 v[48:51], v[10:17], v[212:219], v[48:51], v183, v183 op_sel_hi:[0,0,0]
	s_waitcnt lgkmcnt(0)
	v_mfma_scale_f32_16x16x128_f8f6f4 v[28:31], v[2:9], v[226:233], v[28:31], v183, v183 op_sel_hi:[0,0,0]
	v_mfma_scale_f32_16x16x128_f8f6f4 v[32:35], v[10:17], v[226:233], v[32:35], v183, v183 op_sel_hi:[0,0,0]
	s_setprio 0
	s_setprio 1
	v_mfma_scale_f32_16x16x128_f8f6f4 v[84:87], v[18:25], v[196:203], v[84:87], v183, v183 op_sel_hi:[0,0,0]
	v_mfma_scale_f32_16x16x128_f8f6f4 v[88:91], v[188:195], v[196:203], v[88:91], v183, v183 op_sel_hi:[0,0,0]
	v_mfma_scale_f32_16x16x128_f8f6f4 v[68:71], v[18:25], v[204:211], v[68:71], v183, v183 op_sel_hi:[0,0,0]
	v_mfma_scale_f32_16x16x128_f8f6f4 v[72:75], v[188:195], v[204:211], v[72:75], v183, v183 op_sel_hi:[0,0,0]
	v_mfma_scale_f32_16x16x128_f8f6f4 v[52:55], v[18:25], v[212:219], v[52:55], v183, v183 op_sel_hi:[0,0,0]
	v_mfma_scale_f32_16x16x128_f8f6f4 v[56:59], v[188:195], v[212:219], v[56:59], v183, v183 op_sel_hi:[0,0,0]
	v_mfma_scale_f32_16x16x128_f8f6f4 v[40:43], v[18:25], v[226:233], v[40:43], v183, v183 op_sel_hi:[0,0,0]
	v_mfma_scale_f32_16x16x128_f8f6f4 v[36:39], v[188:195], v[226:233], v[36:39], v183, v183 op_sel_hi:[0,0,0]
	s_barrier
	s_setprio 0
	s_add_i32 s37, 0, 0x18000
	s_add_i32 s12, 0, 0x1c000
	v_add_u32_e32 v2, s37, v186
	v_add_u32_e32 v22, s12, v186
	ds_read_b128 v[10:13], v2
	ds_read_b128 v[14:17], v2 offset:1024
	ds_read_b128 v[188:191], v2 offset:2048
	ds_read_b128 v[192:195], v2 offset:3072
	ds_read_b128 v[2:5], v22
	ds_read_b128 v[6:9], v22 offset:1024
	ds_read_b128 v[18:21], v22 offset:2048
	ds_read_b128 v[22:25], v22 offset:3072
	s_add_u32 s30, s30, 0x20000
	s_addc_u32 s31, s31, 0
	s_mov_b32 m0, s23
	v_lshl_add_u64 v[220:221], s[30:31], 0, v[156:157]
	ds_read_b128 v[196:199], v187 offset:32768
	ds_read_b128 v[200:203], v187 offset:33792
	ds_read_b128 v[204:207], v187 offset:34816
	ds_read_b128 v[208:211], v187 offset:35840
	ds_read_b128 v[212:215], v187 offset:36864
	ds_read_b128 v[216:219], v187 offset:37888
	ds_read_b128 v[226:229], v187 offset:38912
	ds_read_b128 v[230:233], v187 offset:39936
	global_load_lds_dwordx4 v[220:221], off
	v_lshl_add_u64 v[220:221], s[30:31], 0, v[158:159]
	s_mov_b32 m0, s26
	s_nop 0
	global_load_lds_dwordx4 v[220:221], off
	s_waitcnt vmcnt(8)
	s_setprio 1
	s_barrier
	s_waitcnt lgkmcnt(6)
	v_mfma_scale_f32_16x16x128_f8f6f4 v[144:147], v[10:17], v[196:203], v[144:147], v183, v183 op_sel_hi:[0,0,0]
	v_mfma_scale_f32_16x16x128_f8f6f4 v[148:151], v[188:195], v[196:203], v[148:151], v183, v183 op_sel_hi:[0,0,0]
	s_waitcnt lgkmcnt(4)
	v_mfma_scale_f32_16x16x128_f8f6f4 v[124:127], v[10:17], v[204:211], v[124:127], v183, v183 op_sel_hi:[0,0,0]
	v_mfma_scale_f32_16x16x128_f8f6f4 v[128:131], v[188:195], v[204:211], v[128:131], v183, v183 op_sel_hi:[0,0,0]
	s_waitcnt lgkmcnt(2)
	v_mfma_scale_f32_16x16x128_f8f6f4 v[108:111], v[10:17], v[212:219], v[108:111], v183, v183 op_sel_hi:[0,0,0]
	v_mfma_scale_f32_16x16x128_f8f6f4 v[112:115], v[188:195], v[212:219], v[112:115], v183, v183 op_sel_hi:[0,0,0]
	s_waitcnt lgkmcnt(0)
	v_mfma_scale_f32_16x16x128_f8f6f4 v[92:95], v[10:17], v[226:233], v[92:95], v183, v183 op_sel_hi:[0,0,0]
	v_mfma_scale_f32_16x16x128_f8f6f4 v[96:99], v[188:195], v[226:233], v[96:99], v183, v183 op_sel_hi:[0,0,0]
	s_setprio 0
	s_setprio 1
	v_mfma_scale_f32_16x16x128_f8f6f4 v[152:155], v[2:9], v[196:203], v[152:155], v183, v183 op_sel_hi:[0,0,0]
	v_mfma_scale_f32_16x16x128_f8f6f4 v[140:143], v[18:25], v[196:203], v[140:143], v183, v183 op_sel_hi:[0,0,0]
	v_mfma_scale_f32_16x16x128_f8f6f4 v[132:135], v[2:9], v[204:211], v[132:135], v183, v183 op_sel_hi:[0,0,0]
	v_mfma_scale_f32_16x16x128_f8f6f4 v[136:139], v[18:25], v[204:211], v[136:139], v183, v183 op_sel_hi:[0,0,0]
	v_mfma_scale_f32_16x16x128_f8f6f4 v[116:119], v[2:9], v[212:219], v[116:119], v183, v183 op_sel_hi:[0,0,0]
	v_mfma_scale_f32_16x16x128_f8f6f4 v[120:123], v[18:25], v[212:219], v[120:123], v183, v183 op_sel_hi:[0,0,0]
	v_mfma_scale_f32_16x16x128_f8f6f4 v[100:103], v[2:9], v[226:233], v[100:103], v183, v183 op_sel_hi:[0,0,0]
	v_mfma_scale_f32_16x16x128_f8f6f4 v[104:107], v[18:25], v[226:233], v[104:107], v183, v183 op_sel_hi:[0,0,0]
	s_barrier
	s_setprio 0
	s_add_i32 s30, s37, s16
	v_lshl_add_u64 v[166:167], v[166:167], 0, s[82:83]
	s_mov_b32 m0, s30
	ds_read_b128 v[196:199], v187 offset:49152
	ds_read_b128 v[200:203], v187 offset:50176
	ds_read_b128 v[204:207], v187 offset:51200
	ds_read_b128 v[208:211], v187 offset:52224
	ds_read_b128 v[212:215], v187 offset:53248
	ds_read_b128 v[216:219], v187 offset:54272
	ds_read_b128 v[226:229], v187 offset:55296
	ds_read_b128 v[230:233], v187 offset:56320
	global_load_lds_dwordx4 v[166:167], off
	s_add_i32 m0, s30, 0x2000
	s_add_u32 s28, s28, 0x20080
	v_lshl_add_u64 v[166:167], v[176:177], 0, s[82:83]
	s_addc_u32 s29, s29, 0
	s_add_i32 s12, s12, s16
	global_load_lds_dwordx4 v[166:167], off
	v_lshl_add_u64 v[166:167], s[28:29], 0, v[26:27]
	s_mov_b32 m0, s12
	s_nop 0
	global_load_lds_dwordx4 v[166:167], off
	v_lshl_add_u64 v[166:167], s[28:29], 0, v[160:161]
	s_add_i32 m0, s12, 0x2000
	s_nop 0
	global_load_lds_dwordx4 v[166:167], off
	v_lshl_add_u64 v[166:167], v[178:179], 0, s[82:83]
	s_mov_b32 m0, s34
	s_nop 0
	global_load_lds_dwordx4 v[166:167], off
	v_lshl_add_u64 v[166:167], v[180:181], 0, s[82:83]
	s_mov_b32 m0, s35
	s_nop 0
	global_load_lds_dwordx4 v[166:167], off
	s_waitcnt vmcnt(8)
	s_setprio 1
	s_barrier
	s_waitcnt lgkmcnt(6)
	v_mfma_scale_f32_16x16x128_f8f6f4 v[76:79], v[10:17], v[196:203], v[76:79], v183, v183 op_sel_hi:[0,0,0]
	v_mfma_scale_f32_16x16x128_f8f6f4 v[80:83], v[188:195], v[196:203], v[80:83], v183, v183 op_sel_hi:[0,0,0]
	s_waitcnt lgkmcnt(4)
	v_mfma_scale_f32_16x16x128_f8f6f4 v[60:63], v[10:17], v[204:211], v[60:63], v183, v183 op_sel_hi:[0,0,0]
	v_mfma_scale_f32_16x16x128_f8f6f4 v[64:67], v[188:195], v[204:211], v[64:67], v183, v183 op_sel_hi:[0,0,0]
	s_waitcnt lgkmcnt(2)
	v_mfma_scale_f32_16x16x128_f8f6f4 v[44:47], v[10:17], v[212:219], v[44:47], v183, v183 op_sel_hi:[0,0,0]
	v_mfma_scale_f32_16x16x128_f8f6f4 v[48:51], v[188:195], v[212:219], v[48:51], v183, v183 op_sel_hi:[0,0,0]
	s_waitcnt lgkmcnt(0)
	v_mfma_scale_f32_16x16x128_f8f6f4 v[28:31], v[10:17], v[226:233], v[28:31], v183, v183 op_sel_hi:[0,0,0]
	v_mfma_scale_f32_16x16x128_f8f6f4 v[32:35], v[188:195], v[226:233], v[32:35], v183, v183 op_sel_hi:[0,0,0]
	s_setprio 0
	s_setprio 1
	v_mfma_scale_f32_16x16x128_f8f6f4 v[84:87], v[2:9], v[196:203], v[84:87], v183, v183 op_sel_hi:[0,0,0]
	v_mfma_scale_f32_16x16x128_f8f6f4 v[88:91], v[18:25], v[196:203], v[88:91], v183, v183 op_sel_hi:[0,0,0]
	v_mfma_scale_f32_16x16x128_f8f6f4 v[68:71], v[2:9], v[204:211], v[68:71], v183, v183 op_sel_hi:[0,0,0]
	v_mfma_scale_f32_16x16x128_f8f6f4 v[72:75], v[18:25], v[204:211], v[72:75], v183, v183 op_sel_hi:[0,0,0]
	v_mfma_scale_f32_16x16x128_f8f6f4 v[52:55], v[2:9], v[212:219], v[52:55], v183, v183 op_sel_hi:[0,0,0]
	v_mfma_scale_f32_16x16x128_f8f6f4 v[56:59], v[18:25], v[212:219], v[56:59], v183, v183 op_sel_hi:[0,0,0]
	v_mfma_scale_f32_16x16x128_f8f6f4 v[40:43], v[2:9], v[226:233], v[40:43], v183, v183 op_sel_hi:[0,0,0]
	v_mfma_scale_f32_16x16x128_f8f6f4 v[36:39], v[18:25], v[226:233], v[36:39], v183, v183 op_sel_hi:[0,0,0]
	s_barrier
	s_setprio 0
	s_add_i32 s36, s36, 2
	s_add_u32 s20, s20, 0x100
	s_addc_u32 s21, s21, 0
	s_cmp_gt_u32 s36, 5
	s_cbranch_scc0 .LBB0_492
	s_cmpk_lt_u32 s8, 0x100
	s_cbranch_scc0 .LBB0_495
	s_barrier

.LBB0_548:
	s_add_u32 s12, s54, 0xffea0080
	s_addc_u32 s58, s55, -1
	s_add_i32 s72, 0, 0x10000
	s_cmp_eq_u32 s80, 4
	s_cselect_b32 s61, s41, s58
	s_cselect_b32 s60, s40, s12
	v_add_u32_e32 v26, s72, v227
	s_cselect_b32 s59, s53, s57
	s_cselect_b32 s58, s52, s1
	s_add_i32 s12, 0, 0x14000
	ds_read_b128 v[146:149], v26
	ds_read_b128 v[150:153], v26 offset:1024
	ds_read_b128 v[154:157], v26 offset:2048
	ds_read_b128 v[158:161], v26 offset:3072
	v_add_u32_e32 v26, s12, v227
	ds_read_b128 v[162:165], v26
	ds_read_b128 v[176:179], v26 offset:1024
	ds_read_b128 v[180:183], v26 offset:2048
	ds_read_b128 v[184:187], v26 offset:3072
	v_lshl_add_u64 v[166:167], s[54:55], 0, v[142:143]
	s_add_i32 m0, s16, 0xc000
	ds_read_b128 v[188:191], v229
	ds_read_b128 v[192:195], v229 offset:1024
	ds_read_b128 v[196:199], v229 offset:2048
	ds_read_b128 v[200:203], v229 offset:3072
	ds_read_b128 v[204:207], v229 offset:4096
	ds_read_b128 v[208:211], v229 offset:5120
	ds_read_b128 v[212:215], v229 offset:6144
	ds_read_b128 v[216:219], v229 offset:7168
	global_load_lds_dwordx4 v[166:167], off
	v_lshl_add_u64 v[166:167], s[54:55], 0, v[144:145]
	s_add_i32 m0, s16, 0xe000
	s_nop 0
	global_load_lds_dwordx4 v[166:167], off
	s_waitcnt vmcnt(8)
	s_setprio 1
	s_barrier
	s_waitcnt lgkmcnt(7)
	v_mfma_f32_16x16x32_bf16 v[2:5], v[146:149], v[188:191], v[2:5]
	v_mfma_f32_16x16x32_bf16 v[6:9], v[154:157], v[188:191], v[6:9]
	s_waitcnt lgkmcnt(5)
	v_mfma_f32_16x16x32_bf16 v[10:13], v[146:149], v[196:199], v[10:13]
	v_mfma_f32_16x16x32_bf16 v[14:17], v[154:157], v[196:199], v[14:17]
	s_waitcnt lgkmcnt(3)
	v_mfma_f32_16x16x32_bf16 v[18:21], v[146:149], v[204:207], v[18:21]
	v_mfma_f32_16x16x32_bf16 v[22:25], v[154:157], v[204:207], v[22:25]
	s_waitcnt lgkmcnt(1)
	v_mfma_f32_16x16x32_bf16 v[28:31], v[146:149], v[212:215], v[28:31]
	v_mfma_f32_16x16x32_bf16 v[32:35], v[154:157], v[212:215], v[32:35]
	v_mfma_f32_16x16x32_bf16 v[2:5], v[150:153], v[192:195], v[2:5]
	v_mfma_f32_16x16x32_bf16 v[6:9], v[158:161], v[192:195], v[6:9]
	v_mfma_f32_16x16x32_bf16 v[10:13], v[150:153], v[200:203], v[10:13]
	v_mfma_f32_16x16x32_bf16 v[14:17], v[158:161], v[200:203], v[14:17]
	v_mfma_f32_16x16x32_bf16 v[18:21], v[150:153], v[208:211], v[18:21]
	v_mfma_f32_16x16x32_bf16 v[22:25], v[158:161], v[208:211], v[22:25]
	s_waitcnt lgkmcnt(0)
	v_mfma_f32_16x16x32_bf16 v[28:31], v[150:153], v[216:219], v[28:31]
	v_mfma_f32_16x16x32_bf16 v[32:35], v[158:161], v[216:219], v[32:35]
	s_setprio 0
	s_setprio 1
	v_mfma_f32_16x16x32_bf16 v[36:39], v[162:165], v[188:191], v[36:39]
	v_mfma_f32_16x16x32_bf16 v[40:43], v[180:183], v[188:191], v[40:43]
	v_mfma_f32_16x16x32_bf16 v[44:47], v[162:165], v[196:199], v[44:47]
	v_mfma_f32_16x16x32_bf16 v[48:51], v[180:183], v[196:199], v[48:51]
	v_mfma_f32_16x16x32_bf16 v[52:55], v[162:165], v[204:207], v[52:55]
	v_mfma_f32_16x16x32_bf16 v[56:59], v[180:183], v[204:207], v[56:59]
	v_mfma_f32_16x16x32_bf16 v[60:63], v[162:165], v[212:215], v[60:63]
	v_mfma_f32_16x16x32_bf16 v[64:67], v[180:183], v[212:215], v[64:67]
	v_mfma_f32_16x16x32_bf16 v[36:39], v[176:179], v[192:195], v[36:39]
	v_mfma_f32_16x16x32_bf16 v[40:43], v[184:187], v[192:195], v[40:43]
	v_mfma_f32_16x16x32_bf16 v[44:47], v[176:179], v[200:203], v[44:47]
	v_mfma_f32_16x16x32_bf16 v[48:51], v[184:187], v[200:203], v[48:51]
	v_mfma_f32_16x16x32_bf16 v[52:55], v[176:179], v[208:211], v[52:55]
	v_mfma_f32_16x16x32_bf16 v[56:59], v[184:187], v[208:211], v[56:59]
	v_mfma_f32_16x16x32_bf16 v[60:63], v[176:179], v[216:219], v[60:63]
	v_mfma_f32_16x16x32_bf16 v[64:67], v[184:187], v[216:219], v[64:67]
	s_barrier
	s_setprio 0
	s_add_i32 s72, s72, s15
	v_lshl_add_u64 v[166:167], s[58:59], 0, v[134:135]
	s_mov_b32 m0, s72
	ds_read_b128 v[188:191], v229 offset:16384
	ds_read_b128 v[192:195], v229 offset:17408
	ds_read_b128 v[196:199], v229 offset:18432
	ds_read_b128 v[200:203], v229 offset:19456
	ds_read_b128 v[204:207], v229 offset:20480
	ds_read_b128 v[208:211], v229 offset:21504
	ds_read_b128 v[212:215], v229 offset:22528
	ds_read_b128 v[216:219], v229 offset:23552
	global_load_lds_dwordx4 v[166:167], off
	s_add_i32 m0, s72, 0x2000
	s_add_u32 s72, s58, 0x60000
	v_lshl_add_u64 v[220:221], s[58:59], 0, v[138:139]
	s_addc_u32 s73, s59, 0
	s_add_i32 s12, s12, s15
	global_load_lds_dwordx4 v[220:221], off
	v_lshl_add_u64 v[230:231], s[72:73], 0, v[134:135]
	s_mov_b32 m0, s12
	v_lshl_add_u64 v[232:233], s[60:61], 0, v[136:137]
	global_load_lds_dwordx4 v[230:231], off
	v_lshl_add_u64 v[230:231], s[72:73], 0, v[138:139]
	s_add_i32 m0, s12, 0x2000
	s_nop 0
	global_load_lds_dwordx4 v[230:231], off
	v_lshl_add_u64 v[230:231], s[60:61], 0, v[132:133]
	s_mov_b32 m0, s16
	s_nop 0
	global_load_lds_dwordx4 v[230:231], off
	s_mov_b32 m0, s17
	s_nop 0
	global_load_lds_dwordx4 v[232:233], off
	s_waitcnt vmcnt(8)
	s_setprio 1
	s_barrier
	s_waitcnt lgkmcnt(7)
	v_mfma_f32_16x16x32_bf16 v[68:71], v[146:149], v[188:191], v[68:71]
	v_mfma_f32_16x16x32_bf16 v[72:75], v[154:157], v[188:191], v[72:75]
	s_waitcnt lgkmcnt(5)
	v_mfma_f32_16x16x32_bf16 v[76:79], v[146:149], v[196:199], v[76:79]
	v_mfma_f32_16x16x32_bf16 v[80:83], v[154:157], v[196:199], v[80:83]
	s_waitcnt lgkmcnt(3)
	v_mfma_f32_16x16x32_bf16 v[84:87], v[146:149], v[204:207], v[84:87]
	v_mfma_f32_16x16x32_bf16 v[88:91], v[154:157], v[204:207], v[88:91]
	s_waitcnt lgkmcnt(1)
	v_mfma_f32_16x16x32_bf16 v[92:95], v[146:149], v[212:215], v[92:95]
	v_mfma_f32_16x16x32_bf16 v[96:99], v[154:157], v[212:215], v[96:99]
	v_mfma_f32_16x16x32_bf16 v[68:71], v[150:153], v[192:195], v[68:71]
	v_mfma_f32_16x16x32_bf16 v[72:75], v[158:161], v[192:195], v[72:75]
	v_mfma_f32_16x16x32_bf16 v[76:79], v[150:153], v[200:203], v[76:79]
	v_mfma_f32_16x16x32_bf16 v[80:83], v[158:161], v[200:203], v[80:83]
	v_mfma_f32_16x16x32_bf16 v[84:87], v[150:153], v[208:211], v[84:87]
	v_mfma_f32_16x16x32_bf16 v[88:91], v[158:161], v[208:211], v[88:91]
	s_waitcnt lgkmcnt(0)
	v_mfma_f32_16x16x32_bf16 v[92:95], v[150:153], v[216:219], v[92:95]
	v_mfma_f32_16x16x32_bf16 v[96:99], v[158:161], v[216:219], v[96:99]
	s_setprio 0
	s_setprio 1
	v_mfma_f32_16x16x32_bf16 v[100:103], v[162:165], v[188:191], v[100:103]
	v_mfma_f32_16x16x32_bf16 v[104:107], v[180:183], v[188:191], v[104:107]
	v_mfma_f32_16x16x32_bf16 v[108:111], v[162:165], v[196:199], v[108:111]
	v_mfma_f32_16x16x32_bf16 v[112:115], v[180:183], v[196:199], v[112:115]
	v_mfma_f32_16x16x32_bf16 v[116:119], v[162:165], v[204:207], v[116:119]
	v_mfma_f32_16x16x32_bf16 v[120:123], v[180:183], v[204:207], v[120:123]
	v_mfma_f32_16x16x32_bf16 v[124:127], v[162:165], v[212:215], v[124:127]
	v_mfma_f32_16x16x32_bf16 v[128:131], v[180:183], v[212:215], v[128:131]
	v_mfma_f32_16x16x32_bf16 v[100:103], v[176:179], v[192:195], v[100:103]
	v_mfma_f32_16x16x32_bf16 v[104:107], v[184:187], v[192:195], v[104:107]
	v_mfma_f32_16x16x32_bf16 v[108:111], v[176:179], v[200:203], v[108:111]
	v_mfma_f32_16x16x32_bf16 v[112:115], v[184:187], v[200:203], v[112:115]
	v_mfma_f32_16x16x32_bf16 v[116:119], v[176:179], v[208:211], v[116:119]
	v_mfma_f32_16x16x32_bf16 v[120:123], v[184:187], v[208:211], v[120:123]
	v_mfma_f32_16x16x32_bf16 v[124:127], v[176:179], v[216:219], v[124:127]
	v_mfma_f32_16x16x32_bf16 v[128:131], v[184:187], v[216:219], v[128:131]
	s_barrier
	s_setprio 0
	s_add_i32 s12, 0, 0x18000
	v_add_u32_e32 v26, s12, v227
	s_add_i32 s72, 0, 0x1c000
	ds_read_b128 v[146:149], v26
	ds_read_b128 v[150:153], v26 offset:1024
	ds_read_b128 v[154:157], v26 offset:2048
	ds_read_b128 v[158:161], v26 offset:3072
	v_add_u32_e32 v26, s72, v227
	ds_read_b128 v[162:165], v26
	ds_read_b128 v[176:179], v26 offset:1024
	ds_read_b128 v[180:183], v26 offset:2048
	ds_read_b128 v[184:187], v26 offset:3072
	s_add_u32 s60, s60, 0x160000
	s_addc_u32 s61, s61, 0
	s_mov_b32 m0, s22
	v_lshl_add_u64 v[234:235], s[60:61], 0, v[132:133]
	ds_read_b128 v[188:191], v229 offset:32768
	ds_read_b128 v[192:195], v229 offset:33792
	ds_read_b128 v[196:199], v229 offset:34816
	ds_read_b128 v[200:203], v229 offset:35840
	ds_read_b128 v[204:207], v229 offset:36864
	ds_read_b128 v[208:211], v229 offset:37888
	ds_read_b128 v[212:215], v229 offset:38912
	ds_read_b128 v[216:219], v229 offset:39936
	global_load_lds_dwordx4 v[234:235], off
	v_lshl_add_u64 v[234:235], s[60:61], 0, v[136:137]
	s_mov_b32 m0, s23
	s_nop 0
	global_load_lds_dwordx4 v[234:235], off
	s_waitcnt vmcnt(8)
	s_setprio 1
	s_barrier
	s_waitcnt lgkmcnt(7)
	v_mfma_f32_16x16x32_bf16 v[2:5], v[146:149], v[188:191], v[2:5]
	v_mfma_f32_16x16x32_bf16 v[6:9], v[154:157], v[188:191], v[6:9]
	s_waitcnt lgkmcnt(5)
	v_mfma_f32_16x16x32_bf16 v[10:13], v[146:149], v[196:199], v[10:13]
	v_mfma_f32_16x16x32_bf16 v[14:17], v[154:157], v[196:199], v[14:17]
	s_waitcnt lgkmcnt(3)
	v_mfma_f32_16x16x32_bf16 v[18:21], v[146:149], v[204:207], v[18:21]
	v_mfma_f32_16x16x32_bf16 v[22:25], v[154:157], v[204:207], v[22:25]
	s_waitcnt lgkmcnt(1)
	v_mfma_f32_16x16x32_bf16 v[28:31], v[146:149], v[212:215], v[28:31]
	v_mfma_f32_16x16x32_bf16 v[32:35], v[154:157], v[212:215], v[32:35]
	v_mfma_f32_16x16x32_bf16 v[2:5], v[150:153], v[192:195], v[2:5]
	v_mfma_f32_16x16x32_bf16 v[6:9], v[158:161], v[192:195], v[6:9]
	v_mfma_f32_16x16x32_bf16 v[10:13], v[150:153], v[200:203], v[10:13]
	v_mfma_f32_16x16x32_bf16 v[14:17], v[158:161], v[200:203], v[14:17]
	v_mfma_f32_16x16x32_bf16 v[18:21], v[150:153], v[208:211], v[18:21]
	v_mfma_f32_16x16x32_bf16 v[22:25], v[158:161], v[208:211], v[22:25]
	s_waitcnt lgkmcnt(0)
	v_mfma_f32_16x16x32_bf16 v[28:31], v[150:153], v[216:219], v[28:31]
	v_mfma_f32_16x16x32_bf16 v[32:35], v[158:161], v[216:219], v[32:35]
	s_setprio 0
	s_setprio 1
	v_mfma_f32_16x16x32_bf16 v[36:39], v[162:165], v[188:191], v[36:39]
	v_mfma_f32_16x16x32_bf16 v[40:43], v[180:183], v[188:191], v[40:43]
	v_mfma_f32_16x16x32_bf16 v[44:47], v[162:165], v[196:199], v[44:47]
	v_mfma_f32_16x16x32_bf16 v[48:51], v[180:183], v[196:199], v[48:51]
	v_mfma_f32_16x16x32_bf16 v[52:55], v[162:165], v[204:207], v[52:55]
	v_mfma_f32_16x16x32_bf16 v[56:59], v[180:183], v[204:207], v[56:59]
	v_mfma_f32_16x16x32_bf16 v[60:63], v[162:165], v[212:215], v[60:63]
	v_mfma_f32_16x16x32_bf16 v[64:67], v[180:183], v[212:215], v[64:67]
	v_mfma_f32_16x16x32_bf16 v[36:39], v[176:179], v[192:195], v[36:39]
	v_mfma_f32_16x16x32_bf16 v[40:43], v[184:187], v[192:195], v[40:43]
	v_mfma_f32_16x16x32_bf16 v[44:47], v[176:179], v[200:203], v[44:47]
	v_mfma_f32_16x16x32_bf16 v[48:51], v[184:187], v[200:203], v[48:51]
	v_mfma_f32_16x16x32_bf16 v[52:55], v[176:179], v[208:211], v[52:55]
	v_mfma_f32_16x16x32_bf16 v[56:59], v[184:187], v[208:211], v[56:59]
	v_mfma_f32_16x16x32_bf16 v[60:63], v[176:179], v[216:219], v[60:63]
	v_mfma_f32_16x16x32_bf16 v[64:67], v[184:187], v[216:219], v[64:67]
	s_barrier
	s_setprio 0
	s_add_i32 s12, s12, s15
	v_lshl_add_u64 v[166:167], v[166:167], 0, s[82:83]
	s_mov_b32 m0, s12
	ds_read_b128 v[188:191], v229 offset:49152
	ds_read_b128 v[192:195], v229 offset:50176
	ds_read_b128 v[196:199], v229 offset:51200
	ds_read_b128 v[200:203], v229 offset:52224
	ds_read_b128 v[204:207], v229 offset:53248
	ds_read_b128 v[208:211], v229 offset:54272
	ds_read_b128 v[212:215], v229 offset:55296
	ds_read_b128 v[216:219], v229 offset:56320
	global_load_lds_dwordx4 v[166:167], off
	s_add_i32 m0, s12, 0x2000
	s_add_u32 s58, s58, 0x60080
	v_lshl_add_u64 v[166:167], v[220:221], 0, s[82:83]
	s_addc_u32 s59, s59, 0
	s_add_i32 s12, s72, s15
	global_load_lds_dwordx4 v[166:167], off
	v_lshl_add_u64 v[166:167], s[58:59], 0, v[134:135]
	s_mov_b32 m0, s12
	s_nop 0
	global_load_lds_dwordx4 v[166:167], off
	v_lshl_add_u64 v[166:167], s[58:59], 0, v[138:139]
	s_add_i32 m0, s12, 0x2000
	s_nop 0
	global_load_lds_dwordx4 v[166:167], off
	v_lshl_add_u64 v[166:167], v[230:231], 0, s[82:83]
	s_mov_b32 m0, s26
	s_nop 0
	global_load_lds_dwordx4 v[166:167], off
	v_lshl_add_u64 v[166:167], v[232:233], 0, s[82:83]
	s_mov_b32 m0, s27
	s_nop 0
	global_load_lds_dwordx4 v[166:167], off
	s_waitcnt vmcnt(8)
	s_setprio 1
	s_barrier
	s_waitcnt lgkmcnt(7)
	v_mfma_f32_16x16x32_bf16 v[68:71], v[146:149], v[188:191], v[68:71]
	v_mfma_f32_16x16x32_bf16 v[72:75], v[154:157], v[188:191], v[72:75]
	s_waitcnt lgkmcnt(5)
	v_mfma_f32_16x16x32_bf16 v[76:79], v[146:149], v[196:199], v[76:79]
	v_mfma_f32_16x16x32_bf16 v[80:83], v[154:157], v[196:199], v[80:83]
	s_waitcnt lgkmcnt(3)
	v_mfma_f32_16x16x32_bf16 v[84:87], v[146:149], v[204:207], v[84:87]
	v_mfma_f32_16x16x32_bf16 v[88:91], v[154:157], v[204:207], v[88:91]
	s_waitcnt lgkmcnt(1)
	v_mfma_f32_16x16x32_bf16 v[92:95], v[146:149], v[212:215], v[92:95]
	v_mfma_f32_16x16x32_bf16 v[96:99], v[154:157], v[212:215], v[96:99]
	v_mfma_f32_16x16x32_bf16 v[68:71], v[150:153], v[192:195], v[68:71]
	v_mfma_f32_16x16x32_bf16 v[72:75], v[158:161], v[192:195], v[72:75]
	v_mfma_f32_16x16x32_bf16 v[76:79], v[150:153], v[200:203], v[76:79]
	v_mfma_f32_16x16x32_bf16 v[80:83], v[158:161], v[200:203], v[80:83]
	v_mfma_f32_16x16x32_bf16 v[84:87], v[150:153], v[208:211], v[84:87]
	v_mfma_f32_16x16x32_bf16 v[88:91], v[158:161], v[208:211], v[88:91]
	s_waitcnt lgkmcnt(0)
	v_mfma_f32_16x16x32_bf16 v[92:95], v[150:153], v[216:219], v[92:95]
	v_mfma_f32_16x16x32_bf16 v[96:99], v[158:161], v[216:219], v[96:99]
	s_setprio 0
	s_setprio 1
	v_mfma_f32_16x16x32_bf16 v[100:103], v[162:165], v[188:191], v[100:103]
	v_mfma_f32_16x16x32_bf16 v[104:107], v[180:183], v[188:191], v[104:107]
	v_mfma_f32_16x16x32_bf16 v[108:111], v[162:165], v[196:199], v[108:111]
	v_mfma_f32_16x16x32_bf16 v[112:115], v[180:183], v[196:199], v[112:115]
	v_mfma_f32_16x16x32_bf16 v[116:119], v[162:165], v[204:207], v[116:119]
	v_mfma_f32_16x16x32_bf16 v[120:123], v[180:183], v[204:207], v[120:123]
	v_mfma_f32_16x16x32_bf16 v[124:127], v[162:165], v[212:215], v[124:127]
	v_mfma_f32_16x16x32_bf16 v[128:131], v[180:183], v[212:215], v[128:131]
	v_mfma_f32_16x16x32_bf16 v[100:103], v[176:179], v[192:195], v[100:103]
	v_mfma_f32_16x16x32_bf16 v[104:107], v[184:187], v[192:195], v[104:107]
	v_mfma_f32_16x16x32_bf16 v[108:111], v[176:179], v[200:203], v[108:111]
	v_mfma_f32_16x16x32_bf16 v[112:115], v[184:187], v[200:203], v[112:115]
	v_mfma_f32_16x16x32_bf16 v[116:119], v[176:179], v[208:211], v[116:119]
	v_mfma_f32_16x16x32_bf16 v[120:123], v[184:187], v[208:211], v[120:123]
	v_mfma_f32_16x16x32_bf16 v[124:127], v[176:179], v[216:219], v[124:127]
	v_mfma_f32_16x16x32_bf16 v[128:131], v[184:187], v[216:219], v[128:131]
	s_barrier
	s_setprio 0
	s_add_i32 s80, s80, 2
	s_add_u32 s54, s54, 0x100
	s_addc_u32 s55, s55, 0
	s_add_u32 s1, s1, 0x100
	s_addc_u32 s57, s57, 0
	s_cmp_gt_u32 s80, 5
	s_cbranch_scc0 .LBB0_548
	s_and_b64 vcc, exec, s[30:31]
	s_cbranch_vccz .LBB0_551
	s_barrier

.LBB0_678:
	s_add_u32 s12, s86, 0xffea0080
	s_addc_u32 s72, s87, -1
	s_add_i32 s73, 0, 0x10000
	s_cmp_eq_u32 s61, 12
	s_cselect_b32 s77, s89, s72
	s_cselect_b32 s76, s88, s12
	v_add_u32_e32 v26, s73, v202
	s_cselect_b32 s75, s91, s59
	s_cselect_b32 s74, s90, s35
	s_add_i32 s12, 0, 0x14000
	ds_read_b128 v[132:135], v26
	ds_read_b128 v[136:139], v26 offset:1024
	ds_read_b128 v[140:143], v26 offset:2048
	ds_read_b128 v[144:147], v26 offset:3072
	v_add_u32_e32 v26, s12, v202
	ds_read_b128 v[148:151], v26
	ds_read_b128 v[152:155], v26 offset:1024
	ds_read_b128 v[156:159], v26 offset:2048
	ds_read_b128 v[160:163], v26 offset:3072
	v_lshl_add_u64 v[220:221], s[86:87], 0, v[188:189]
	s_add_i32 m0, s11, 0xc000
	ds_read_b128 v[164:167], v185
	ds_read_b128 v[192:195], v185 offset:1024
	ds_read_b128 v[196:199], v185 offset:2048
	ds_read_b128 v[204:207], v185 offset:3072
	ds_read_b128 v[208:211], v185 offset:4096
	ds_read_b128 v[212:215], v185 offset:5120
	ds_read_b128 v[216:219], v185 offset:6144
	ds_read_b128 v[226:229], v185 offset:7168
	global_load_lds_dwordx4 v[220:221], off
	v_lshl_add_u64 v[220:221], s[86:87], 0, v[190:191]
	s_add_i32 m0, s11, 0xe000
	s_nop 0
	global_load_lds_dwordx4 v[220:221], off
	s_waitcnt vmcnt(8)
	s_setprio 1
	s_barrier
	s_waitcnt lgkmcnt(7)
	v_mfma_f32_16x16x32_bf16 v[2:5], v[132:135], v[164:167], v[2:5]
	v_mfma_f32_16x16x32_bf16 v[6:9], v[140:143], v[164:167], v[6:9]
	s_waitcnt lgkmcnt(5)
	v_mfma_f32_16x16x32_bf16 v[10:13], v[132:135], v[196:199], v[10:13]
	v_mfma_f32_16x16x32_bf16 v[14:17], v[140:143], v[196:199], v[14:17]
	s_waitcnt lgkmcnt(3)
	v_mfma_f32_16x16x32_bf16 v[18:21], v[132:135], v[208:211], v[18:21]
	v_mfma_f32_16x16x32_bf16 v[22:25], v[140:143], v[208:211], v[22:25]
	s_waitcnt lgkmcnt(1)
	v_mfma_f32_16x16x32_bf16 v[28:31], v[132:135], v[216:219], v[28:31]
	v_mfma_f32_16x16x32_bf16 v[32:35], v[140:143], v[216:219], v[32:35]
	v_mfma_f32_16x16x32_bf16 v[2:5], v[136:139], v[192:195], v[2:5]
	v_mfma_f32_16x16x32_bf16 v[6:9], v[144:147], v[192:195], v[6:9]
	v_mfma_f32_16x16x32_bf16 v[10:13], v[136:139], v[204:207], v[10:13]
	v_mfma_f32_16x16x32_bf16 v[14:17], v[144:147], v[204:207], v[14:17]
	v_mfma_f32_16x16x32_bf16 v[18:21], v[136:139], v[212:215], v[18:21]
	v_mfma_f32_16x16x32_bf16 v[22:25], v[144:147], v[212:215], v[22:25]
	s_waitcnt lgkmcnt(0)
	v_mfma_f32_16x16x32_bf16 v[28:31], v[136:139], v[226:229], v[28:31]
	v_mfma_f32_16x16x32_bf16 v[32:35], v[144:147], v[226:229], v[32:35]
	s_setprio 0
	s_setprio 1
	v_mfma_f32_16x16x32_bf16 v[36:39], v[148:151], v[164:167], v[36:39]
	v_mfma_f32_16x16x32_bf16 v[40:43], v[156:159], v[164:167], v[40:43]
	v_mfma_f32_16x16x32_bf16 v[44:47], v[148:151], v[196:199], v[44:47]
	v_mfma_f32_16x16x32_bf16 v[48:51], v[156:159], v[196:199], v[48:51]
	v_mfma_f32_16x16x32_bf16 v[52:55], v[148:151], v[208:211], v[52:55]
	v_mfma_f32_16x16x32_bf16 v[56:59], v[156:159], v[208:211], v[56:59]
	v_mfma_f32_16x16x32_bf16 v[60:63], v[148:151], v[216:219], v[60:63]
	v_mfma_f32_16x16x32_bf16 v[64:67], v[156:159], v[216:219], v[64:67]
	v_mfma_f32_16x16x32_bf16 v[36:39], v[152:155], v[192:195], v[36:39]
	v_mfma_f32_16x16x32_bf16 v[40:43], v[160:163], v[192:195], v[40:43]
	v_mfma_f32_16x16x32_bf16 v[44:47], v[152:155], v[204:207], v[44:47]
	v_mfma_f32_16x16x32_bf16 v[48:51], v[160:163], v[204:207], v[48:51]
	v_mfma_f32_16x16x32_bf16 v[52:55], v[152:155], v[212:215], v[52:55]
	v_mfma_f32_16x16x32_bf16 v[56:59], v[160:163], v[212:215], v[56:59]
	v_mfma_f32_16x16x32_bf16 v[60:63], v[152:155], v[226:229], v[60:63]
	v_mfma_f32_16x16x32_bf16 v[64:67], v[160:163], v[226:229], v[64:67]
	s_barrier
	s_setprio 0
	s_add_i32 s72, s73, s8
	v_lshl_add_u64 v[220:221], s[74:75], 0, v[178:179]
	s_mov_b32 m0, s72
	ds_read_b128 v[164:167], v185 offset:16384
	ds_read_b128 v[192:195], v185 offset:17408
	ds_read_b128 v[196:199], v185 offset:18432
	ds_read_b128 v[204:207], v185 offset:19456
	ds_read_b128 v[208:211], v185 offset:20480
	ds_read_b128 v[212:215], v185 offset:21504
	ds_read_b128 v[216:219], v185 offset:22528
	ds_read_b128 v[226:229], v185 offset:23552
	global_load_lds_dwordx4 v[220:221], off
	s_add_i32 m0, s72, 0x2000
	s_add_u32 s72, s74, 0x40000
	v_lshl_add_u64 v[230:231], s[74:75], 0, v[182:183]
	s_addc_u32 s73, s75, 0
	s_add_i32 s12, s12, s8
	global_load_lds_dwordx4 v[230:231], off
	v_lshl_add_u64 v[232:233], s[72:73], 0, v[178:179]
	s_mov_b32 m0, s12
	v_lshl_add_u64 v[234:235], s[76:77], 0, v[180:181]
	global_load_lds_dwordx4 v[232:233], off
	v_lshl_add_u64 v[232:233], s[72:73], 0, v[182:183]
	s_add_i32 m0, s12, 0x2000
	s_nop 0
	global_load_lds_dwordx4 v[232:233], off
	v_lshl_add_u64 v[232:233], s[76:77], 0, v[176:177]
	s_mov_b32 m0, s11
	s_nop 0
	global_load_lds_dwordx4 v[232:233], off
	s_mov_b32 m0, s16
	s_nop 0
	global_load_lds_dwordx4 v[234:235], off
	s_waitcnt vmcnt(8)
	s_setprio 1
	s_barrier
	s_waitcnt lgkmcnt(7)
	v_mfma_f32_16x16x32_bf16 v[68:71], v[132:135], v[164:167], v[68:71]
	v_mfma_f32_16x16x32_bf16 v[72:75], v[140:143], v[164:167], v[72:75]
	s_waitcnt lgkmcnt(5)
	v_mfma_f32_16x16x32_bf16 v[76:79], v[132:135], v[196:199], v[76:79]
	v_mfma_f32_16x16x32_bf16 v[80:83], v[140:143], v[196:199], v[80:83]
	s_waitcnt lgkmcnt(3)
	v_mfma_f32_16x16x32_bf16 v[84:87], v[132:135], v[208:211], v[84:87]
	v_mfma_f32_16x16x32_bf16 v[88:91], v[140:143], v[208:211], v[88:91]
	s_waitcnt lgkmcnt(1)
	v_mfma_f32_16x16x32_bf16 v[92:95], v[132:135], v[216:219], v[92:95]
	v_mfma_f32_16x16x32_bf16 v[96:99], v[140:143], v[216:219], v[96:99]
	v_mfma_f32_16x16x32_bf16 v[68:71], v[136:139], v[192:195], v[68:71]
	v_mfma_f32_16x16x32_bf16 v[72:75], v[144:147], v[192:195], v[72:75]
	v_mfma_f32_16x16x32_bf16 v[76:79], v[136:139], v[204:207], v[76:79]
	v_mfma_f32_16x16x32_bf16 v[80:83], v[144:147], v[204:207], v[80:83]
	v_mfma_f32_16x16x32_bf16 v[84:87], v[136:139], v[212:215], v[84:87]
	v_mfma_f32_16x16x32_bf16 v[88:91], v[144:147], v[212:215], v[88:91]
	s_waitcnt lgkmcnt(0)
	v_mfma_f32_16x16x32_bf16 v[92:95], v[136:139], v[226:229], v[92:95]
	v_mfma_f32_16x16x32_bf16 v[96:99], v[144:147], v[226:229], v[96:99]
	s_setprio 0
	s_setprio 1
	v_mfma_f32_16x16x32_bf16 v[100:103], v[148:151], v[164:167], v[100:103]
	v_mfma_f32_16x16x32_bf16 v[104:107], v[156:159], v[164:167], v[104:107]
	v_mfma_f32_16x16x32_bf16 v[108:111], v[148:151], v[196:199], v[108:111]
	v_mfma_f32_16x16x32_bf16 v[112:115], v[156:159], v[196:199], v[112:115]
	v_mfma_f32_16x16x32_bf16 v[116:119], v[148:151], v[208:211], v[116:119]
	v_mfma_f32_16x16x32_bf16 v[120:123], v[156:159], v[208:211], v[120:123]
	v_mfma_f32_16x16x32_bf16 v[124:127], v[148:151], v[216:219], v[124:127]
	v_mfma_f32_16x16x32_bf16 v[128:131], v[156:159], v[216:219], v[128:131]
	v_mfma_f32_16x16x32_bf16 v[100:103], v[152:155], v[192:195], v[100:103]
	v_mfma_f32_16x16x32_bf16 v[104:107], v[160:163], v[192:195], v[104:107]
	v_mfma_f32_16x16x32_bf16 v[108:111], v[152:155], v[204:207], v[108:111]
	v_mfma_f32_16x16x32_bf16 v[112:115], v[160:163], v[204:207], v[112:115]
	v_mfma_f32_16x16x32_bf16 v[116:119], v[152:155], v[212:215], v[116:119]
	v_mfma_f32_16x16x32_bf16 v[120:123], v[160:163], v[212:215], v[120:123]
	v_mfma_f32_16x16x32_bf16 v[124:127], v[152:155], v[226:229], v[124:127]
	v_mfma_f32_16x16x32_bf16 v[128:131], v[160:163], v[226:229], v[128:131]
	s_barrier
	s_setprio 0
	s_add_i32 s12, 0, 0x18000
	v_add_u32_e32 v26, s12, v202
	s_add_i32 s78, 0, 0x1c000
	ds_read_b128 v[132:135], v26
	ds_read_b128 v[136:139], v26 offset:1024
	ds_read_b128 v[140:143], v26 offset:2048
	ds_read_b128 v[144:147], v26 offset:3072
	v_add_u32_e32 v26, s78, v202
	ds_read_b128 v[148:151], v26
	ds_read_b128 v[152:155], v26 offset:1024
	ds_read_b128 v[156:159], v26 offset:2048
	ds_read_b128 v[160:163], v26 offset:3072
	s_add_u32 s72, s76, 0x160000
	s_addc_u32 s73, s77, 0
	s_mov_b32 m0, s17
	v_lshl_add_u64 v[236:237], s[72:73], 0, v[176:177]
	ds_read_b128 v[164:167], v185 offset:32768
	ds_read_b128 v[192:195], v185 offset:33792
	ds_read_b128 v[196:199], v185 offset:34816
	ds_read_b128 v[204:207], v185 offset:35840
	ds_read_b128 v[208:211], v185 offset:36864
	ds_read_b128 v[212:215], v185 offset:37888
	ds_read_b128 v[216:219], v185 offset:38912
	ds_read_b128 v[226:229], v185 offset:39936
	global_load_lds_dwordx4 v[236:237], off
	v_lshl_add_u64 v[236:237], s[72:73], 0, v[180:181]
	s_mov_b32 m0, s22
	s_nop 0
	global_load_lds_dwordx4 v[236:237], off
	s_waitcnt vmcnt(8)
	s_setprio 1
	s_barrier
	s_waitcnt lgkmcnt(7)
	v_mfma_f32_16x16x32_bf16 v[2:5], v[132:135], v[164:167], v[2:5]
	v_mfma_f32_16x16x32_bf16 v[6:9], v[140:143], v[164:167], v[6:9]
	s_waitcnt lgkmcnt(5)
	v_mfma_f32_16x16x32_bf16 v[10:13], v[132:135], v[196:199], v[10:13]
	v_mfma_f32_16x16x32_bf16 v[14:17], v[140:143], v[196:199], v[14:17]
	s_waitcnt lgkmcnt(3)
	v_mfma_f32_16x16x32_bf16 v[18:21], v[132:135], v[208:211], v[18:21]
	v_mfma_f32_16x16x32_bf16 v[22:25], v[140:143], v[208:211], v[22:25]
	s_waitcnt lgkmcnt(1)
	v_mfma_f32_16x16x32_bf16 v[28:31], v[132:135], v[216:219], v[28:31]
	v_mfma_f32_16x16x32_bf16 v[32:35], v[140:143], v[216:219], v[32:35]
	v_mfma_f32_16x16x32_bf16 v[2:5], v[136:139], v[192:195], v[2:5]
	v_mfma_f32_16x16x32_bf16 v[6:9], v[144:147], v[192:195], v[6:9]
	v_mfma_f32_16x16x32_bf16 v[10:13], v[136:139], v[204:207], v[10:13]
	v_mfma_f32_16x16x32_bf16 v[14:17], v[144:147], v[204:207], v[14:17]
	v_mfma_f32_16x16x32_bf16 v[18:21], v[136:139], v[212:215], v[18:21]
	v_mfma_f32_16x16x32_bf16 v[22:25], v[144:147], v[212:215], v[22:25]
	s_waitcnt lgkmcnt(0)
	v_mfma_f32_16x16x32_bf16 v[28:31], v[136:139], v[226:229], v[28:31]
	v_mfma_f32_16x16x32_bf16 v[32:35], v[144:147], v[226:229], v[32:35]
	s_setprio 0
	s_setprio 1
	v_mfma_f32_16x16x32_bf16 v[36:39], v[148:151], v[164:167], v[36:39]
	v_mfma_f32_16x16x32_bf16 v[40:43], v[156:159], v[164:167], v[40:43]
	v_mfma_f32_16x16x32_bf16 v[44:47], v[148:151], v[196:199], v[44:47]
	v_mfma_f32_16x16x32_bf16 v[48:51], v[156:159], v[196:199], v[48:51]
	v_mfma_f32_16x16x32_bf16 v[52:55], v[148:151], v[208:211], v[52:55]
	v_mfma_f32_16x16x32_bf16 v[56:59], v[156:159], v[208:211], v[56:59]
	v_mfma_f32_16x16x32_bf16 v[60:63], v[148:151], v[216:219], v[60:63]
	v_mfma_f32_16x16x32_bf16 v[64:67], v[156:159], v[216:219], v[64:67]
	v_mfma_f32_16x16x32_bf16 v[36:39], v[152:155], v[192:195], v[36:39]
	v_mfma_f32_16x16x32_bf16 v[40:43], v[160:163], v[192:195], v[40:43]
	v_mfma_f32_16x16x32_bf16 v[44:47], v[152:155], v[204:207], v[44:47]
	v_mfma_f32_16x16x32_bf16 v[48:51], v[160:163], v[204:207], v[48:51]
	v_mfma_f32_16x16x32_bf16 v[52:55], v[152:155], v[212:215], v[52:55]
	v_mfma_f32_16x16x32_bf16 v[56:59], v[160:163], v[212:215], v[56:59]
	v_mfma_f32_16x16x32_bf16 v[60:63], v[152:155], v[226:229], v[60:63]
	v_mfma_f32_16x16x32_bf16 v[64:67], v[160:163], v[226:229], v[64:67]
	s_barrier
	s_setprio 0
	s_add_i32 s12, s12, s8
	v_lshl_add_u64 v[220:221], v[220:221], 0, s[82:83]
	s_mov_b32 m0, s12
	ds_read_b128 v[164:167], v185 offset:49152
	ds_read_b128 v[192:195], v185 offset:50176
	ds_read_b128 v[196:199], v185 offset:51200
	ds_read_b128 v[204:207], v185 offset:52224
	ds_read_b128 v[208:211], v185 offset:53248
	ds_read_b128 v[212:215], v185 offset:54272
	ds_read_b128 v[216:219], v185 offset:55296
	ds_read_b128 v[226:229], v185 offset:56320
	global_load_lds_dwordx4 v[220:221], off
	s_add_i32 m0, s12, 0x2000
	s_add_u32 s72, s74, 0x40080
	v_lshl_add_u64 v[220:221], v[230:231], 0, s[82:83]
	s_addc_u32 s73, s75, 0
	s_add_i32 s12, s78, s8
	global_load_lds_dwordx4 v[220:221], off
	v_lshl_add_u64 v[220:221], s[72:73], 0, v[178:179]
	s_mov_b32 m0, s12
	s_nop 0
	global_load_lds_dwordx4 v[220:221], off
	v_lshl_add_u64 v[220:221], s[72:73], 0, v[182:183]
	s_add_i32 m0, s12, 0x2000
	s_nop 0
	global_load_lds_dwordx4 v[220:221], off
	v_lshl_add_u64 v[220:221], v[232:233], 0, s[82:83]
	s_mov_b32 m0, s46
	s_nop 0
	global_load_lds_dwordx4 v[220:221], off
	v_lshl_add_u64 v[220:221], v[234:235], 0, s[82:83]
	s_mov_b32 m0, s47
	s_nop 0
	global_load_lds_dwordx4 v[220:221], off
	s_waitcnt vmcnt(8)
	s_setprio 1
	s_barrier
	s_waitcnt lgkmcnt(7)
	v_mfma_f32_16x16x32_bf16 v[68:71], v[132:135], v[164:167], v[68:71]
	v_mfma_f32_16x16x32_bf16 v[72:75], v[140:143], v[164:167], v[72:75]
	s_waitcnt lgkmcnt(5)
	v_mfma_f32_16x16x32_bf16 v[76:79], v[132:135], v[196:199], v[76:79]
	v_mfma_f32_16x16x32_bf16 v[80:83], v[140:143], v[196:199], v[80:83]
	s_waitcnt lgkmcnt(3)
	v_mfma_f32_16x16x32_bf16 v[84:87], v[132:135], v[208:211], v[84:87]
	v_mfma_f32_16x16x32_bf16 v[88:91], v[140:143], v[208:211], v[88:91]
	s_waitcnt lgkmcnt(1)
	v_mfma_f32_16x16x32_bf16 v[92:95], v[132:135], v[216:219], v[92:95]
	v_mfma_f32_16x16x32_bf16 v[96:99], v[140:143], v[216:219], v[96:99]
	v_mfma_f32_16x16x32_bf16 v[68:71], v[136:139], v[192:195], v[68:71]
	v_mfma_f32_16x16x32_bf16 v[72:75], v[144:147], v[192:195], v[72:75]
	v_mfma_f32_16x16x32_bf16 v[76:79], v[136:139], v[204:207], v[76:79]
	v_mfma_f32_16x16x32_bf16 v[80:83], v[144:147], v[204:207], v[80:83]
	v_mfma_f32_16x16x32_bf16 v[84:87], v[136:139], v[212:215], v[84:87]
	v_mfma_f32_16x16x32_bf16 v[88:91], v[144:147], v[212:215], v[88:91]
	s_waitcnt lgkmcnt(0)
	v_mfma_f32_16x16x32_bf16 v[92:95], v[136:139], v[226:229], v[92:95]
	v_mfma_f32_16x16x32_bf16 v[96:99], v[144:147], v[226:229], v[96:99]
	s_setprio 0
	s_setprio 1
	v_mfma_f32_16x16x32_bf16 v[100:103], v[148:151], v[164:167], v[100:103]
	v_mfma_f32_16x16x32_bf16 v[104:107], v[156:159], v[164:167], v[104:107]
	v_mfma_f32_16x16x32_bf16 v[108:111], v[148:151], v[196:199], v[108:111]
	v_mfma_f32_16x16x32_bf16 v[112:115], v[156:159], v[196:199], v[112:115]
	v_mfma_f32_16x16x32_bf16 v[116:119], v[148:151], v[208:211], v[116:119]
	v_mfma_f32_16x16x32_bf16 v[120:123], v[156:159], v[208:211], v[120:123]
	v_mfma_f32_16x16x32_bf16 v[124:127], v[148:151], v[216:219], v[124:127]
	v_mfma_f32_16x16x32_bf16 v[128:131], v[156:159], v[216:219], v[128:131]
	v_mfma_f32_16x16x32_bf16 v[100:103], v[152:155], v[192:195], v[100:103]
	v_mfma_f32_16x16x32_bf16 v[104:107], v[160:163], v[192:195], v[104:107]
	v_mfma_f32_16x16x32_bf16 v[108:111], v[152:155], v[204:207], v[108:111]
	v_mfma_f32_16x16x32_bf16 v[112:115], v[160:163], v[204:207], v[112:115]
	v_mfma_f32_16x16x32_bf16 v[116:119], v[152:155], v[212:215], v[116:119]
	v_mfma_f32_16x16x32_bf16 v[120:123], v[160:163], v[212:215], v[120:123]
	v_mfma_f32_16x16x32_bf16 v[124:127], v[152:155], v[226:229], v[124:127]
	v_mfma_f32_16x16x32_bf16 v[128:131], v[160:163], v[226:229], v[128:131]
	s_barrier
	s_setprio 0
	s_add_i32 s61, s61, 2
	s_add_u32 s86, s86, 0x100
	s_addc_u32 s87, s87, 0
	s_add_u32 s35, s35, 0x100
	s_addc_u32 s59, s59, 0
	s_cmp_gt_u32 s61, 13
	s_cbranch_scc0 .LBB0_678
	s_and_b64 vcc, exec, s[26:27]
	s_cbranch_vccz .LBB0_681
	s_barrier

.LBB0_737:
	s_add_u32 s12, s60, 0xffea0080
	s_addc_u32 s58, s61, -1
	s_add_i32 s72, 0, 0x10000
	s_cmp_eq_u32 s55, 12
	s_cselect_b32 s77, s75, s58
	s_cselect_b32 s76, s74, s12
	v_add_u32_e32 v26, s72, v165
	s_cselect_b32 s59, s87, s53
	s_cselect_b32 s58, s86, s31
	s_add_i32 s12, 0, 0x14000
	s_waitcnt lgkmcnt(0)
	ds_read_b128 v[132:135], v26
	ds_read_b128 v[136:139], v26 offset:1024
	ds_read_b128 v[140:143], v26 offset:2048
	ds_read_b128 v[156:159], v26 offset:3072
	v_add_u32_e32 v26, s12, v165
	ds_read_b128 v[160:163], v26
	ds_read_b128 v[176:179], v26 offset:1024
	ds_read_b128 v[180:183], v26 offset:2048
	ds_read_b128 v[184:187], v26 offset:3072
	v_lshl_add_u64 v[220:221], s[60:61], 0, v[152:153]
	s_add_i32 m0, s11, 0xc000
	ds_read_b128 v[188:191], v167
	ds_read_b128 v[192:195], v167 offset:1024
	ds_read_b128 v[196:199], v167 offset:2048
	ds_read_b128 v[200:203], v167 offset:3072
	ds_read_b128 v[204:207], v167 offset:4096
	ds_read_b128 v[208:211], v167 offset:5120
	ds_read_b128 v[212:215], v167 offset:6144
	ds_read_b128 v[216:219], v167 offset:7168
	global_load_lds_dwordx4 v[220:221], off
	v_lshl_add_u64 v[220:221], s[60:61], 0, v[154:155]
	s_add_i32 m0, s11, 0xe000
	s_nop 0
	global_load_lds_dwordx4 v[220:221], off
	s_waitcnt vmcnt(8)
	s_setprio 1
	s_barrier
	s_waitcnt lgkmcnt(7)
	v_mfma_f32_16x16x32_bf16 v[2:5], v[132:135], v[188:191], v[2:5]
	v_mfma_f32_16x16x32_bf16 v[6:9], v[140:143], v[188:191], v[6:9]
	s_waitcnt lgkmcnt(5)
	v_mfma_f32_16x16x32_bf16 v[10:13], v[132:135], v[196:199], v[10:13]
	v_mfma_f32_16x16x32_bf16 v[14:17], v[140:143], v[196:199], v[14:17]
	s_waitcnt lgkmcnt(3)
	v_mfma_f32_16x16x32_bf16 v[18:21], v[132:135], v[204:207], v[18:21]
	v_mfma_f32_16x16x32_bf16 v[22:25], v[140:143], v[204:207], v[22:25]
	s_waitcnt lgkmcnt(1)
	v_mfma_f32_16x16x32_bf16 v[28:31], v[132:135], v[212:215], v[28:31]
	v_mfma_f32_16x16x32_bf16 v[32:35], v[140:143], v[212:215], v[32:35]
	v_mfma_f32_16x16x32_bf16 v[2:5], v[136:139], v[192:195], v[2:5]
	v_mfma_f32_16x16x32_bf16 v[6:9], v[156:159], v[192:195], v[6:9]
	v_mfma_f32_16x16x32_bf16 v[10:13], v[136:139], v[200:203], v[10:13]
	v_mfma_f32_16x16x32_bf16 v[14:17], v[156:159], v[200:203], v[14:17]
	v_mfma_f32_16x16x32_bf16 v[18:21], v[136:139], v[208:211], v[18:21]
	v_mfma_f32_16x16x32_bf16 v[22:25], v[156:159], v[208:211], v[22:25]
	s_waitcnt lgkmcnt(0)
	v_mfma_f32_16x16x32_bf16 v[28:31], v[136:139], v[216:219], v[28:31]
	v_mfma_f32_16x16x32_bf16 v[32:35], v[156:159], v[216:219], v[32:35]
	s_setprio 0
	s_setprio 1
	v_mfma_f32_16x16x32_bf16 v[36:39], v[160:163], v[188:191], v[36:39]
	v_mfma_f32_16x16x32_bf16 v[40:43], v[180:183], v[188:191], v[40:43]
	v_mfma_f32_16x16x32_bf16 v[44:47], v[160:163], v[196:199], v[44:47]
	v_mfma_f32_16x16x32_bf16 v[48:51], v[180:183], v[196:199], v[48:51]
	v_mfma_f32_16x16x32_bf16 v[52:55], v[160:163], v[204:207], v[52:55]
	v_mfma_f32_16x16x32_bf16 v[56:59], v[180:183], v[204:207], v[56:59]
	v_mfma_f32_16x16x32_bf16 v[60:63], v[160:163], v[212:215], v[60:63]
	v_mfma_f32_16x16x32_bf16 v[64:67], v[180:183], v[212:215], v[64:67]
	v_mfma_f32_16x16x32_bf16 v[36:39], v[176:179], v[192:195], v[36:39]
	v_mfma_f32_16x16x32_bf16 v[40:43], v[184:187], v[192:195], v[40:43]
	v_mfma_f32_16x16x32_bf16 v[44:47], v[176:179], v[200:203], v[44:47]
	v_mfma_f32_16x16x32_bf16 v[48:51], v[184:187], v[200:203], v[48:51]
	v_mfma_f32_16x16x32_bf16 v[52:55], v[176:179], v[208:211], v[52:55]
	v_mfma_f32_16x16x32_bf16 v[56:59], v[184:187], v[208:211], v[56:59]
	v_mfma_f32_16x16x32_bf16 v[60:63], v[176:179], v[216:219], v[60:63]
	v_mfma_f32_16x16x32_bf16 v[64:67], v[184:187], v[216:219], v[64:67]
	s_barrier
	s_setprio 0
	s_add_i32 s72, s72, s8
	v_lshl_add_u64 v[220:221], s[58:59], 0, v[146:147]
	s_mov_b32 m0, s72
	ds_read_b128 v[188:191], v167 offset:16384
	ds_read_b128 v[192:195], v167 offset:17408
	ds_read_b128 v[196:199], v167 offset:18432
	ds_read_b128 v[200:203], v167 offset:19456
	ds_read_b128 v[204:207], v167 offset:20480
	ds_read_b128 v[208:211], v167 offset:21504
	ds_read_b128 v[212:215], v167 offset:22528
	ds_read_b128 v[216:219], v167 offset:23552
	global_load_lds_dwordx4 v[220:221], off
	s_add_i32 m0, s72, 0x2000
	s_add_u32 s72, s58, 0x40000
	v_lshl_add_u64 v[226:227], s[58:59], 0, v[150:151]
	s_addc_u32 s73, s59, 0
	s_add_i32 s12, s12, s8
	global_load_lds_dwordx4 v[226:227], off
	v_lshl_add_u64 v[228:229], s[72:73], 0, v[146:147]
	s_mov_b32 m0, s12
	v_lshl_add_u64 v[230:231], s[76:77], 0, v[148:149]
	global_load_lds_dwordx4 v[228:229], off
	v_lshl_add_u64 v[228:229], s[72:73], 0, v[150:151]
	s_add_i32 m0, s12, 0x2000
	s_nop 0
	global_load_lds_dwordx4 v[228:229], off
	v_lshl_add_u64 v[228:229], s[76:77], 0, v[144:145]
	s_mov_b32 m0, s11
	s_nop 0
	global_load_lds_dwordx4 v[228:229], off
	s_mov_b32 m0, s16
	s_nop 0
	global_load_lds_dwordx4 v[230:231], off
	s_waitcnt vmcnt(8)
	s_setprio 1
	s_barrier
	s_waitcnt lgkmcnt(7)
	v_mfma_f32_16x16x32_bf16 v[68:71], v[132:135], v[188:191], v[68:71]
	v_mfma_f32_16x16x32_bf16 v[72:75], v[140:143], v[188:191], v[72:75]
	s_waitcnt lgkmcnt(5)
	v_mfma_f32_16x16x32_bf16 v[76:79], v[132:135], v[196:199], v[76:79]
	v_mfma_f32_16x16x32_bf16 v[80:83], v[140:143], v[196:199], v[80:83]
	s_waitcnt lgkmcnt(3)
	v_mfma_f32_16x16x32_bf16 v[84:87], v[132:135], v[204:207], v[84:87]
	v_mfma_f32_16x16x32_bf16 v[88:91], v[140:143], v[204:207], v[88:91]
	s_waitcnt lgkmcnt(1)
	v_mfma_f32_16x16x32_bf16 v[92:95], v[132:135], v[212:215], v[92:95]
	v_mfma_f32_16x16x32_bf16 v[96:99], v[140:143], v[212:215], v[96:99]
	v_mfma_f32_16x16x32_bf16 v[68:71], v[136:139], v[192:195], v[68:71]
	v_mfma_f32_16x16x32_bf16 v[72:75], v[156:159], v[192:195], v[72:75]
	v_mfma_f32_16x16x32_bf16 v[76:79], v[136:139], v[200:203], v[76:79]
	v_mfma_f32_16x16x32_bf16 v[80:83], v[156:159], v[200:203], v[80:83]
	v_mfma_f32_16x16x32_bf16 v[84:87], v[136:139], v[208:211], v[84:87]
	v_mfma_f32_16x16x32_bf16 v[88:91], v[156:159], v[208:211], v[88:91]
	s_waitcnt lgkmcnt(0)
	v_mfma_f32_16x16x32_bf16 v[92:95], v[136:139], v[216:219], v[92:95]
	v_mfma_f32_16x16x32_bf16 v[96:99], v[156:159], v[216:219], v[96:99]
	s_setprio 0
	s_setprio 1
	v_mfma_f32_16x16x32_bf16 v[100:103], v[160:163], v[188:191], v[100:103]
	v_mfma_f32_16x16x32_bf16 v[104:107], v[180:183], v[188:191], v[104:107]
	v_mfma_f32_16x16x32_bf16 v[108:111], v[160:163], v[196:199], v[108:111]
	v_mfma_f32_16x16x32_bf16 v[112:115], v[180:183], v[196:199], v[112:115]
	v_mfma_f32_16x16x32_bf16 v[116:119], v[160:163], v[204:207], v[116:119]
	v_mfma_f32_16x16x32_bf16 v[120:123], v[180:183], v[204:207], v[120:123]
	v_mfma_f32_16x16x32_bf16 v[124:127], v[160:163], v[212:215], v[124:127]
	v_mfma_f32_16x16x32_bf16 v[128:131], v[180:183], v[212:215], v[128:131]
	v_mfma_f32_16x16x32_bf16 v[100:103], v[176:179], v[192:195], v[100:103]
	v_mfma_f32_16x16x32_bf16 v[104:107], v[184:187], v[192:195], v[104:107]
	v_mfma_f32_16x16x32_bf16 v[108:111], v[176:179], v[200:203], v[108:111]
	v_mfma_f32_16x16x32_bf16 v[112:115], v[184:187], v[200:203], v[112:115]
	v_mfma_f32_16x16x32_bf16 v[116:119], v[176:179], v[208:211], v[116:119]
	v_mfma_f32_16x16x32_bf16 v[120:123], v[184:187], v[208:211], v[120:123]
	v_mfma_f32_16x16x32_bf16 v[124:127], v[176:179], v[216:219], v[124:127]
	v_mfma_f32_16x16x32_bf16 v[128:131], v[184:187], v[216:219], v[128:131]
	s_barrier
	s_setprio 0
	s_add_i32 s12, 0, 0x18000
	v_add_u32_e32 v26, s12, v165
	s_add_i32 s79, 0, 0x1c000
	ds_read_b128 v[132:135], v26
	ds_read_b128 v[136:139], v26 offset:1024
	ds_read_b128 v[140:143], v26 offset:2048
	ds_read_b128 v[156:159], v26 offset:3072
	v_add_u32_e32 v26, s79, v165
	ds_read_b128 v[160:163], v26
	ds_read_b128 v[176:179], v26 offset:1024
	ds_read_b128 v[180:183], v26 offset:2048
	ds_read_b128 v[184:187], v26 offset:3072
	s_add_u32 s72, s76, 0x160000
	s_addc_u32 s73, s77, 0
	s_mov_b32 m0, s17
	v_lshl_add_u64 v[232:233], s[72:73], 0, v[144:145]
	ds_read_b128 v[188:191], v167 offset:32768
	ds_read_b128 v[192:195], v167 offset:33792
	ds_read_b128 v[196:199], v167 offset:34816
	ds_read_b128 v[200:203], v167 offset:35840
	ds_read_b128 v[204:207], v167 offset:36864
	ds_read_b128 v[208:211], v167 offset:37888
	ds_read_b128 v[212:215], v167 offset:38912
	ds_read_b128 v[216:219], v167 offset:39936
	global_load_lds_dwordx4 v[232:233], off
	v_lshl_add_u64 v[232:233], s[72:73], 0, v[148:149]
	s_mov_b32 m0, s22
	s_nop 0
	global_load_lds_dwordx4 v[232:233], off
	s_waitcnt vmcnt(8)
	s_setprio 1
	s_barrier
	s_waitcnt lgkmcnt(7)
	v_mfma_f32_16x16x32_bf16 v[2:5], v[132:135], v[188:191], v[2:5]
	v_mfma_f32_16x16x32_bf16 v[6:9], v[140:143], v[188:191], v[6:9]
	s_waitcnt lgkmcnt(5)
	v_mfma_f32_16x16x32_bf16 v[10:13], v[132:135], v[196:199], v[10:13]
	v_mfma_f32_16x16x32_bf16 v[14:17], v[140:143], v[196:199], v[14:17]
	s_waitcnt lgkmcnt(3)
	v_mfma_f32_16x16x32_bf16 v[18:21], v[132:135], v[204:207], v[18:21]
	v_mfma_f32_16x16x32_bf16 v[22:25], v[140:143], v[204:207], v[22:25]
	s_waitcnt lgkmcnt(1)
	v_mfma_f32_16x16x32_bf16 v[28:31], v[132:135], v[212:215], v[28:31]
	v_mfma_f32_16x16x32_bf16 v[32:35], v[140:143], v[212:215], v[32:35]
	v_mfma_f32_16x16x32_bf16 v[2:5], v[136:139], v[192:195], v[2:5]
	v_mfma_f32_16x16x32_bf16 v[6:9], v[156:159], v[192:195], v[6:9]
	v_mfma_f32_16x16x32_bf16 v[10:13], v[136:139], v[200:203], v[10:13]
	v_mfma_f32_16x16x32_bf16 v[14:17], v[156:159], v[200:203], v[14:17]
	v_mfma_f32_16x16x32_bf16 v[18:21], v[136:139], v[208:211], v[18:21]
	v_mfma_f32_16x16x32_bf16 v[22:25], v[156:159], v[208:211], v[22:25]
	s_waitcnt lgkmcnt(0)
	v_mfma_f32_16x16x32_bf16 v[28:31], v[136:139], v[216:219], v[28:31]
	v_mfma_f32_16x16x32_bf16 v[32:35], v[156:159], v[216:219], v[32:35]
	s_setprio 0
	s_setprio 1
	v_mfma_f32_16x16x32_bf16 v[36:39], v[160:163], v[188:191], v[36:39]
	v_mfma_f32_16x16x32_bf16 v[40:43], v[180:183], v[188:191], v[40:43]
	v_mfma_f32_16x16x32_bf16 v[44:47], v[160:163], v[196:199], v[44:47]
	v_mfma_f32_16x16x32_bf16 v[48:51], v[180:183], v[196:199], v[48:51]
	v_mfma_f32_16x16x32_bf16 v[52:55], v[160:163], v[204:207], v[52:55]
	v_mfma_f32_16x16x32_bf16 v[56:59], v[180:183], v[204:207], v[56:59]
	v_mfma_f32_16x16x32_bf16 v[60:63], v[160:163], v[212:215], v[60:63]
	v_mfma_f32_16x16x32_bf16 v[64:67], v[180:183], v[212:215], v[64:67]
	v_mfma_f32_16x16x32_bf16 v[36:39], v[176:179], v[192:195], v[36:39]
	v_mfma_f32_16x16x32_bf16 v[40:43], v[184:187], v[192:195], v[40:43]
	v_mfma_f32_16x16x32_bf16 v[44:47], v[176:179], v[200:203], v[44:47]
	v_mfma_f32_16x16x32_bf16 v[48:51], v[184:187], v[200:203], v[48:51]
	v_mfma_f32_16x16x32_bf16 v[52:55], v[176:179], v[208:211], v[52:55]
	v_mfma_f32_16x16x32_bf16 v[56:59], v[184:187], v[208:211], v[56:59]
	v_mfma_f32_16x16x32_bf16 v[60:63], v[176:179], v[216:219], v[60:63]
	v_mfma_f32_16x16x32_bf16 v[64:67], v[184:187], v[216:219], v[64:67]
	s_barrier
	s_setprio 0
	s_add_i32 s12, s12, s8
	v_lshl_add_u64 v[220:221], v[220:221], 0, s[82:83]
	s_mov_b32 m0, s12
	ds_read_b128 v[188:191], v167 offset:49152
	ds_read_b128 v[192:195], v167 offset:50176
	ds_read_b128 v[196:199], v167 offset:51200
	ds_read_b128 v[200:203], v167 offset:52224
	ds_read_b128 v[204:207], v167 offset:53248
	ds_read_b128 v[208:211], v167 offset:54272
	ds_read_b128 v[212:215], v167 offset:55296
	ds_read_b128 v[216:219], v167 offset:56320
	global_load_lds_dwordx4 v[220:221], off
	s_add_i32 m0, s12, 0x2000
	s_add_u32 s58, s58, 0x40080
	v_lshl_add_u64 v[220:221], v[226:227], 0, s[82:83]
	s_addc_u32 s59, s59, 0
	s_add_i32 s12, s79, s8
	global_load_lds_dwordx4 v[220:221], off
	v_lshl_add_u64 v[220:221], s[58:59], 0, v[146:147]
	s_mov_b32 m0, s12
	s_nop 0
	global_load_lds_dwordx4 v[220:221], off
	v_lshl_add_u64 v[220:221], s[58:59], 0, v[150:151]
	s_add_i32 m0, s12, 0x2000
	s_nop 0
	global_load_lds_dwordx4 v[220:221], off
	v_lshl_add_u64 v[220:221], v[228:229], 0, s[82:83]
	s_mov_b32 m0, s46
	s_nop 0
	global_load_lds_dwordx4 v[220:221], off
	v_lshl_add_u64 v[220:221], v[230:231], 0, s[82:83]
	s_mov_b32 m0, s47
	s_nop 0
	global_load_lds_dwordx4 v[220:221], off
	s_waitcnt vmcnt(8)
	s_setprio 1
	s_barrier
	s_waitcnt lgkmcnt(7)
	v_mfma_f32_16x16x32_bf16 v[68:71], v[132:135], v[188:191], v[68:71]
	v_mfma_f32_16x16x32_bf16 v[72:75], v[140:143], v[188:191], v[72:75]
	s_waitcnt lgkmcnt(5)
	v_mfma_f32_16x16x32_bf16 v[76:79], v[132:135], v[196:199], v[76:79]
	v_mfma_f32_16x16x32_bf16 v[80:83], v[140:143], v[196:199], v[80:83]
	s_waitcnt lgkmcnt(3)
	v_mfma_f32_16x16x32_bf16 v[84:87], v[132:135], v[204:207], v[84:87]
	v_mfma_f32_16x16x32_bf16 v[88:91], v[140:143], v[204:207], v[88:91]
	s_waitcnt lgkmcnt(1)
	v_mfma_f32_16x16x32_bf16 v[92:95], v[132:135], v[212:215], v[92:95]
	v_mfma_f32_16x16x32_bf16 v[96:99], v[140:143], v[212:215], v[96:99]
	v_mfma_f32_16x16x32_bf16 v[68:71], v[136:139], v[192:195], v[68:71]
	v_mfma_f32_16x16x32_bf16 v[72:75], v[156:159], v[192:195], v[72:75]
	v_mfma_f32_16x16x32_bf16 v[76:79], v[136:139], v[200:203], v[76:79]
	v_mfma_f32_16x16x32_bf16 v[80:83], v[156:159], v[200:203], v[80:83]
	v_mfma_f32_16x16x32_bf16 v[84:87], v[136:139], v[208:211], v[84:87]
	v_mfma_f32_16x16x32_bf16 v[88:91], v[156:159], v[208:211], v[88:91]
	s_waitcnt lgkmcnt(0)
	v_mfma_f32_16x16x32_bf16 v[92:95], v[136:139], v[216:219], v[92:95]
	v_mfma_f32_16x16x32_bf16 v[96:99], v[156:159], v[216:219], v[96:99]
	s_setprio 0
	s_setprio 1
	v_mfma_f32_16x16x32_bf16 v[100:103], v[160:163], v[188:191], v[100:103]
	v_mfma_f32_16x16x32_bf16 v[104:107], v[180:183], v[188:191], v[104:107]
	v_mfma_f32_16x16x32_bf16 v[108:111], v[160:163], v[196:199], v[108:111]
	v_mfma_f32_16x16x32_bf16 v[112:115], v[180:183], v[196:199], v[112:115]
	v_mfma_f32_16x16x32_bf16 v[116:119], v[160:163], v[204:207], v[116:119]
	v_mfma_f32_16x16x32_bf16 v[120:123], v[180:183], v[204:207], v[120:123]
	v_mfma_f32_16x16x32_bf16 v[124:127], v[160:163], v[212:215], v[124:127]
	v_mfma_f32_16x16x32_bf16 v[128:131], v[180:183], v[212:215], v[128:131]
	v_mfma_f32_16x16x32_bf16 v[100:103], v[176:179], v[192:195], v[100:103]
	v_mfma_f32_16x16x32_bf16 v[104:107], v[184:187], v[192:195], v[104:107]
	v_mfma_f32_16x16x32_bf16 v[108:111], v[176:179], v[200:203], v[108:111]
	v_mfma_f32_16x16x32_bf16 v[112:115], v[184:187], v[200:203], v[112:115]
	v_mfma_f32_16x16x32_bf16 v[116:119], v[176:179], v[208:211], v[116:119]
	v_mfma_f32_16x16x32_bf16 v[120:123], v[184:187], v[208:211], v[120:123]
	v_mfma_f32_16x16x32_bf16 v[124:127], v[176:179], v[216:219], v[124:127]
	v_mfma_f32_16x16x32_bf16 v[128:131], v[184:187], v[216:219], v[128:131]
	s_barrier
	s_setprio 0
	s_add_i32 s55, s55, 2
	s_add_u32 s60, s60, 0x100
	s_addc_u32 s61, s61, 0
	s_add_u32 s31, s31, 0x100
	s_addc_u32 s53, s53, 0
	s_cmp_gt_u32 s55, 13
	s_cbranch_scc0 .LBB0_737
	s_and_b64 vcc, exec, s[26:27]
	s_cbranch_vccz .LBB0_740
	s_barrier
